# SwiGLU epilogues: row sums kept in registers from previous epilogue prefetch, no vmcnt(0) at epilogue start, peeled first seg1 wait
# baseline (speedup 1.0000x reference)
; #define PG8_STAGE(bufoff, gbase, voff) do { _Pragma("unroll") for (int _i = 0; _i < 2; ++_i) \
;         __builtin_amdgcn_global_load_lds((const unsigned*)((const char*)(gbase) + (voff)[_i]), (PG8_LAS unsigned*)(lds + (bufoff) + ldsw + _i * 8192), 16, 0, 0); } while (0)
; #define PG8_WAIT_V(n) asm volatile("s_waitcnt vmcnt(" #n ")" ::: "memory")
; #define PG8_BAR __builtin_amdgcn_s_barrier()
;     __device__ __forceinline__ void operator()(const f32x4 (&acc)[2][2][4][2], const Unit& u, const Unit& nxt, bool has_next, int wr, int wc, int fr, int fq) const {
;         const int row0 = u.pm * BM + wr * 64 + fr, col0 = u.pn * HALF + wc * 32 + 8 * fq;
;         u64 cur[8], warm[8];
; #pragma unroll
;         for (int g = 0; g < 8; ++g) cur[g] = rowss[row0 + (g >> 2) * HALF + (g & 3) * 16];
; template <class Epi, class Sched, bool ALIGN_EPI = false, bool SP2 = false>
; __device__ __forceinline__ void gemm_phase(PG8_LAS unsigned char* lds, const Gemm g, const Sched& S, const Epi& E) {
;     ...
;     const char* cA = (const char*)g.A + (size_t)cur.pm * tstep; const char* cB = (const char*)g.Bt + (size_t)cur.pn * tstep;
;     S.a_ready(cur);
;     if constexpr (SP2) {
;         PG8_STAGE(PG8_SB(0, 0), cB, voffB); PG8_STAGE(PG8_SB(0, 1), cB + hstep, voffB); PG8_STAGE(PG8_SA(0, 0), cA, voffA); PG8_STAGE(PG8_SA(0, 1), cA + hstep, voffA);
;         if (wr == 1) PG8_BAR;
;         PG8_WAIT_V(2); PG8_BAR;
;         PG8_STAGE(PG8_SB(1, 0), cB + kstep, voffB); PG8_STAGE(PG8_SA(1, 0), cA + kstep, voffA); PG8_STAGE(PG8_SB(1, 1), cB + hstep + kstep, voffB);
;         PG8_WAIT_V(6); PG8_BAR;
;     } else {
;         PG8_STAGE(PG8_SB(0, 0), cB, voffB); PG8_STAGE(PG8_SA(0, 0), cA, voffA); PG8_STAGE(PG8_SB(0, 1), cB + hstep, voffB); PG8_STAGE(PG8_SA(0, 1), cA + hstep, voffA);
;         if (wr == 1) PG8_BAR;
;         PG8_WAIT_V(4); PG8_BAR;
;         PG8_STAGE(PG8_SB(1, 0), cB + kstep, voffB); PG8_STAGE(PG8_SA(1, 0), cA + kstep, voffA); PG8_STAGE(PG8_SB(1, 1), cB + hstep + kstep, voffB);
;         PG8_WAIT_V(6); PG8_BAR;
;     }
.LBB0_169:
	s_lshl_b32 s36, s36, 5
	s_and_b32 s41, s36, 0x60
	s_mov_b64 s[36:37], 0x80
	s_add_i32 m0, s28, 0x18000
	v_lshl_add_u64 v[6:7], v[6:7], 0, s[36:37]
	s_lshl_b32 s3, s40, 13
	s_lshl_b32 s46, s41, 7
	s_waitcnt vmcnt(2)
	s_barrier
	global_load_lds_dwordx4 v[6:7], off
	v_lshl_add_u64 v[4:5], v[4:5], 0, s[36:37]
	s_add_i32 m0, s28, 0x1a000
	s_add_i32 s65, s28, 0x8000
	s_add_i32 s66, s28, 0xa000
	global_load_lds_dwordx4 v[4:5], off
	v_lshl_add_u64 v[0:1], v[0:1], 0, s[36:37]
	s_mov_b32 m0, s65
	s_add_u32 s44, s60, 0x40080
	global_load_lds_dwordx4 v[0:1], off
	v_lshl_add_u64 v[0:1], v[2:3], 0, s[36:37]
	s_mov_b32 m0, s66
	s_addc_u32 s45, s61, 0
	global_load_lds_dwordx4 v[0:1], off
	s_add_i32 m0, s28, 0x1c000
	v_lshl_add_u64 v[0:1], s[44:45], 0, v[132:133]
	global_load_lds_dwordx4 v[0:1], off
	v_lshl_add_u64 v[0:1], s[44:45], 0, v[128:129]
	s_add_i32 m0, s28, 0x1e000
	v_lshlrev_b32_e32 v2, 2, v201
	global_load_lds_dwordx4 v[0:1], off
	v_and_b32_e32 v0, 15, v201
	v_lshlrev_b32_e32 v1, 1, v11
	v_lshl_or_b32 v174, s40, 6, v0
	v_lshl_or_b32 v0, v0, 6, v1
	v_and_b32_e32 v2, 32, v2
	v_bitop3_b32 v0, v0, s3, v2 bitop3:0xde
	v_lshlrev_b32_e32 v3, 6, v201
	s_movk_i32 s3, 0x3c0
	v_and_or_b32 v1, v3, s3, v1
	v_bitop3_b32 v175, s46, v1, v2 bitop3:0xf6
	v_lshlrev_b32_e32 v1, 8, v201
	v_and_b32_e32 v1, 0x38000, v1
	v_lshlrev_b32_e32 v2, 11, v12
	v_or3_b32 v1, v9, v1, v2
	v_add_u32_e32 v136, v1, v10
	v_lshlrev_b32_e32 v1, 4, v8
	s_waitcnt vmcnt(6)
	s_cmpk_lt_u32 s39, 0x100
	v_and_b32_e32 v1, 0x78000, v1
	s_sext_i32_i8 s70, s38
	s_cselect_b64 s[38:39], -1, 0
	v_or3_b32 v1, v9, v1, v2
	s_add_i32 s67, 0, 0x10000
	s_add_i32 s68, 0, 0x14000
	v_or_b32_e32 v176, s41, v11
	v_mov_b32_e32 v137, v133
	v_add_u32_e32 v138, v1, v10
	v_mov_b32_e32 v139, v133
	v_add_u32_e32 v177, s67, v175
	v_add_u32_e32 v178, s68, v175
	v_add_u32_e32 v179, 0, v0
	v_mov_b32_e32 v180, 0x358637bd
	s_movk_i32 s69, 0x1600
	v_lshl_add_u32 v232, s2, 8, v174
	v_ashrrev_i32_e32 v233, 31, v232
	v_lshl_add_u64 v[246:247], v[232:233], 3, s[26:27]
	global_load_dwordx2 v[232:233], v[246:247], off
	global_load_dwordx2 v[234:235], v[246:247], off offset:128
	global_load_dwordx2 v[236:237], v[246:247], off offset:256
	global_load_dwordx2 v[238:239], v[246:247], off offset:384
	global_load_dwordx2 v[240:241], v[246:247], off offset:1024
	global_load_dwordx2 v[242:243], v[246:247], off offset:1152
	global_load_dwordx2 v[244:245], v[246:247], off offset:1280
	global_load_dwordx2 v[246:247], v[246:247], off offset:1408
	s_barrier
	s_branch .LBB0_172

; #define PG8_STAGE(bufoff, gbase, voff) do { _Pragma("unroll") for (int _i = 0; _i < 2; ++_i) \
;         __builtin_amdgcn_global_load_lds((const unsigned*)((const char*)(gbase) + (voff)[_i]), (PG8_LAS unsigned*)(lds + (bufoff) + ldsw + _i * 8192), 16, 0, 0); } while (0)
; #define PG8_LDA(dst, b, h) do { _Pragma("unroll") for (int m = 0; m < 4; ++m) _Pragma("unroll") for (int k = 0; k < 2; ++k) dst[m][k] = *(const PG8_LAS bf16x8*)(lds + PG8_SA(b, h) + aoff + m * 2048 + k * 1024); } while (0)
; #define PG8_LDB(dst, b, h) do { _Pragma("unroll") for (int n = 0; n < 2; ++n) _Pragma("unroll") for (int k = 0; k < 2; ++k) dst[n][k] = *(const PG8_LAS bf16x8*)(lds + PG8_SB(b, h) + boff + n * 2048 + k * 1024); } while (0)
; #define PG8_MMA(ai, bj, At, Bt) do { __builtin_amdgcn_s_setprio(1); _Pragma("unroll") for (int m = 0; m < 4; ++m) _Pragma("unroll") for (int n = 0; n < 2; ++n) _Pragma("unroll") for (int k = 0; k < 2; ++k) \
;         acc[ai][bj][m][n] = __builtin_amdgcn_mfma_f32_16x16x32_bf16(Bt[n][k], At[m][k], acc[ai][bj][m][n], 0, 0, 0); __builtin_amdgcn_s_setprio(0); } while (0)
; #define PG8_WAIT_V(n) asm volatile("s_waitcnt vmcnt(" #n ")" ::: "memory")
; #define PG8_WAIT_L(n) asm volatile("s_waitcnt lgkmcnt(" #n ")" ::: "memory")
; #define PG8_BAR __builtin_amdgcn_s_barrier()
; #define PG8_SCHED __builtin_amdgcn_sched_barrier(0)
; template <class Epi, class Sched, bool ALIGN_EPI = false, bool SP2 = false>
; __device__ __forceinline__ void gemm_phase(PG8_LAS unsigned char* lds, const Gemm g, const Sched& S, const Epi& E) {
;     ...
;             PG8_LDB(B0, 0, 0); PG8_LDB(B1, 0, 1); PG8_SCHED; PG8_LDA(At, 0, 0); PG8_STAGE(PG8_SA(1, 1), a1 + hstep, voffA);
;             PG8_WAIT_V(8); PG8_WAIT_L(0); PG8_BAR; PG8_MMA(0, 0, At, B0); PG8_MMA(0, 1, At, B1); PG8_BAR; PG8_SCHED;
;     ...
; #pragma unroll
;         for (int a = 0; a < 2; ++a)
; #pragma unroll
;             for (int b = 0; b < 2; ++b)
; #pragma unroll
;                 for (int m = 0; m < 4; ++m)
; #pragma unroll
;                     for (int n = 0; n < 2; ++n) acc[a][b][m][n] = (f32x4){0.f, 0.f, 0.f, 0.f};
;         cur = nxt; cA = nA; cB = nB; ++ui;
.LBB0_174:
	s_ashr_i32 s41, s40, 31
	s_lshl_b64 s[46:47], s[40:41], 19
	s_add_u32 s46, s22, s46
	s_addc_u32 s47, s23, s47
	s_and_b64 s[50:51], s[56:57], exec
	s_cselect_b32 s3, s47, s59
	s_cselect_b32 s41, s46, s58
	s_ashr_i32 s45, s44, 31
	s_lshl_b64 s[50:51], s[44:45], 19
	s_add_u32 s50, s11, s50
	s_addc_u32 s51, s20, s51
	s_and_b64 s[62:63], s[56:57], exec
	s_cselect_b32 s45, s51, s61
	s_cselect_b32 s71, s50, s60
	s_add_u32 s58, s58, 0x40080
	s_addc_u32 s59, s59, 0
	s_add_u32 s72, s60, 0x100
	v_mov_b32_e32 v0, 0
	s_addc_u32 s73, s61, 0
	s_mov_b32 s74, -2
	v_mov_b32_e32 v1, v0
	v_mov_b32_e32 v2, v0
	v_mov_b32_e32 v3, v0
	v_mov_b32_e32 v4, v0
	v_mov_b32_e32 v5, v0
	v_mov_b32_e32 v6, v0
	v_mov_b32_e32 v7, v0
	v_mov_b32_e32 v16, v0
	v_mov_b32_e32 v17, v0
	v_mov_b32_e32 v18, v0
	v_mov_b32_e32 v19, v0
	v_mov_b32_e32 v20, v0
	v_mov_b32_e32 v21, v0
	v_mov_b32_e32 v22, v0
	v_mov_b32_e32 v23, v0
	v_mov_b32_e32 v32, v0
	v_mov_b32_e32 v33, v0
	v_mov_b32_e32 v34, v0
	v_mov_b32_e32 v35, v0
	v_mov_b32_e32 v36, v0
	v_mov_b32_e32 v37, v0
	v_mov_b32_e32 v38, v0
	v_mov_b32_e32 v39, v0
	v_mov_b32_e32 v48, v0
	v_mov_b32_e32 v49, v0
	v_mov_b32_e32 v50, v0
	v_mov_b32_e32 v51, v0
	v_mov_b32_e32 v52, v0
	v_mov_b32_e32 v53, v0
	v_mov_b32_e32 v54, v0
	v_mov_b32_e32 v55, v0
	v_mov_b32_e32 v8, v0
	v_mov_b32_e32 v9, v0
	v_mov_b32_e32 v10, v0
	v_mov_b32_e32 v11, v0
	v_mov_b32_e32 v12, v0
	v_mov_b32_e32 v13, v0
	v_mov_b32_e32 v14, v0
	v_mov_b32_e32 v15, v0
	v_mov_b32_e32 v24, v0
	v_mov_b32_e32 v25, v0
	v_mov_b32_e32 v26, v0
	v_mov_b32_e32 v27, v0
	v_mov_b32_e32 v28, v0
	v_mov_b32_e32 v29, v0
	v_mov_b32_e32 v30, v0
	v_mov_b32_e32 v31, v0
	v_mov_b32_e32 v40, v0
	v_mov_b32_e32 v41, v0
	v_mov_b32_e32 v42, v0
	v_mov_b32_e32 v43, v0
	v_mov_b32_e32 v44, v0
	v_mov_b32_e32 v45, v0
	v_mov_b32_e32 v46, v0
	v_mov_b32_e32 v47, v0
	v_mov_b32_e32 v56, v0
	v_mov_b32_e32 v57, v0
	v_mov_b32_e32 v58, v0
	v_mov_b32_e32 v59, v0
	v_mov_b32_e32 v60, v0
	v_mov_b32_e32 v61, v0
	v_mov_b32_e32 v62, v0
	v_mov_b32_e32 v63, v0
	v_mov_b32_e32 v64, v0
	v_mov_b32_e32 v65, v0
	v_mov_b32_e32 v66, v0
	v_mov_b32_e32 v67, v0
	v_mov_b32_e32 v68, v0
	v_mov_b32_e32 v69, v0
	v_mov_b32_e32 v70, v0
	v_mov_b32_e32 v71, v0
	v_mov_b32_e32 v80, v0
	v_mov_b32_e32 v81, v0
	v_mov_b32_e32 v82, v0
	v_mov_b32_e32 v83, v0
	v_mov_b32_e32 v84, v0
	v_mov_b32_e32 v85, v0
	v_mov_b32_e32 v86, v0
	v_mov_b32_e32 v87, v0
	v_mov_b32_e32 v96, v0
	v_mov_b32_e32 v97, v0
	v_mov_b32_e32 v98, v0
	v_mov_b32_e32 v99, v0
	v_mov_b32_e32 v100, v0
	v_mov_b32_e32 v101, v0
	v_mov_b32_e32 v102, v0
	v_mov_b32_e32 v103, v0
	v_mov_b32_e32 v112, v0
	v_mov_b32_e32 v113, v0
	v_mov_b32_e32 v114, v0
	v_mov_b32_e32 v115, v0
	v_mov_b32_e32 v116, v0
	v_mov_b32_e32 v117, v0
	v_mov_b32_e32 v118, v0
	v_mov_b32_e32 v119, v0
	v_mov_b32_e32 v72, v0
	v_mov_b32_e32 v73, v0
	v_mov_b32_e32 v74, v0
	v_mov_b32_e32 v75, v0
	v_mov_b32_e32 v76, v0
	v_mov_b32_e32 v77, v0
	v_mov_b32_e32 v78, v0
	v_mov_b32_e32 v79, v0
	v_mov_b32_e32 v88, v0
	v_mov_b32_e32 v89, v0
	v_mov_b32_e32 v90, v0
	v_mov_b32_e32 v91, v0
	v_mov_b32_e32 v92, v0
	v_mov_b32_e32 v93, v0
	v_mov_b32_e32 v94, v0
	v_mov_b32_e32 v95, v0
	v_mov_b32_e32 v104, v0
	v_mov_b32_e32 v105, v0
	v_mov_b32_e32 v106, v0
	v_mov_b32_e32 v107, v0
	v_mov_b32_e32 v108, v0
	v_mov_b32_e32 v109, v0
	v_mov_b32_e32 v110, v0
	v_mov_b32_e32 v111, v0
	v_mov_b32_e32 v120, v0
	v_mov_b32_e32 v121, v0
	v_mov_b32_e32 v122, v0
	v_mov_b32_e32 v123, v0
	v_mov_b32_e32 v124, v0
	v_mov_b32_e32 v125, v0
	v_mov_b32_e32 v126, v0
	v_mov_b32_e32 v127, v0
	ds_read_b128 v[140:143], v177
	ds_read_b128 v[144:147], v177 offset:1024
	ds_read_b128 v[148:151], v177 offset:2048
	ds_read_b128 v[152:155], v177 offset:3072
	ds_read_b128 v[156:159], v178
	ds_read_b128 v[160:163], v178 offset:1024
	ds_read_b128 v[164:167], v178 offset:2048
	ds_read_b128 v[168:171], v178 offset:3072
	s_add_u32 s60, s58, 0xfffc0080
	s_addc_u32 s61, s59, -1
	s_cmp_eq_u32 s74, 12
	s_cselect_b32 s63, s3, s61
	s_cselect_b32 s62, s41, s60
	s_cselect_b32 s61, s45, s73
	s_cselect_b32 s60, s71, s72
	v_lshl_add_u64 v[172:173], s[58:59], 0, v[136:137]
	s_add_i32 m0, s28, 0xc000
	ds_read_b128 v[182:185], v179
	ds_read_b128 v[186:189], v179 offset:1024
	ds_read_b128 v[190:193], v179 offset:2048
	ds_read_b128 v[194:197], v179 offset:3072
	ds_read_b128 v[202:205], v179 offset:4096
	ds_read_b128 v[206:209], v179 offset:5120
	ds_read_b128 v[210:213], v179 offset:6144
	ds_read_b128 v[214:217], v179 offset:7168
	global_load_lds_dwordx4 v[172:173], off
	v_lshl_add_u64 v[172:173], s[58:59], 0, v[138:139]
	s_add_i32 m0, s28, 0xe000
	s_nop 0
	global_load_lds_dwordx4 v[172:173], off
	s_waitcnt vmcnt(24)
	s_waitcnt lgkmcnt(0)
	s_branch .Lpeel_join_175
.LBB0_175:
	ds_read_b128 v[140:143], v177
	ds_read_b128 v[144:147], v177 offset:1024
	ds_read_b128 v[148:151], v177 offset:2048
	ds_read_b128 v[152:155], v177 offset:3072
	ds_read_b128 v[156:159], v178
	ds_read_b128 v[160:163], v178 offset:1024
	ds_read_b128 v[164:167], v178 offset:2048
	ds_read_b128 v[168:171], v178 offset:3072
	s_add_u32 s60, s58, 0xfffc0080
	s_addc_u32 s61, s59, -1
	s_cmp_eq_u32 s74, 12
	s_cselect_b32 s63, s3, s61
	s_cselect_b32 s62, s41, s60
	s_cselect_b32 s61, s45, s73
	s_cselect_b32 s60, s71, s72
	v_lshl_add_u64 v[172:173], s[58:59], 0, v[136:137]
	s_add_i32 m0, s28, 0xc000
	ds_read_b128 v[182:185], v179
	ds_read_b128 v[186:189], v179 offset:1024
	ds_read_b128 v[190:193], v179 offset:2048
	ds_read_b128 v[194:197], v179 offset:3072
	ds_read_b128 v[202:205], v179 offset:4096
	ds_read_b128 v[206:209], v179 offset:5120
	ds_read_b128 v[210:213], v179 offset:6144
	ds_read_b128 v[214:217], v179 offset:7168
	global_load_lds_dwordx4 v[172:173], off
	v_lshl_add_u64 v[172:173], s[58:59], 0, v[138:139]
	s_add_i32 m0, s28, 0xe000
	s_nop 0
	global_load_lds_dwordx4 v[172:173], off
	s_waitcnt vmcnt(8)
	s_waitcnt lgkmcnt(0)
; #define PG8_STAGE(bufoff, gbase, voff) do { _Pragma("unroll") for (int _i = 0; _i < 2; ++_i) \
;         __builtin_amdgcn_global_load_lds((const unsigned*)((const char*)(gbase) + (voff)[_i]), (PG8_LAS unsigned*)(lds + (bufoff) + ldsw + _i * 8192), 16, 0, 0); } while (0)
; #define PG8_LDA(dst, b, h) do { _Pragma("unroll") for (int m = 0; m < 4; ++m) _Pragma("unroll") for (int k = 0; k < 2; ++k) dst[m][k] = *(const PG8_LAS bf16x8*)(lds + PG8_SA(b, h) + aoff + m * 2048 + k * 1024); } while (0)
; #define PG8_MMA(ai, bj, At, Bt) do { __builtin_amdgcn_s_setprio(1); _Pragma("unroll") for (int m = 0; m < 4; ++m) _Pragma("unroll") for (int n = 0; n < 2; ++n) _Pragma("unroll") for (int k = 0; k < 2; ++k) \
;         acc[ai][bj][m][n] = __builtin_amdgcn_mfma_f32_16x16x32_bf16(Bt[n][k], At[m][k], acc[ai][bj][m][n], 0, 0, 0); __builtin_amdgcn_s_setprio(0); } while (0)
; #define PG8_WAIT_V(n) asm volatile("s_waitcnt vmcnt(" #n ")" ::: "memory")
; #define PG8_WAIT_L(n) asm volatile("s_waitcnt lgkmcnt(" #n ")" ::: "memory")
; #define PG8_BAR __builtin_amdgcn_s_barrier()
; #define PG8_SCHED __builtin_amdgcn_sched_barrier(0)
; template <class Epi, class Sched, bool ALIGN_EPI = false, bool SP2 = false>
; __device__ __forceinline__ void gemm_phase(PG8_LAS unsigned char* lds, const Gemm g, const Sched& S, const Epi& E) {
;     ...
;             PG8_WAIT_V(8); PG8_WAIT_L(0); PG8_BAR; PG8_MMA(0, 0, At, B0); PG8_MMA(0, 1, At, B1); PG8_BAR; PG8_SCHED;
;             PG8_LDA(At, 0, 1); PG8_STAGE(PG8_SB(0, 0), b2, voffB); PG8_STAGE(PG8_SB(0, 1), b2 + hstep, voffB); PG8_STAGE(PG8_SA(0, 0), a2, voffA);
;             PG8_WAIT_V(8); PG8_WAIT_L(0); PG8_BAR; PG8_MMA(1, 0, At, B0); PG8_MMA(1, 1, At, B1); PG8_BAR; PG8_SCHED;
.Lpeel_join_175:
	s_barrier
	s_setprio 1
	s_waitcnt lgkmcnt(0)
	v_mfma_f32_16x16x32_bf16 v[124:127], v[140:143], v[182:185], v[124:127]
	v_mfma_f32_16x16x32_bf16 v[120:123], v[148:151], v[182:185], v[120:123]
	v_mfma_f32_16x16x32_bf16 v[108:111], v[140:143], v[190:193], v[108:111]
	v_mfma_f32_16x16x32_bf16 v[104:107], v[148:151], v[190:193], v[104:107]
	v_mfma_f32_16x16x32_bf16 v[92:95], v[140:143], v[202:205], v[92:95]
	v_mfma_f32_16x16x32_bf16 v[88:91], v[148:151], v[202:205], v[88:91]
	v_mfma_f32_16x16x32_bf16 v[76:79], v[140:143], v[210:213], v[76:79]
	v_mfma_f32_16x16x32_bf16 v[72:75], v[148:151], v[210:213], v[72:75]
	v_mfma_f32_16x16x32_bf16 v[124:127], v[144:147], v[186:189], v[124:127]
	v_mfma_f32_16x16x32_bf16 v[120:123], v[152:155], v[186:189], v[120:123]
	v_mfma_f32_16x16x32_bf16 v[108:111], v[144:147], v[194:197], v[108:111]
	v_mfma_f32_16x16x32_bf16 v[104:107], v[152:155], v[194:197], v[104:107]
	v_mfma_f32_16x16x32_bf16 v[92:95], v[144:147], v[206:209], v[92:95]
	v_mfma_f32_16x16x32_bf16 v[88:91], v[152:155], v[206:209], v[88:91]
	v_mfma_f32_16x16x32_bf16 v[76:79], v[144:147], v[214:217], v[76:79]
	v_mfma_f32_16x16x32_bf16 v[72:75], v[152:155], v[214:217], v[72:75]
	s_setprio 0
	s_setprio 1
	v_mfma_f32_16x16x32_bf16 v[116:119], v[156:159], v[182:185], v[116:119]
	v_mfma_f32_16x16x32_bf16 v[112:115], v[164:167], v[182:185], v[112:115]
	v_mfma_f32_16x16x32_bf16 v[100:103], v[156:159], v[190:193], v[100:103]
	v_mfma_f32_16x16x32_bf16 v[96:99], v[164:167], v[190:193], v[96:99]
	v_mfma_f32_16x16x32_bf16 v[84:87], v[156:159], v[202:205], v[84:87]
	v_mfma_f32_16x16x32_bf16 v[80:83], v[164:167], v[202:205], v[80:83]
	v_mfma_f32_16x16x32_bf16 v[68:71], v[156:159], v[210:213], v[68:71]
	v_mfma_f32_16x16x32_bf16 v[64:67], v[164:167], v[210:213], v[64:67]
	v_mfma_f32_16x16x32_bf16 v[116:119], v[160:163], v[186:189], v[116:119]
	v_mfma_f32_16x16x32_bf16 v[112:115], v[168:171], v[186:189], v[112:115]
	v_mfma_f32_16x16x32_bf16 v[100:103], v[160:163], v[194:197], v[100:103]
	v_mfma_f32_16x16x32_bf16 v[96:99], v[168:171], v[194:197], v[96:99]
	v_mfma_f32_16x16x32_bf16 v[84:87], v[160:163], v[206:209], v[84:87]
	v_mfma_f32_16x16x32_bf16 v[80:83], v[168:171], v[206:209], v[80:83]
	v_mfma_f32_16x16x32_bf16 v[68:71], v[160:163], v[214:217], v[68:71]
	v_mfma_f32_16x16x32_bf16 v[64:67], v[168:171], v[214:217], v[64:67]
	s_setprio 0
	s_barrier
	s_add_i32 s75, s67, s21
	v_lshl_add_u64 v[172:173], s[60:61], 0, v[132:133]
	s_mov_b32 m0, s75
	ds_read_b128 v[182:185], v179 offset:16384
	ds_read_b128 v[186:189], v179 offset:17408
	ds_read_b128 v[190:193], v179 offset:18432
	ds_read_b128 v[194:197], v179 offset:19456
	ds_read_b128 v[202:205], v179 offset:20480
	ds_read_b128 v[206:209], v179 offset:21504
	ds_read_b128 v[210:213], v179 offset:22528
	ds_read_b128 v[214:217], v179 offset:23552
	global_load_lds_dwordx4 v[172:173], off
	s_add_i32 m0, s75, 0x2000
	s_add_u32 s76, s60, 0x40000
	v_lshl_add_u64 v[198:199], s[60:61], 0, v[128:129]
	s_addc_u32 s77, s61, 0
	s_add_i32 s75, s68, s21
	global_load_lds_dwordx4 v[198:199], off
	v_lshl_add_u64 v[218:219], s[76:77], 0, v[132:133]
	s_mov_b32 m0, s75
	v_lshl_add_u64 v[220:221], s[62:63], 0, v[130:131]
	global_load_lds_dwordx4 v[218:219], off
	v_lshl_add_u64 v[218:219], s[76:77], 0, v[128:129]
	s_add_i32 m0, s75, 0x2000
	s_nop 0
	global_load_lds_dwordx4 v[218:219], off
	v_lshl_add_u64 v[218:219], s[62:63], 0, v[134:135]
	s_mov_b32 m0, s28
	s_nop 0
	global_load_lds_dwordx4 v[218:219], off
	s_mov_b32 m0, s29
	s_nop 0
	global_load_lds_dwordx4 v[220:221], off
	s_waitcnt vmcnt(8)
	s_waitcnt lgkmcnt(0)
	s_barrier
	s_setprio 1
	s_waitcnt lgkmcnt(0)
	v_mfma_f32_16x16x32_bf16 v[60:63], v[140:143], v[182:185], v[60:63]
	v_mfma_f32_16x16x32_bf16 v[56:59], v[148:151], v[182:185], v[56:59]
	v_mfma_f32_16x16x32_bf16 v[44:47], v[140:143], v[190:193], v[44:47]
	v_mfma_f32_16x16x32_bf16 v[40:43], v[148:151], v[190:193], v[40:43]
	v_mfma_f32_16x16x32_bf16 v[28:31], v[140:143], v[202:205], v[28:31]
	v_mfma_f32_16x16x32_bf16 v[24:27], v[148:151], v[202:205], v[24:27]
	v_mfma_f32_16x16x32_bf16 v[12:15], v[140:143], v[210:213], v[12:15]
	v_mfma_f32_16x16x32_bf16 v[8:11], v[148:151], v[210:213], v[8:11]
	v_mfma_f32_16x16x32_bf16 v[60:63], v[144:147], v[186:189], v[60:63]
	v_mfma_f32_16x16x32_bf16 v[56:59], v[152:155], v[186:189], v[56:59]
	v_mfma_f32_16x16x32_bf16 v[44:47], v[144:147], v[194:197], v[44:47]
	v_mfma_f32_16x16x32_bf16 v[40:43], v[152:155], v[194:197], v[40:43]
	v_mfma_f32_16x16x32_bf16 v[28:31], v[144:147], v[206:209], v[28:31]
	v_mfma_f32_16x16x32_bf16 v[24:27], v[152:155], v[206:209], v[24:27]
	v_mfma_f32_16x16x32_bf16 v[12:15], v[144:147], v[214:217], v[12:15]
	v_mfma_f32_16x16x32_bf16 v[8:11], v[152:155], v[214:217], v[8:11]
	s_setprio 0
	s_setprio 1
	v_mfma_f32_16x16x32_bf16 v[52:55], v[156:159], v[182:185], v[52:55]
	v_mfma_f32_16x16x32_bf16 v[48:51], v[164:167], v[182:185], v[48:51]
	v_mfma_f32_16x16x32_bf16 v[36:39], v[156:159], v[190:193], v[36:39]
	v_mfma_f32_16x16x32_bf16 v[32:35], v[164:167], v[190:193], v[32:35]
	v_mfma_f32_16x16x32_bf16 v[20:23], v[156:159], v[202:205], v[20:23]
	v_mfma_f32_16x16x32_bf16 v[16:19], v[164:167], v[202:205], v[16:19]
	v_mfma_f32_16x16x32_bf16 v[4:7], v[156:159], v[210:213], v[4:7]
	v_mfma_f32_16x16x32_bf16 v[0:3], v[164:167], v[210:213], v[0:3]
	v_mfma_f32_16x16x32_bf16 v[52:55], v[160:163], v[186:189], v[52:55]
	v_mfma_f32_16x16x32_bf16 v[48:51], v[168:171], v[186:189], v[48:51]
	v_mfma_f32_16x16x32_bf16 v[36:39], v[160:163], v[194:197], v[36:39]
	v_mfma_f32_16x16x32_bf16 v[32:35], v[168:171], v[194:197], v[32:35]
	v_mfma_f32_16x16x32_bf16 v[20:23], v[160:163], v[206:209], v[20:23]
	v_mfma_f32_16x16x32_bf16 v[16:19], v[168:171], v[206:209], v[16:19]
	v_mfma_f32_16x16x32_bf16 v[4:7], v[160:163], v[214:217], v[4:7]
	v_mfma_f32_16x16x32_bf16 v[0:3], v[168:171], v[214:217], v[0:3]
	s_setprio 0
	s_barrier
; #define PG8_STAGE(bufoff, gbase, voff) do { _Pragma("unroll") for (int _i = 0; _i < 2; ++_i) \
;         __builtin_amdgcn_global_load_lds((const unsigned*)((const char*)(gbase) + (voff)[_i]), (PG8_LAS unsigned*)(lds + (bufoff) + ldsw + _i * 8192), 16, 0, 0); } while (0)
; #define PG8_LDA(dst, b, h) do { _Pragma("unroll") for (int m = 0; m < 4; ++m) _Pragma("unroll") for (int k = 0; k < 2; ++k) dst[m][k] = *(const PG8_LAS bf16x8*)(lds + PG8_SA(b, h) + aoff + m * 2048 + k * 1024); } while (0)
; #define PG8_LDB(dst, b, h) do { _Pragma("unroll") for (int n = 0; n < 2; ++n) _Pragma("unroll") for (int k = 0; k < 2; ++k) dst[n][k] = *(const PG8_LAS bf16x8*)(lds + PG8_SB(b, h) + boff + n * 2048 + k * 1024); } while (0)
; #define PG8_MMA(ai, bj, At, Bt) do { __builtin_amdgcn_s_setprio(1); _Pragma("unroll") for (int m = 0; m < 4; ++m) _Pragma("unroll") for (int n = 0; n < 2; ++n) _Pragma("unroll") for (int k = 0; k < 2; ++k) \
;         acc[ai][bj][m][n] = __builtin_amdgcn_mfma_f32_16x16x32_bf16(Bt[n][k], At[m][k], acc[ai][bj][m][n], 0, 0, 0); __builtin_amdgcn_s_setprio(0); } while (0)
; #define PG8_WAIT_V(n) asm volatile("s_waitcnt vmcnt(" #n ")" ::: "memory")
; #define PG8_WAIT_L(n) asm volatile("s_waitcnt lgkmcnt(" #n ")" ::: "memory")
; #define PG8_BAR __builtin_amdgcn_s_barrier()
; #define PG8_SCHED __builtin_amdgcn_sched_barrier(0)
; template <class Epi, class Sched, bool ALIGN_EPI = false, bool SP2 = false>
; __device__ __forceinline__ void gemm_phase(PG8_LAS unsigned char* lds, const Gemm g, const Sched& S, const Epi& E) {
;     ...
;             PG8_LDB(B0, 1, 0); PG8_LDB(B1, 1, 1); PG8_SCHED; PG8_LDA(At, 1, 0); PG8_STAGE(PG8_SA(0, 1), a2 + hstep, voffA);
;             PG8_WAIT_V(8); PG8_WAIT_L(0); PG8_BAR; PG8_MMA(0, 0, At, B0); PG8_MMA(0, 1, At, B1); PG8_BAR; PG8_SCHED;
;             PG8_LDA(At, 1, 1); PG8_STAGE(PG8_SB(1, 0), b3, voffB); PG8_STAGE(PG8_SB(1, 1), b3 + hstep, voffB); PG8_STAGE(PG8_SA(1, 0), a3, voffA);
;             PG8_WAIT_V(8); PG8_WAIT_L(0); PG8_BAR; PG8_MMA(1, 0, At, B0); PG8_MMA(1, 1, At, B1); PG8_BAR; PG8_SCHED;
	s_add_i32 s75, 0, 0x18000
	s_add_i32 s76, 0, 0x1c000
	v_add_u32_e32 v152, s75, v175
	v_add_u32_e32 v168, s76, v175
	ds_read_b128 v[140:143], v152
	ds_read_b128 v[144:147], v152 offset:1024
	ds_read_b128 v[148:151], v152 offset:2048
	ds_read_b128 v[152:155], v152 offset:3072
	ds_read_b128 v[156:159], v168
	ds_read_b128 v[160:163], v168 offset:1024
	ds_read_b128 v[164:167], v168 offset:2048
	ds_read_b128 v[168:171], v168 offset:3072
	s_add_u32 s62, s62, 0x40000
	s_addc_u32 s63, s63, 0
	s_mov_b32 m0, s30
	v_lshl_add_u64 v[222:223], s[62:63], 0, v[134:135]
	ds_read_b128 v[182:185], v179 offset:32768
	ds_read_b128 v[186:189], v179 offset:33792
	ds_read_b128 v[190:193], v179 offset:34816
	ds_read_b128 v[194:197], v179 offset:35840
	ds_read_b128 v[202:205], v179 offset:36864
	ds_read_b128 v[206:209], v179 offset:37888
	ds_read_b128 v[210:213], v179 offset:38912
	ds_read_b128 v[214:217], v179 offset:39936
	global_load_lds_dwordx4 v[222:223], off
	v_lshl_add_u64 v[222:223], s[62:63], 0, v[130:131]
	s_mov_b32 m0, s31
	s_nop 0
	global_load_lds_dwordx4 v[222:223], off
	s_waitcnt vmcnt(8)
	s_waitcnt lgkmcnt(0)
	s_barrier
	s_setprio 1
	s_waitcnt lgkmcnt(0)
	v_mfma_f32_16x16x32_bf16 v[124:127], v[140:143], v[182:185], v[124:127]
	v_mfma_f32_16x16x32_bf16 v[120:123], v[148:151], v[182:185], v[120:123]
	v_mfma_f32_16x16x32_bf16 v[108:111], v[140:143], v[190:193], v[108:111]
	v_mfma_f32_16x16x32_bf16 v[104:107], v[148:151], v[190:193], v[104:107]
	v_mfma_f32_16x16x32_bf16 v[92:95], v[140:143], v[202:205], v[92:95]
	v_mfma_f32_16x16x32_bf16 v[88:91], v[148:151], v[202:205], v[88:91]
	v_mfma_f32_16x16x32_bf16 v[76:79], v[140:143], v[210:213], v[76:79]
	v_mfma_f32_16x16x32_bf16 v[72:75], v[148:151], v[210:213], v[72:75]
	v_mfma_f32_16x16x32_bf16 v[124:127], v[144:147], v[186:189], v[124:127]
	v_mfma_f32_16x16x32_bf16 v[120:123], v[152:155], v[186:189], v[120:123]
	v_mfma_f32_16x16x32_bf16 v[108:111], v[144:147], v[194:197], v[108:111]
	v_mfma_f32_16x16x32_bf16 v[104:107], v[152:155], v[194:197], v[104:107]
	v_mfma_f32_16x16x32_bf16 v[92:95], v[144:147], v[206:209], v[92:95]
	v_mfma_f32_16x16x32_bf16 v[88:91], v[152:155], v[206:209], v[88:91]
	v_mfma_f32_16x16x32_bf16 v[76:79], v[144:147], v[214:217], v[76:79]
	v_mfma_f32_16x16x32_bf16 v[72:75], v[152:155], v[214:217], v[72:75]
	s_setprio 0
	s_setprio 1
	v_mfma_f32_16x16x32_bf16 v[116:119], v[156:159], v[182:185], v[116:119]
	v_mfma_f32_16x16x32_bf16 v[112:115], v[164:167], v[182:185], v[112:115]
	v_mfma_f32_16x16x32_bf16 v[100:103], v[156:159], v[190:193], v[100:103]
	v_mfma_f32_16x16x32_bf16 v[96:99], v[164:167], v[190:193], v[96:99]
	v_mfma_f32_16x16x32_bf16 v[84:87], v[156:159], v[202:205], v[84:87]
	v_mfma_f32_16x16x32_bf16 v[80:83], v[164:167], v[202:205], v[80:83]
	v_mfma_f32_16x16x32_bf16 v[68:71], v[156:159], v[210:213], v[68:71]
	v_mfma_f32_16x16x32_bf16 v[64:67], v[164:167], v[210:213], v[64:67]
	v_mfma_f32_16x16x32_bf16 v[116:119], v[160:163], v[186:189], v[116:119]
	v_mfma_f32_16x16x32_bf16 v[112:115], v[168:171], v[186:189], v[112:115]
	v_mfma_f32_16x16x32_bf16 v[100:103], v[160:163], v[194:197], v[100:103]
	v_mfma_f32_16x16x32_bf16 v[96:99], v[168:171], v[194:197], v[96:99]
	v_mfma_f32_16x16x32_bf16 v[84:87], v[160:163], v[206:209], v[84:87]
	v_mfma_f32_16x16x32_bf16 v[80:83], v[168:171], v[206:209], v[80:83]
	v_mfma_f32_16x16x32_bf16 v[68:71], v[160:163], v[214:217], v[68:71]
	v_mfma_f32_16x16x32_bf16 v[64:67], v[168:171], v[214:217], v[64:67]
	s_setprio 0
	s_barrier
	s_add_i32 s62, s75, s21
	v_lshl_add_u64 v[172:173], v[172:173], 0, s[36:37]
	s_mov_b32 m0, s62
	ds_read_b128 v[182:185], v179 offset:49152
	ds_read_b128 v[186:189], v179 offset:50176
	ds_read_b128 v[190:193], v179 offset:51200
	ds_read_b128 v[194:197], v179 offset:52224
	ds_read_b128 v[202:205], v179 offset:53248
	ds_read_b128 v[206:209], v179 offset:54272
	ds_read_b128 v[210:213], v179 offset:55296
	ds_read_b128 v[214:217], v179 offset:56320
	global_load_lds_dwordx4 v[172:173], off
	s_add_i32 m0, s62, 0x2000
	s_add_u32 s60, s60, 0x40080
	v_lshl_add_u64 v[172:173], v[198:199], 0, s[36:37]
	s_addc_u32 s61, s61, 0
	s_add_i32 s62, s76, s21
	global_load_lds_dwordx4 v[172:173], off
	v_lshl_add_u64 v[172:173], s[60:61], 0, v[132:133]
	s_mov_b32 m0, s62
	s_nop 0
	global_load_lds_dwordx4 v[172:173], off
	v_lshl_add_u64 v[172:173], s[60:61], 0, v[128:129]
	s_add_i32 m0, s62, 0x2000
	s_nop 0
	global_load_lds_dwordx4 v[172:173], off
	v_lshl_add_u64 v[172:173], v[218:219], 0, s[36:37]
	s_mov_b32 m0, s65
	s_nop 0
	global_load_lds_dwordx4 v[172:173], off
	v_lshl_add_u64 v[172:173], v[220:221], 0, s[36:37]
	s_mov_b32 m0, s66
	s_nop 0
	global_load_lds_dwordx4 v[172:173], off
	s_waitcnt vmcnt(8)
	s_waitcnt lgkmcnt(0)
	s_barrier
; __device__ __forceinline__ float ss_val(u64 v) { return (float)v * (1.0f / 1099511627776.0f); }
;     __device__ __forceinline__ void operator()(const f32x4 (&acc)[2][2][4][2], const Unit& u, const Unit& nxt, bool has_next, int wr, int wc, int fr, int fq) const {
;         const int row0 = u.pm * BM + wr * 64 + fr, col0 = u.pn * HALF + wc * 32 + 8 * fq;
;         u64 cur[8], warm[8];
; #pragma unroll
;         for (int g = 0; g < 8; ++g) cur[g] = rowss[row0 + (g >> 2) * HALF + (g & 3) * 16];
;         if (has_next) {
; #pragma unroll
;             for (int g = 0; g < 8; ++g) warm[g] = rowss[nxt.pm * BM + wr * 64 + fr + (g >> 2) * HALF + (g & 3) * 16];
;         }
; #pragma unroll
;         for (int g = 0; g < 8; ++g) {
;             const int ai = g >> 2, m = g & 3;
;             const float rs = __builtin_amdgcn_rsqf(ss_val(cur[g]) * inv_k + eps), rsn = rs * -1.44269504089f, rs2 = rs * rs;
;             float h[8];
; #pragma unroll
;             for (int n = 0; n < 2; ++n)
; #pragma unroll
;                 for (int jp = 0; jp < 2; ++jp) {
;                     const f32x2v av = {acc[ai][0][m][n][2 * jp], acc[ai][0][m][n][2 * jp + 1]}, gv = {acc[ai][1][m][n][2 * jp], acc[ai][1][m][n][2 * jp + 1]};
;                     const f32x2v t = (av * gv) * rs2, y = gv * rsn;
;                     f32x2v ex; ex.x = __builtin_amdgcn_exp2f(y.x); ex.y = __builtin_amdgcn_exp2f(y.y);
;                     const f32x2v d = ex + 1.0f;
;                     f32x2v r; r.x = __builtin_amdgcn_rcpf(d.x); r.y = __builtin_amdgcn_rcpf(d.y);
;                     const f32x2v o = t * r;
;                     h[4 * n + 2 * jp] = o.x; h[4 * n + 2 * jp + 1] = o.y;
	s_setprio 1
	s_waitcnt lgkmcnt(0)
	v_mfma_f32_16x16x32_bf16 v[60:63], v[140:143], v[182:185], v[60:63]
	v_mfma_f32_16x16x32_bf16 v[56:59], v[148:151], v[182:185], v[56:59]
	v_mfma_f32_16x16x32_bf16 v[44:47], v[140:143], v[190:193], v[44:47]
	v_mfma_f32_16x16x32_bf16 v[40:43], v[148:151], v[190:193], v[40:43]
	v_mfma_f32_16x16x32_bf16 v[28:31], v[140:143], v[202:205], v[28:31]
	v_mfma_f32_16x16x32_bf16 v[24:27], v[148:151], v[202:205], v[24:27]
	v_mfma_f32_16x16x32_bf16 v[12:15], v[140:143], v[210:213], v[12:15]
	v_mfma_f32_16x16x32_bf16 v[8:11], v[148:151], v[210:213], v[8:11]
	v_mfma_f32_16x16x32_bf16 v[60:63], v[144:147], v[186:189], v[60:63]
	v_mfma_f32_16x16x32_bf16 v[56:59], v[152:155], v[186:189], v[56:59]
	v_mfma_f32_16x16x32_bf16 v[44:47], v[144:147], v[194:197], v[44:47]
	v_mfma_f32_16x16x32_bf16 v[40:43], v[152:155], v[194:197], v[40:43]
	v_mfma_f32_16x16x32_bf16 v[28:31], v[144:147], v[206:209], v[28:31]
	v_mfma_f32_16x16x32_bf16 v[24:27], v[152:155], v[206:209], v[24:27]
	v_mfma_f32_16x16x32_bf16 v[12:15], v[144:147], v[214:217], v[12:15]
	v_mfma_f32_16x16x32_bf16 v[8:11], v[152:155], v[214:217], v[8:11]
	s_setprio 0
	s_setprio 1
	v_mfma_f32_16x16x32_bf16 v[52:55], v[156:159], v[182:185], v[52:55]
	v_mfma_f32_16x16x32_bf16 v[48:51], v[164:167], v[182:185], v[48:51]
	v_mfma_f32_16x16x32_bf16 v[36:39], v[156:159], v[190:193], v[36:39]
	v_mfma_f32_16x16x32_bf16 v[32:35], v[164:167], v[190:193], v[32:35]
	v_mfma_f32_16x16x32_bf16 v[20:23], v[156:159], v[202:205], v[20:23]
	v_mfma_f32_16x16x32_bf16 v[16:19], v[164:167], v[202:205], v[16:19]
	v_mfma_f32_16x16x32_bf16 v[4:7], v[156:159], v[210:213], v[4:7]
	v_mfma_f32_16x16x32_bf16 v[0:3], v[164:167], v[210:213], v[0:3]
	v_mfma_f32_16x16x32_bf16 v[52:55], v[160:163], v[186:189], v[52:55]
	v_mfma_f32_16x16x32_bf16 v[48:51], v[168:171], v[186:189], v[48:51]
	v_mfma_f32_16x16x32_bf16 v[36:39], v[160:163], v[194:197], v[36:39]
	v_mfma_f32_16x16x32_bf16 v[32:35], v[168:171], v[194:197], v[32:35]
	v_mfma_f32_16x16x32_bf16 v[20:23], v[160:163], v[206:209], v[20:23]
	v_mfma_f32_16x16x32_bf16 v[16:19], v[168:171], v[206:209], v[16:19]
	v_mfma_f32_16x16x32_bf16 v[4:7], v[160:163], v[214:217], v[4:7]
	v_mfma_f32_16x16x32_bf16 v[0:3], v[168:171], v[214:217], v[0:3]
	s_setprio 0
	s_barrier
	s_add_i32 s74, s74, 2
	s_add_u32 s58, s58, 0x100
	s_addc_u32 s59, s59, 0
	s_add_u32 s72, s72, 0x100
	s_addc_u32 s73, s73, 0
	s_cmp_gt_u32 s74, 13
	s_cbranch_scc0 .LBB0_175
	s_and_b64 vcc, exec, s[38:39]
	s_cbranch_vccz .LBB0_178
	s_barrier
.LBB0_178:
	v_lshl_add_u32 v168, s2, 8, v174
	v_ashrrev_i32_e32 v169, 31, v168
	v_lshl_add_u64 v[140:141], v[168:169], 3, s[26:27]
	v_mov_b32_e32 v172, v232
	v_mov_b32_e32 v173, v233
	v_mov_b32_e32 v170, v234
	v_mov_b32_e32 v171, v235
	v_mov_b32_e32 v166, v236
	v_mov_b32_e32 v167, v237
	v_mov_b32_e32 v164, v238
	v_mov_b32_e32 v165, v239
	v_mov_b32_e32 v162, v240
	v_mov_b32_e32 v163, v241
	v_mov_b32_e32 v160, v242
	v_mov_b32_e32 v161, v243
	v_mov_b32_e32 v158, v244
	v_mov_b32_e32 v159, v245
	v_mov_b32_e32 v156, v246
	v_mov_b32_e32 v157, v247
	v_cndmask_b32_e64 v140, 0, 1, s[56:57]
	v_cmp_ne_u32_e64 s[2:3], 1, v140
	s_andn2_b64 vcc, exec, s[56:57]
	s_cbranch_vccnz .LBB0_180
	v_lshl_add_u32 v140, s40, 8, v174
	v_ashrrev_i32_e32 v141, 31, v140
	v_lshl_add_u64 v[152:153], v[140:141], 3, s[26:27]
	global_load_dwordx2 v[232:233], v[152:153], off
	global_load_dwordx2 v[234:235], v[152:153], off offset:128
	global_load_dwordx2 v[236:237], v[152:153], off offset:256
	global_load_dwordx2 v[238:239], v[152:153], off offset:384
	global_load_dwordx2 v[240:241], v[152:153], off offset:1024
	global_load_dwordx2 v[242:243], v[152:153], off offset:1152
	global_load_dwordx2 v[244:245], v[152:153], off offset:1280
	s_nop 0
	global_load_dwordx2 v[246:247], v[152:153], off offset:1408
.LBB0_180:
	v_ffbh_u32_e32 v169, v173
	v_min_u32_e32 v169, 32, v169
	v_lshlrev_b64 v[172:173], v169, v[172:173]
	v_min_u32_e32 v172, 1, v172
	v_or_b32_e32 v172, v173, v172
	v_cvt_f32_u32_e32 v182, v172
	v_sub_u32_e32 v169, 32, v169
	v_or_b32_e32 v185, 16, v168
	v_pk_mul_f32 v[124:125], v[124:125], v[116:117]
	v_ldexp_f32 v169, v182, v169
	v_mul_f32_e32 v169, 0x2b800000, v169
	v_fmamk_f32 v169, v169, 0x3a800000, v180
	v_rsq_f32_e32 v186, v169
	v_pk_mul_f32 v[120:121], v[120:121], v[112:113]
	v_pk_mul_f32 v[126:127], v[126:127], v[118:119]
	v_pk_mul_f32 v[122:123], v[122:123], v[114:115]
	v_mul_f32_e32 v184, 0xbfb8aa3b, v186
	v_pk_mul_f32 v[116:117], v[116:117], v[184:185] op_sel_hi:[1,0]
	v_pk_mul_f32 v[112:113], v[112:113], v[184:185] op_sel_hi:[1,0]
	v_exp_f32_e32 v116, v116
	v_exp_f32_e32 v117, v117
	v_pk_mul_f32 v[118:119], v[118:119], v[184:185] op_sel_hi:[1,0]
	v_exp_f32_e32 v112, v112
	v_exp_f32_e32 v113, v113
	v_pk_mul_f32 v[114:115], v[114:115], v[184:185] op_sel_hi:[1,0]
	v_exp_f32_e32 v118, v118
	v_exp_f32_e32 v119, v119
	v_exp_f32_e32 v114, v114
	v_exp_f32_e32 v115, v115
	v_pk_add_f32 v[116:117], v[116:117], 1.0 op_sel_hi:[1,0]
	v_pk_add_f32 v[112:113], v[112:113], 1.0 op_sel_hi:[1,0]
	v_rcp_f32_e32 v116, v116
	v_rcp_f32_e32 v117, v117
	v_pk_add_f32 v[118:119], v[118:119], 1.0 op_sel_hi:[1,0]
	v_rcp_f32_e32 v112, v112
	v_rcp_f32_e32 v113, v113
	v_pk_add_f32 v[114:115], v[114:115], 1.0 op_sel_hi:[1,0]
	v_rcp_f32_e32 v118, v118
	v_rcp_f32_e32 v119, v119
	v_rcp_f32_e32 v114, v114
	v_rcp_f32_e32 v115, v115
	v_or_b32_e32 v187, 32, v168
	v_mul_f32_e32 v186, v186, v186
	v_pk_mul_f32 v[124:125], v[124:125], v[186:187] op_sel_hi:[1,0]
	v_pk_mul_f32 v[120:121], v[120:121], v[186:187] op_sel_hi:[1,0]
	v_pk_mul_f32 v[116:117], v[124:125], v[116:117]
	v_pk_mul_f32 v[124:125], v[126:127], v[186:187] op_sel_hi:[1,0]
; __device__ __forceinline__ unsigned cvt_pk_bf16(float lo, float hi) { unsigned r; asm volatile("v_cvt_pk_bf16_f32 %0, %1, %2" : "=v"(r) : "v"(lo), "v"(hi)); return r; }
; __device__ __forceinline__ float ss_val(u64 v) { return (float)v * (1.0f / 1099511627776.0f); }
;     __device__ __forceinline__ void operator()(const f32x4 (&acc)[2][2][4][2], const Unit& u, const Unit& nxt, bool has_next, int wr, int wc, int fr, int fq) const {
;     ...
;         for (int g = 0; g < 8; ++g) {
;             const int ai = g >> 2, m = g & 3;
;             const float rs = __builtin_amdgcn_rsqf(ss_val(cur[g]) * inv_k + eps), rsn = rs * -1.44269504089f, rs2 = rs * rs;
;             float h[8];
; #pragma unroll
;             for (int n = 0; n < 2; ++n)
; #pragma unroll
;                 for (int jp = 0; jp < 2; ++jp) {
;                     const f32x2v av = {acc[ai][0][m][n][2 * jp], acc[ai][0][m][n][2 * jp + 1]}, gv = {acc[ai][1][m][n][2 * jp], acc[ai][1][m][n][2 * jp + 1]};
;                     const f32x2v t = (av * gv) * rs2, y = gv * rsn;
;                     f32x2v ex; ex.x = __builtin_amdgcn_exp2f(y.x); ex.y = __builtin_amdgcn_exp2f(y.y);
;                     const f32x2v d = ex + 1.0f;
;                     f32x2v r; r.x = __builtin_amdgcn_rcpf(d.x); r.y = __builtin_amdgcn_rcpf(d.y);
;                     const f32x2v o = t * r;
;                     h[4 * n + 2 * jp] = o.x; h[4 * n + 2 * jp + 1] = o.y;
;                 }
;             u32x4 w; w.x = cvt_pk_bf16(h[0], h[1]); w.y = cvt_pk_bf16(h[2], h[3]); w.z = cvt_pk_bf16(h[4], h[5]); w.w = cvt_pk_bf16(h[6], h[7]);
;             *(u32x4*)(O + (size_t)(row0 + ai * HALF + m * 16) * ldc + col0) = w;
	v_pk_mul_f32 v[112:113], v[120:121], v[112:113]
	v_pk_mul_f32 v[120:121], v[122:123], v[186:187] op_sel_hi:[1,0]
	v_pk_mul_f32 v[118:119], v[124:125], v[118:119]
	v_pk_mul_f32 v[114:115], v[120:121], v[114:115]
	v_cvt_pk_bf16_f32 v116, v116, v117
	v_cvt_pk_bf16_f32 v117, v118, v119
	v_cvt_pk_bf16_f32 v118, v112, v113
	v_lshl_or_b32 v182, s70, 7, v176
	v_cvt_pk_bf16_f32 v119, v114, v115
	v_ffbh_u32_e32 v114, v171
	v_min_u32_e32 v122, 32, v114
	v_lshlrev_b64 v[114:115], v122, v[170:171]
	v_min_u32_e32 v114, 1, v114
	v_or_b32_e32 v114, v115, v114
	v_cvt_f32_u32_e32 v114, v114
	v_sub_u32_e32 v115, 32, v122
	v_ashrrev_i32_e32 v183, 31, v182
	v_mov_b64_e32 v[112:113], s[24:25]
	v_ldexp_f32 v114, v114, v115
	v_mul_f32_e32 v114, 0x2b800000, v114
	v_fmamk_f32 v114, v114, 0x3a800000, v180
	v_rsq_f32_e32 v122, v114
	v_mad_i64_i32 v[120:121], s[56:57], v168, s69, v[112:113]
	v_lshlrev_b64 v[114:115], 1, v[182:183]
	v_lshl_add_u64 v[120:121], v[120:121], 0, v[114:115]
	global_store_dwordx4 v[120:121], v[116:119], off
	v_pk_mul_f32 v[104:105], v[104:105], v[96:97]
	v_pk_mul_f32 v[108:109], v[108:109], v[100:101]
	v_mul_f32_e32 v116, 0xbfb8aa3b, v122
	v_pk_mul_f32 v[96:97], v[96:97], v[116:117] op_sel_hi:[1,0]
	v_pk_mul_f32 v[100:101], v[100:101], v[116:117] op_sel_hi:[1,0]
	v_pk_mul_f32 v[106:107], v[106:107], v[98:99]
	v_exp_f32_e32 v96, v96
	v_exp_f32_e32 v97, v97
	v_pk_mul_f32 v[98:99], v[98:99], v[116:117] op_sel_hi:[1,0]
	v_exp_f32_e32 v100, v100
	v_exp_f32_e32 v101, v101
	v_exp_f32_e32 v98, v98
	v_exp_f32_e32 v99, v99
	v_pk_add_f32 v[96:97], v[96:97], 1.0 op_sel_hi:[1,0]
	v_pk_add_f32 v[100:101], v[100:101], 1.0 op_sel_hi:[1,0]
	v_rcp_f32_e32 v96, v96
	v_rcp_f32_e32 v97, v97
	v_pk_add_f32 v[98:99], v[98:99], 1.0 op_sel_hi:[1,0]
	v_rcp_f32_e32 v100, v100
	v_rcp_f32_e32 v101, v101
	v_rcp_f32_e32 v98, v98
	v_rcp_f32_e32 v99, v99
	v_mul_f32_e32 v118, v122, v122
	v_pk_mul_f32 v[104:105], v[104:105], v[118:119] op_sel_hi:[1,0]
	v_pk_mul_f32 v[108:109], v[108:109], v[118:119] op_sel_hi:[1,0]
	v_pk_mul_f32 v[104:105], v[104:105], v[96:97]
	v_pk_mul_f32 v[96:97], v[106:107], v[118:119] op_sel_hi:[1,0]
	v_pk_mul_f32 v[100:101], v[108:109], v[100:101]
	v_pk_mul_f32 v[106:107], v[96:97], v[98:99]
	v_ffbh_u32_e32 v98, v167
	v_pk_mul_f32 v[110:111], v[110:111], v[102:103]
	v_pk_mul_f32 v[102:103], v[102:103], v[116:117] op_sel_hi:[1,0]
	v_cvt_pk_bf16_f32 v96, v100, v101
	v_min_u32_e32 v100, 32, v98
	v_exp_f32_e32 v102, v102
	v_exp_f32_e32 v103, v103
	v_lshlrev_b64 v[98:99], v100, v[166:167]
	v_min_u32_e32 v98, 1, v98
	v_or_b32_e32 v98, v99, v98
	v_cvt_f32_u32_e32 v101, v98
	v_pk_add_f32 v[102:103], v[102:103], 1.0 op_sel_hi:[1,0]
	v_sub_u32_e32 v100, 32, v100
	v_rcp_f32_e32 v102, v102
	v_rcp_f32_e32 v103, v103
	v_ldexp_f32 v100, v101, v100
	v_pk_mul_f32 v[108:109], v[110:111], v[118:119] op_sel_hi:[1,0]
	v_mul_f32_e32 v100, 0x2b800000, v100
	v_pk_mul_f32 v[102:103], v[108:109], v[102:103]
	v_fmamk_f32 v100, v100, 0x3a800000, v180
	v_cvt_pk_bf16_f32 v97, v102, v103
	v_rsq_f32_e32 v102, v100
	v_mad_i64_i32 v[100:101], s[56:57], v185, s69, v[112:113]
	v_lshl_add_u64 v[100:101], v[100:101], 0, v[114:115]
	v_cvt_pk_bf16_f32 v98, v104, v105
	v_cvt_pk_bf16_f32 v99, v106, v107
	global_store_dwordx4 v[100:101], v[96:99], off
	v_pk_mul_f32 v[88:89], v[88:89], v[80:81]
	v_pk_mul_f32 v[92:93], v[92:93], v[84:85]
	v_mul_f32_e32 v96, 0xbfb8aa3b, v102
	v_pk_mul_f32 v[80:81], v[80:81], v[96:97] op_sel_hi:[1,0]
	v_pk_mul_f32 v[84:85], v[84:85], v[96:97] op_sel_hi:[1,0]
	v_pk_mul_f32 v[90:91], v[90:91], v[82:83]
	v_exp_f32_e32 v80, v80
	v_exp_f32_e32 v81, v81
	v_pk_mul_f32 v[82:83], v[82:83], v[96:97] op_sel_hi:[1,0]
	v_exp_f32_e32 v84, v84
	v_exp_f32_e32 v85, v85
	v_exp_f32_e32 v82, v82
	v_exp_f32_e32 v83, v83
	v_pk_add_f32 v[80:81], v[80:81], 1.0 op_sel_hi:[1,0]
	v_pk_add_f32 v[84:85], v[84:85], 1.0 op_sel_hi:[1,0]
	v_rcp_f32_e32 v80, v80
	v_rcp_f32_e32 v81, v81
	v_pk_add_f32 v[82:83], v[82:83], 1.0 op_sel_hi:[1,0]
	v_rcp_f32_e32 v84, v84
	v_rcp_f32_e32 v85, v85
	v_rcp_f32_e32 v82, v82
	v_rcp_f32_e32 v83, v83
	v_mul_f32_e32 v98, v102, v102
	v_pk_mul_f32 v[88:89], v[88:89], v[98:99] op_sel_hi:[1,0]
	v_pk_mul_f32 v[92:93], v[92:93], v[98:99] op_sel_hi:[1,0]
	v_pk_mul_f32 v[88:89], v[88:89], v[80:81]
	v_pk_mul_f32 v[80:81], v[90:91], v[98:99] op_sel_hi:[1,0]
	v_pk_mul_f32 v[84:85], v[92:93], v[84:85]
	v_pk_mul_f32 v[90:91], v[80:81], v[82:83]
	v_ffbh_u32_e32 v82, v165
	v_pk_mul_f32 v[94:95], v[94:95], v[86:87]
	v_pk_mul_f32 v[86:87], v[86:87], v[96:97] op_sel_hi:[1,0]
	v_cvt_pk_bf16_f32 v80, v84, v85
	v_min_u32_e32 v84, 32, v82
	v_exp_f32_e32 v86, v86
	v_exp_f32_e32 v87, v87
	v_lshlrev_b64 v[82:83], v84, v[164:165]
	v_min_u32_e32 v82, 1, v82
	v_or_b32_e32 v82, v83, v82
	v_cvt_f32_u32_e32 v85, v82
	v_pk_add_f32 v[86:87], v[86:87], 1.0 op_sel_hi:[1,0]
	v_sub_u32_e32 v84, 32, v84
	v_rcp_f32_e32 v86, v86
	v_rcp_f32_e32 v87, v87
	v_ldexp_f32 v84, v85, v84
	v_pk_mul_f32 v[92:93], v[94:95], v[98:99] op_sel_hi:[1,0]
	v_mul_f32_e32 v84, 0x2b800000, v84
	v_pk_mul_f32 v[86:87], v[92:93], v[86:87]
	v_fmamk_f32 v84, v84, 0x3a800000, v180
	v_cvt_pk_bf16_f32 v81, v86, v87
	v_rsq_f32_e32 v86, v84
	v_mad_i64_i32 v[84:85], s[56:57], v187, s69, v[112:113]
	v_lshl_add_u64 v[84:85], v[84:85], 0, v[114:115]
	v_cvt_pk_bf16_f32 v82, v88, v89
	v_cvt_pk_bf16_f32 v83, v90, v91
	global_store_dwordx4 v[84:85], v[80:83], off
	v_pk_mul_f32 v[72:73], v[72:73], v[64:65]
	v_pk_mul_f32 v[76:77], v[76:77], v[68:69]
	v_mul_f32_e32 v80, 0xbfb8aa3b, v86
	v_pk_mul_f32 v[64:65], v[64:65], v[80:81] op_sel_hi:[1,0]
	v_pk_mul_f32 v[68:69], v[68:69], v[80:81] op_sel_hi:[1,0]
	v_pk_mul_f32 v[74:75], v[74:75], v[66:67]
; __device__ __forceinline__ unsigned cvt_pk_bf16(float lo, float hi) { unsigned r; asm volatile("v_cvt_pk_bf16_f32 %0, %1, %2" : "=v"(r) : "v"(lo), "v"(hi)); return r; }
; __device__ __forceinline__ float ss_val(u64 v) { return (float)v * (1.0f / 1099511627776.0f); }
;     __device__ __forceinline__ void operator()(const f32x4 (&acc)[2][2][4][2], const Unit& u, const Unit& nxt, bool has_next, int wr, int wc, int fr, int fq) const {
;     ...
;         for (int g = 0; g < 8; ++g) {
;             const int ai = g >> 2, m = g & 3;
;             const float rs = __builtin_amdgcn_rsqf(ss_val(cur[g]) * inv_k + eps), rsn = rs * -1.44269504089f, rs2 = rs * rs;
;             float h[8];
; #pragma unroll
;             for (int n = 0; n < 2; ++n)
; #pragma unroll
;                 for (int jp = 0; jp < 2; ++jp) {
;                     const f32x2v av = {acc[ai][0][m][n][2 * jp], acc[ai][0][m][n][2 * jp + 1]}, gv = {acc[ai][1][m][n][2 * jp], acc[ai][1][m][n][2 * jp + 1]};
;                     const f32x2v t = (av * gv) * rs2, y = gv * rsn;
;                     f32x2v ex; ex.x = __builtin_amdgcn_exp2f(y.x); ex.y = __builtin_amdgcn_exp2f(y.y);
;                     const f32x2v d = ex + 1.0f;
;                     f32x2v r; r.x = __builtin_amdgcn_rcpf(d.x); r.y = __builtin_amdgcn_rcpf(d.y);
;                     const f32x2v o = t * r;
;                     h[4 * n + 2 * jp] = o.x; h[4 * n + 2 * jp + 1] = o.y;
;                 }
;             u32x4 w; w.x = cvt_pk_bf16(h[0], h[1]); w.y = cvt_pk_bf16(h[2], h[3]); w.z = cvt_pk_bf16(h[4], h[5]); w.w = cvt_pk_bf16(h[6], h[7]);
;             *(u32x4*)(O + (size_t)(row0 + ai * HALF + m * 16) * ldc + col0) = w;
	v_exp_f32_e32 v64, v64
	v_exp_f32_e32 v65, v65
	v_pk_mul_f32 v[66:67], v[66:67], v[80:81] op_sel_hi:[1,0]
	v_exp_f32_e32 v68, v68
	v_exp_f32_e32 v69, v69
	v_exp_f32_e32 v66, v66
	v_exp_f32_e32 v67, v67
	v_pk_add_f32 v[64:65], v[64:65], 1.0 op_sel_hi:[1,0]
	v_pk_add_f32 v[68:69], v[68:69], 1.0 op_sel_hi:[1,0]
	v_rcp_f32_e32 v64, v64
	v_rcp_f32_e32 v65, v65
	v_pk_add_f32 v[66:67], v[66:67], 1.0 op_sel_hi:[1,0]
	v_rcp_f32_e32 v68, v68
	v_rcp_f32_e32 v69, v69
	v_rcp_f32_e32 v66, v66
	v_rcp_f32_e32 v67, v67
	v_mul_f32_e32 v82, v86, v86
	v_pk_mul_f32 v[72:73], v[72:73], v[82:83] op_sel_hi:[1,0]
	v_pk_mul_f32 v[76:77], v[76:77], v[82:83] op_sel_hi:[1,0]
	v_pk_mul_f32 v[72:73], v[72:73], v[64:65]
	v_pk_mul_f32 v[64:65], v[74:75], v[82:83] op_sel_hi:[1,0]
	v_pk_mul_f32 v[68:69], v[76:77], v[68:69]
	v_pk_mul_f32 v[74:75], v[64:65], v[66:67]
	v_ffbh_u32_e32 v66, v163
	v_pk_mul_f32 v[78:79], v[78:79], v[70:71]
	v_pk_mul_f32 v[70:71], v[70:71], v[80:81] op_sel_hi:[1,0]
	v_cvt_pk_bf16_f32 v64, v68, v69
	v_min_u32_e32 v68, 32, v66
	v_exp_f32_e32 v70, v70
	v_exp_f32_e32 v71, v71
	v_lshlrev_b64 v[66:67], v68, v[162:163]
	v_min_u32_e32 v66, 1, v66
	v_or_b32_e32 v66, v67, v66
	v_cvt_f32_u32_e32 v69, v66
	v_pk_add_f32 v[70:71], v[70:71], 1.0 op_sel_hi:[1,0]
	v_sub_u32_e32 v68, 32, v68
	v_rcp_f32_e32 v70, v70
	v_rcp_f32_e32 v71, v71
	v_ldexp_f32 v68, v69, v68
	v_pk_mul_f32 v[76:77], v[78:79], v[82:83] op_sel_hi:[1,0]
	v_mul_f32_e32 v68, 0x2b800000, v68
	v_pk_mul_f32 v[70:71], v[76:77], v[70:71]
	v_fmamk_f32 v68, v68, 0x3a800000, v180
	v_cvt_pk_bf16_f32 v65, v70, v71
	v_rsq_f32_e32 v70, v68
	v_or_b32_e32 v188, 48, v168
	v_mad_i64_i32 v[68:69], s[56:57], v188, s69, v[112:113]
	v_lshl_add_u64 v[68:69], v[68:69], 0, v[114:115]
	v_cvt_pk_bf16_f32 v66, v72, v73
	v_cvt_pk_bf16_f32 v67, v74, v75
	global_store_dwordx4 v[68:69], v[64:67], off
	v_pk_mul_f32 v[56:57], v[56:57], v[48:49]
	v_pk_mul_f32 v[60:61], v[60:61], v[52:53]
	v_mul_f32_e32 v64, 0xbfb8aa3b, v70
	v_pk_mul_f32 v[48:49], v[48:49], v[64:65] op_sel_hi:[1,0]
	v_pk_mul_f32 v[52:53], v[52:53], v[64:65] op_sel_hi:[1,0]
	v_pk_mul_f32 v[58:59], v[58:59], v[50:51]
	v_exp_f32_e32 v48, v48
	v_exp_f32_e32 v49, v49
	v_pk_mul_f32 v[50:51], v[50:51], v[64:65] op_sel_hi:[1,0]
	v_exp_f32_e32 v52, v52
	v_exp_f32_e32 v53, v53
	v_exp_f32_e32 v50, v50
	v_exp_f32_e32 v51, v51
	v_pk_add_f32 v[48:49], v[48:49], 1.0 op_sel_hi:[1,0]
	v_pk_add_f32 v[52:53], v[52:53], 1.0 op_sel_hi:[1,0]
	v_rcp_f32_e32 v48, v48
	v_rcp_f32_e32 v49, v49
	v_pk_add_f32 v[50:51], v[50:51], 1.0 op_sel_hi:[1,0]
	v_rcp_f32_e32 v52, v52
	v_rcp_f32_e32 v53, v53
	v_rcp_f32_e32 v50, v50
	v_rcp_f32_e32 v51, v51
	v_mul_f32_e32 v66, v70, v70
	v_pk_mul_f32 v[56:57], v[56:57], v[66:67] op_sel_hi:[1,0]
	v_pk_mul_f32 v[60:61], v[60:61], v[66:67] op_sel_hi:[1,0]
	v_pk_mul_f32 v[56:57], v[56:57], v[48:49]
	v_pk_mul_f32 v[48:49], v[58:59], v[66:67] op_sel_hi:[1,0]
	v_pk_mul_f32 v[52:53], v[60:61], v[52:53]
	v_pk_mul_f32 v[58:59], v[48:49], v[50:51]
	v_ffbh_u32_e32 v50, v161
	v_pk_mul_f32 v[62:63], v[62:63], v[54:55]
	v_pk_mul_f32 v[54:55], v[54:55], v[64:65] op_sel_hi:[1,0]
	v_cvt_pk_bf16_f32 v48, v52, v53
	v_min_u32_e32 v52, 32, v50
	v_exp_f32_e32 v54, v54
	v_exp_f32_e32 v55, v55
	v_lshlrev_b64 v[50:51], v52, v[160:161]
	v_min_u32_e32 v50, 1, v50
	v_or_b32_e32 v50, v51, v50
	v_cvt_f32_u32_e32 v53, v50
	v_pk_add_f32 v[54:55], v[54:55], 1.0 op_sel_hi:[1,0]
	v_sub_u32_e32 v52, 32, v52
	v_rcp_f32_e32 v54, v54
	v_rcp_f32_e32 v55, v55
	v_ldexp_f32 v52, v53, v52
	v_pk_mul_f32 v[60:61], v[62:63], v[66:67] op_sel_hi:[1,0]
	v_mul_f32_e32 v52, 0x2b800000, v52
	v_pk_mul_f32 v[54:55], v[60:61], v[54:55]
	v_fmamk_f32 v52, v52, 0x3a800000, v180
	v_cvt_pk_bf16_f32 v49, v54, v55
	v_rsq_f32_e32 v54, v52
	v_add_u32_e32 v181, 0x80, v168
	v_mad_i64_i32 v[52:53], s[56:57], v181, s69, v[112:113]
	v_lshl_add_u64 v[52:53], v[52:53], 0, v[114:115]
	v_cvt_pk_bf16_f32 v50, v56, v57
	v_cvt_pk_bf16_f32 v51, v58, v59
	global_store_dwordx4 v[52:53], v[48:51], off
	v_pk_mul_f32 v[40:41], v[40:41], v[32:33]
	v_pk_mul_f32 v[44:45], v[44:45], v[36:37]
	v_mul_f32_e32 v48, 0xbfb8aa3b, v54
	v_pk_mul_f32 v[32:33], v[32:33], v[48:49] op_sel_hi:[1,0]
	v_pk_mul_f32 v[36:37], v[36:37], v[48:49] op_sel_hi:[1,0]
	v_pk_mul_f32 v[42:43], v[42:43], v[34:35]
	v_exp_f32_e32 v32, v32
	v_exp_f32_e32 v33, v33
	v_pk_mul_f32 v[34:35], v[34:35], v[48:49] op_sel_hi:[1,0]
	v_exp_f32_e32 v36, v36
	v_exp_f32_e32 v37, v37
	v_exp_f32_e32 v34, v34
	v_exp_f32_e32 v35, v35
	v_pk_add_f32 v[32:33], v[32:33], 1.0 op_sel_hi:[1,0]
	v_pk_add_f32 v[36:37], v[36:37], 1.0 op_sel_hi:[1,0]
	v_rcp_f32_e32 v32, v32
	v_rcp_f32_e32 v33, v33
	v_pk_add_f32 v[34:35], v[34:35], 1.0 op_sel_hi:[1,0]
	v_rcp_f32_e32 v36, v36
	v_rcp_f32_e32 v37, v37
	v_rcp_f32_e32 v34, v34
	v_rcp_f32_e32 v35, v35
	v_mul_f32_e32 v50, v54, v54
	v_pk_mul_f32 v[40:41], v[40:41], v[50:51] op_sel_hi:[1,0]
	v_pk_mul_f32 v[44:45], v[44:45], v[50:51] op_sel_hi:[1,0]
	v_pk_mul_f32 v[40:41], v[40:41], v[32:33]
	v_pk_mul_f32 v[32:33], v[42:43], v[50:51] op_sel_hi:[1,0]
	v_pk_mul_f32 v[36:37], v[44:45], v[36:37]
	v_pk_mul_f32 v[42:43], v[32:33], v[34:35]
	v_ffbh_u32_e32 v34, v159
	v_pk_mul_f32 v[46:47], v[46:47], v[38:39]
; __device__ __forceinline__ unsigned cvt_pk_bf16(float lo, float hi) { unsigned r; asm volatile("v_cvt_pk_bf16_f32 %0, %1, %2" : "=v"(r) : "v"(lo), "v"(hi)); return r; }
; __device__ __forceinline__ float ss_val(u64 v) { return (float)v * (1.0f / 1099511627776.0f); }
;     __device__ __forceinline__ void operator()(const f32x4 (&acc)[2][2][4][2], const Unit& u, const Unit& nxt, bool has_next, int wr, int wc, int fr, int fq) const {
;     ...
;         for (int g = 0; g < 8; ++g) {
;             const int ai = g >> 2, m = g & 3;
;             const float rs = __builtin_amdgcn_rsqf(ss_val(cur[g]) * inv_k + eps), rsn = rs * -1.44269504089f, rs2 = rs * rs;
;             float h[8];
; #pragma unroll
;             for (int n = 0; n < 2; ++n)
; #pragma unroll
;                 for (int jp = 0; jp < 2; ++jp) {
;                     const f32x2v av = {acc[ai][0][m][n][2 * jp], acc[ai][0][m][n][2 * jp + 1]}, gv = {acc[ai][1][m][n][2 * jp], acc[ai][1][m][n][2 * jp + 1]};
;                     const f32x2v t = (av * gv) * rs2, y = gv * rsn;
;                     f32x2v ex; ex.x = __builtin_amdgcn_exp2f(y.x); ex.y = __builtin_amdgcn_exp2f(y.y);
;                     const f32x2v d = ex + 1.0f;
;                     f32x2v r; r.x = __builtin_amdgcn_rcpf(d.x); r.y = __builtin_amdgcn_rcpf(d.y);
;                     const f32x2v o = t * r;
;                     h[4 * n + 2 * jp] = o.x; h[4 * n + 2 * jp + 1] = o.y;
;                 }
;             u32x4 w; w.x = cvt_pk_bf16(h[0], h[1]); w.y = cvt_pk_bf16(h[2], h[3]); w.z = cvt_pk_bf16(h[4], h[5]); w.w = cvt_pk_bf16(h[6], h[7]);
;             *(u32x4*)(O + (size_t)(row0 + ai * HALF + m * 16) * ldc + col0) = w;
;         }
;         if (has_next) { u64 x = 0;
; #pragma unroll
;             for (int g = 0; g < 8; ++g) x |= warm[g];
;             asm volatile("" :: "v"((unsigned)x), "v"((unsigned)(x >> 32))); }
	v_pk_mul_f32 v[38:39], v[38:39], v[48:49] op_sel_hi:[1,0]
	v_cvt_pk_bf16_f32 v32, v36, v37
	v_min_u32_e32 v36, 32, v34
	v_exp_f32_e32 v38, v38
	v_exp_f32_e32 v39, v39
	v_lshlrev_b64 v[34:35], v36, v[158:159]
	v_min_u32_e32 v34, 1, v34
	v_or_b32_e32 v34, v35, v34
	v_cvt_f32_u32_e32 v37, v34
	v_pk_add_f32 v[38:39], v[38:39], 1.0 op_sel_hi:[1,0]
	v_sub_u32_e32 v36, 32, v36
	v_rcp_f32_e32 v38, v38
	v_rcp_f32_e32 v39, v39
	v_ldexp_f32 v36, v37, v36
	v_pk_mul_f32 v[44:45], v[46:47], v[50:51] op_sel_hi:[1,0]
	v_mul_f32_e32 v36, 0x2b800000, v36
	v_pk_mul_f32 v[38:39], v[44:45], v[38:39]
	v_fmamk_f32 v36, v36, 0x3a800000, v180
	v_cvt_pk_bf16_f32 v33, v38, v39
	v_rsq_f32_e32 v38, v36
	v_add_u32_e32 v173, 0x90, v168
	v_mad_i64_i32 v[36:37], s[56:57], v173, s69, v[112:113]
	v_lshl_add_u64 v[36:37], v[36:37], 0, v[114:115]
	v_cvt_pk_bf16_f32 v34, v40, v41
	v_cvt_pk_bf16_f32 v35, v42, v43
	global_store_dwordx4 v[36:37], v[32:35], off
	v_pk_mul_f32 v[24:25], v[24:25], v[16:17]
	v_pk_mul_f32 v[28:29], v[28:29], v[20:21]
	v_mul_f32_e32 v32, 0xbfb8aa3b, v38
	v_pk_mul_f32 v[16:17], v[16:17], v[32:33] op_sel_hi:[1,0]
	v_pk_mul_f32 v[20:21], v[20:21], v[32:33] op_sel_hi:[1,0]
	v_pk_mul_f32 v[26:27], v[26:27], v[18:19]
	v_exp_f32_e32 v16, v16
	v_exp_f32_e32 v17, v17
	v_pk_mul_f32 v[18:19], v[18:19], v[32:33] op_sel_hi:[1,0]
	v_exp_f32_e32 v20, v20
	v_exp_f32_e32 v21, v21
	v_exp_f32_e32 v18, v18
	v_exp_f32_e32 v19, v19
	v_pk_add_f32 v[16:17], v[16:17], 1.0 op_sel_hi:[1,0]
	v_pk_add_f32 v[20:21], v[20:21], 1.0 op_sel_hi:[1,0]
	v_rcp_f32_e32 v16, v16
	v_rcp_f32_e32 v17, v17
	v_pk_add_f32 v[18:19], v[18:19], 1.0 op_sel_hi:[1,0]
	v_rcp_f32_e32 v20, v20
	v_rcp_f32_e32 v21, v21
	v_rcp_f32_e32 v18, v18
	v_rcp_f32_e32 v19, v19
	v_mul_f32_e32 v34, v38, v38
	v_pk_mul_f32 v[24:25], v[24:25], v[34:35] op_sel_hi:[1,0]
	v_pk_mul_f32 v[28:29], v[28:29], v[34:35] op_sel_hi:[1,0]
	v_pk_mul_f32 v[24:25], v[24:25], v[16:17]
	v_pk_mul_f32 v[16:17], v[26:27], v[34:35] op_sel_hi:[1,0]
	v_pk_mul_f32 v[20:21], v[28:29], v[20:21]
	v_pk_mul_f32 v[26:27], v[16:17], v[18:19]
	v_ffbh_u32_e32 v18, v157
	v_pk_mul_f32 v[30:31], v[30:31], v[22:23]
	v_pk_mul_f32 v[22:23], v[22:23], v[32:33] op_sel_hi:[1,0]
	v_cvt_pk_bf16_f32 v16, v20, v21
	v_min_u32_e32 v20, 32, v18
	v_exp_f32_e32 v22, v22
	v_exp_f32_e32 v23, v23
	v_lshlrev_b64 v[18:19], v20, v[156:157]
	v_min_u32_e32 v18, 1, v18
	v_or_b32_e32 v18, v19, v18
	v_cvt_f32_u32_e32 v21, v18
	v_pk_add_f32 v[22:23], v[22:23], 1.0 op_sel_hi:[1,0]
	v_sub_u32_e32 v20, 32, v20
	v_rcp_f32_e32 v22, v22
	v_rcp_f32_e32 v23, v23
	v_ldexp_f32 v20, v21, v20
	v_pk_mul_f32 v[28:29], v[30:31], v[34:35] op_sel_hi:[1,0]
	v_mul_f32_e32 v20, 0x2b800000, v20
	v_pk_mul_f32 v[22:23], v[28:29], v[22:23]
	v_fmamk_f32 v20, v20, 0x3a800000, v180
	v_cvt_pk_bf16_f32 v17, v22, v23
	v_rsq_f32_e32 v22, v20
	v_add_u32_e32 v172, 0xa0, v168
	v_mad_i64_i32 v[20:21], s[56:57], v172, s69, v[112:113]
	v_lshl_add_u64 v[20:21], v[20:21], 0, v[114:115]
	v_cvt_pk_bf16_f32 v18, v24, v25
	v_cvt_pk_bf16_f32 v19, v26, v27
	global_store_dwordx4 v[20:21], v[16:19], off
	v_pk_mul_f32 v[12:13], v[12:13], v[4:5]
	v_pk_mul_f32 v[8:9], v[8:9], v[0:1]
	v_mul_f32_e32 v16, 0xbfb8aa3b, v22
	v_pk_mul_f32 v[4:5], v[4:5], v[16:17] op_sel_hi:[1,0]
	v_pk_mul_f32 v[0:1], v[0:1], v[16:17] op_sel_hi:[1,0]
	v_exp_f32_e32 v4, v4
	v_exp_f32_e32 v5, v5
	v_pk_mul_f32 v[10:11], v[10:11], v[2:3]
	v_exp_f32_e32 v0, v0
	v_exp_f32_e32 v1, v1
	v_pk_mul_f32 v[2:3], v[2:3], v[16:17] op_sel_hi:[1,0]
	v_pk_mul_f32 v[14:15], v[14:15], v[6:7]
	v_exp_f32_e32 v2, v2
	v_exp_f32_e32 v3, v3
	v_pk_mul_f32 v[6:7], v[6:7], v[16:17] op_sel_hi:[1,0]
	v_pk_add_f32 v[4:5], v[4:5], 1.0 op_sel_hi:[1,0]
	v_exp_f32_e32 v6, v6
	v_exp_f32_e32 v7, v7
	v_pk_add_f32 v[0:1], v[0:1], 1.0 op_sel_hi:[1,0]
	v_rcp_f32_e32 v4, v4
	v_rcp_f32_e32 v5, v5
	v_rcp_f32_e32 v0, v0
	v_rcp_f32_e32 v1, v1
	v_pk_add_f32 v[2:3], v[2:3], 1.0 op_sel_hi:[1,0]
	v_mul_f32_e32 v18, v22, v22
	v_rcp_f32_e32 v2, v2
	v_rcp_f32_e32 v3, v3
	v_pk_add_f32 v[6:7], v[6:7], 1.0 op_sel_hi:[1,0]
	v_pk_mul_f32 v[12:13], v[12:13], v[18:19] op_sel_hi:[1,0]
	v_rcp_f32_e32 v6, v6
	v_rcp_f32_e32 v7, v7
	v_pk_mul_f32 v[8:9], v[8:9], v[18:19] op_sel_hi:[1,0]
	v_add_u32_e32 v169, 0xb0, v168
	v_pk_mul_f32 v[4:5], v[12:13], v[4:5]
	v_pk_mul_f32 v[8:9], v[8:9], v[0:1]
	v_pk_mul_f32 v[0:1], v[10:11], v[18:19] op_sel_hi:[1,0]
	v_pk_mul_f32 v[12:13], v[14:15], v[18:19] op_sel_hi:[1,0]
	v_pk_mul_f32 v[10:11], v[0:1], v[2:3]
	v_cvt_pk_bf16_f32 v0, v4, v5
	v_mad_i64_i32 v[4:5], s[56:57], v169, s69, v[112:113]
	v_lshl_add_u64 v[4:5], v[4:5], 0, v[114:115]
	s_and_b64 vcc, exec, s[2:3]
	s_mov_b64 s[2:3], -1
	v_pk_mul_f32 v[6:7], v[12:13], v[6:7]
	s_nop 0
	v_cvt_pk_bf16_f32 v1, v6, v7
	v_cvt_pk_bf16_f32 v2, v8, v9
	v_cvt_pk_bf16_f32 v3, v10, v11
	global_store_dwordx4 v[4:5], v[0:3], off
	s_cbranch_vccnz .LBB0_171
	s_nop 0
	v_or_b32_e32 v0, v155, v153
	v_or_b32_e32 v1, v154, v152
	v_or3_b32 v0, v0, v149, v151
	v_or3_b32 v1, v1, v148, v150
	v_or3_b32 v0, v0, v145, v147
	v_or3_b32 v1, v1, v144, v146
	s_andn2_b64 vcc, exec, s[4:5]
	v_or3_b32 v0, v0, v141, v143
	v_or3_b32 v1, v1, v140, v142
	s_cbranch_vccnz .LBB0_170
	s_barrier
	s_branch .LBB0_170

; #define PG8_STAGE(bufoff, gbase, voff) do { _Pragma("unroll") for (int _i = 0; _i < 2; ++_i) \
;         __builtin_amdgcn_global_load_lds((const unsigned*)((const char*)(gbase) + (voff)[_i]), (PG8_LAS unsigned*)(lds + (bufoff) + ldsw + _i * 8192), 16, 0, 0); } while (0)
; #define PG8_WAIT_V(n) asm volatile("s_waitcnt vmcnt(" #n ")" ::: "memory")
; #define PG8_BAR __builtin_amdgcn_s_barrier()
;     __device__ __forceinline__ void operator()(const f32x4 (&acc)[2][2][4][2], const Unit& u, const Unit& nxt, bool has_next, int wr, int wc, int fr, int fq) const {
;         const int row0 = u.pm * BM + wr * 64 + fr, col0 = u.pn * HALF + wc * 32 + 8 * fq;
;         u64 cur[8], warm[8];
; #pragma unroll
;         for (int g = 0; g < 8; ++g) cur[g] = rowss[row0 + (g >> 2) * HALF + (g & 3) * 16];
; template <class Epi, class Sched, bool ALIGN_EPI = false, bool SP2 = false>
; __device__ __forceinline__ void gemm_phase(PG8_LAS unsigned char* lds, const Gemm g, const Sched& S, const Epi& E) {
;     ...
;     const char* cA = (const char*)g.A + (size_t)cur.pm * tstep; const char* cB = (const char*)g.Bt + (size_t)cur.pn * tstep;
;     S.a_ready(cur);
;     if constexpr (SP2) {
;         PG8_STAGE(PG8_SB(0, 0), cB, voffB); PG8_STAGE(PG8_SB(0, 1), cB + hstep, voffB); PG8_STAGE(PG8_SA(0, 0), cA, voffA); PG8_STAGE(PG8_SA(0, 1), cA + hstep, voffA);
;         if (wr == 1) PG8_BAR;
;         PG8_WAIT_V(2); PG8_BAR;
;         PG8_STAGE(PG8_SB(1, 0), cB + kstep, voffB); PG8_STAGE(PG8_SA(1, 0), cA + kstep, voffA); PG8_STAGE(PG8_SB(1, 1), cB + hstep + kstep, voffB);
;         PG8_WAIT_V(6); PG8_BAR;
;     } else {
;         PG8_STAGE(PG8_SB(0, 0), cB, voffB); PG8_STAGE(PG8_SA(0, 0), cA, voffA); PG8_STAGE(PG8_SB(0, 1), cB + hstep, voffB); PG8_STAGE(PG8_SA(0, 1), cA + hstep, voffA);
;         if (wr == 1) PG8_BAR;
;         PG8_WAIT_V(4); PG8_BAR;
;         PG8_STAGE(PG8_SB(1, 0), cB + kstep, voffB); PG8_STAGE(PG8_SA(1, 0), cA + kstep, voffA); PG8_STAGE(PG8_SB(1, 1), cB + hstep + kstep, voffB);
;         PG8_WAIT_V(6); PG8_BAR;
;     }
.LBB0_654:
	s_add_u32 s64, s26, 0x80000
	s_addc_u32 s65, s27, 0
	s_lshl_b32 s31, s31, 5
	s_mov_b64 s[66:67], 0x80
	s_and_b32 s57, s31, 0x60
	s_add_i32 m0, s20, 0x18000
	v_lshl_add_u64 v[6:7], v[6:7], 0, s[66:67]
	s_lshl_b32 s5, s56, 13
	s_lshl_b32 s60, s57, 7
	s_waitcnt vmcnt(2)
	s_barrier
	global_load_lds_dwordx4 v[6:7], off
	v_lshl_add_u64 v[4:5], v[4:5], 0, s[66:67]
	s_add_i32 m0, s20, 0x1a000
	s_add_i32 s31, s20, 0x8000
	s_add_i32 s37, s20, 0xa000
	global_load_lds_dwordx4 v[4:5], off
	v_lshl_add_u64 v[0:1], v[0:1], 0, s[66:67]
	s_mov_b32 m0, s31
	s_add_u32 s58, s82, 0x40080
	global_load_lds_dwordx4 v[0:1], off
	v_lshl_add_u64 v[0:1], v[2:3], 0, s[66:67]
	s_mov_b32 m0, s37
	s_addc_u32 s59, s83, 0
	global_load_lds_dwordx4 v[0:1], off
	s_add_i32 m0, s20, 0x1c000
	v_lshl_add_u64 v[0:1], s[58:59], 0, v[132:133]
	global_load_lds_dwordx4 v[0:1], off
	v_lshl_add_u64 v[0:1], s[58:59], 0, v[128:129]
	s_add_i32 m0, s20, 0x1e000
	v_lshlrev_b32_e32 v2, 2, v201
	global_load_lds_dwordx4 v[0:1], off
	v_and_b32_e32 v0, 15, v201
	v_lshlrev_b32_e32 v1, 1, v11
	v_lshl_or_b32 v145, s56, 6, v0
	v_lshl_or_b32 v0, v0, 6, v1
	v_and_b32_e32 v2, 32, v2
	v_bitop3_b32 v0, v0, s5, v2 bitop3:0xde
	v_lshlrev_b32_e32 v3, 6, v201
	s_movk_i32 s5, 0x3c0
	v_and_or_b32 v1, v3, s5, v1
	v_bitop3_b32 v188, s60, v1, v2 bitop3:0xf6
	v_lshlrev_b32_e32 v1, 8, v201
	v_and_b32_e32 v1, 0x38000, v1
	v_lshlrev_b32_e32 v2, 11, v12
	v_or3_b32 v1, v9, v1, v2
	v_add_u32_e32 v136, v1, v10
	v_lshlrev_b32_e32 v1, 4, v8
	s_waitcnt vmcnt(6)
	s_cmpk_lt_u32 s39, 0x100
	v_and_b32_e32 v1, 0x78000, v1
	s_sext_i32_i8 s86, s68
	s_cselect_b64 s[68:69], -1, 0
	v_or3_b32 v1, v9, v1, v2
	s_add_i32 s39, 0, 0x10000
	s_add_i32 s56, 0, 0x14000
	v_or_b32_e32 v189, s57, v11
	v_mov_b32_e32 v137, v133
	v_add_u32_e32 v138, v1, v10
	v_mov_b32_e32 v139, v133
	v_add_u32_e32 v190, s39, v188
	v_add_u32_e32 v191, s56, v188
	v_add_u32_e32 v192, 0, v0
	v_mov_b32_e32 v193, 0x358637bd
	s_movk_i32 s57, 0x1600
	v_lshl_add_u32 v232, s4, 8, v145
	v_ashrrev_i32_e32 v233, 31, v232
	v_lshl_add_u64 v[246:247], v[232:233], 3, s[64:65]
	global_load_dwordx2 v[232:233], v[246:247], off
	global_load_dwordx2 v[234:235], v[246:247], off offset:128
	global_load_dwordx2 v[236:237], v[246:247], off offset:256
	global_load_dwordx2 v[238:239], v[246:247], off offset:384
	global_load_dwordx2 v[240:241], v[246:247], off offset:1024
	global_load_dwordx2 v[242:243], v[246:247], off offset:1152
	global_load_dwordx2 v[244:245], v[246:247], off offset:1280
	global_load_dwordx2 v[246:247], v[246:247], off offset:1408
	s_barrier
	s_branch .LBB0_657

; #define PG8_STAGE(bufoff, gbase, voff) do { _Pragma("unroll") for (int _i = 0; _i < 2; ++_i) \
;         __builtin_amdgcn_global_load_lds((const unsigned*)((const char*)(gbase) + (voff)[_i]), (PG8_LAS unsigned*)(lds + (bufoff) + ldsw + _i * 8192), 16, 0, 0); } while (0)
; #define PG8_LDA(dst, b, h) do { _Pragma("unroll") for (int m = 0; m < 4; ++m) _Pragma("unroll") for (int k = 0; k < 2; ++k) dst[m][k] = *(const PG8_LAS bf16x8*)(lds + PG8_SA(b, h) + aoff + m * 2048 + k * 1024); } while (0)
; #define PG8_LDB(dst, b, h) do { _Pragma("unroll") for (int n = 0; n < 2; ++n) _Pragma("unroll") for (int k = 0; k < 2; ++k) dst[n][k] = *(const PG8_LAS bf16x8*)(lds + PG8_SB(b, h) + boff + n * 2048 + k * 1024); } while (0)
; #define PG8_WAIT_V(n) asm volatile("s_waitcnt vmcnt(" #n ")" ::: "memory")
; #define PG8_WAIT_L(n) asm volatile("s_waitcnt lgkmcnt(" #n ")" ::: "memory")
; #define PG8_BAR __builtin_amdgcn_s_barrier()
; #define PG8_SCHED __builtin_amdgcn_sched_barrier(0)
; template <class Epi, class Sched, bool ALIGN_EPI = false, bool SP2 = false>
; __device__ __forceinline__ void gemm_phase(PG8_LAS unsigned char* lds, const Gemm g, const Sched& S, const Epi& E) {
;     ...
;         const bool has_next = S.next(ui + 1, nxt);
;         const char* nA = has_next ? (const char*)g.A + (size_t)nxt.pm * tstep : cA; const char* nB = has_next ? (const char*)g.Bt + (size_t)nxt.pn * tstep : cB;
;         for (int t = 0; t < nt; t += 2) {
;             const bool last = (t == nt - 2);
;             const char* a1 = cA + (size_t)(t + 1) * kstep;
;             const char* a2 = last ? nA : cA + (size_t)(t + 2) * kstep; const char* b2 = last ? nB : cB + (size_t)(t + 2) * kstep;
;             const char* a3 = a2 + kstep; const char* b3 = b2 + kstep;
;             if (last && has_next) S.a_ready(nxt);
;             if constexpr (SP2) {
;             PG8_LDB(B0, 0, 0); PG8_LDB(B1, 0, 1); PG8_SCHED; PG8_LDA(At, 0, 0); PG8_STAGE(PG8_SA(1, 1), a1 + hstep, voffA);
;             PG8_WAIT_V(8); PG8_WAIT_L(0); PG8_BAR; PG8_MMA(0, 0, At, B0); PG8_MMA(0, 1, At, B1); PG8_BAR; PG8_SCHED;
;     ...
; #pragma unroll
;         for (int a = 0; a < 2; ++a)
; #pragma unroll
;             for (int b = 0; b < 2; ++b)
; #pragma unroll
;                 for (int m = 0; m < 4; ++m)
; #pragma unroll
;                     for (int n = 0; n < 2; ++n) acc[a][b][m][n] = (f32x4){0.f, 0.f, 0.f, 0.f};
.LBB0_659:
	s_ashr_i32 s71, s70, 31
	s_lshl_b64 s[58:59], s[70:71], 19
	s_add_u32 s74, s22, s58
	s_addc_u32 s75, s23, s59
	s_and_b64 s[58:59], s[78:79], exec
	s_cselect_b32 s5, s75, s81
	s_cselect_b32 s71, s74, s80
	s_ashr_i32 s73, s72, 31
	s_lshl_b64 s[58:59], s[72:73], 19
	s_add_u32 s76, s2, s58
	s_addc_u32 s77, s3, s59
	s_and_b64 s[58:59], s[78:79], exec
	s_cselect_b32 s73, s77, s83
	s_cselect_b32 s87, s76, s82
	s_add_u32 s80, s80, 0x40080
	s_addc_u32 s81, s81, 0
	s_add_u32 s88, s82, 0x100
	v_mov_b32_e32 v0, 0
	s_addc_u32 s89, s83, 0
	s_mov_b32 s90, -2
	v_mov_b32_e32 v1, v0
	v_mov_b32_e32 v2, v0
	v_mov_b32_e32 v3, v0
	v_mov_b32_e32 v4, v0
	v_mov_b32_e32 v5, v0
	v_mov_b32_e32 v6, v0
	v_mov_b32_e32 v7, v0
	v_mov_b32_e32 v16, v0
	v_mov_b32_e32 v17, v0
	v_mov_b32_e32 v18, v0
	v_mov_b32_e32 v19, v0
	v_mov_b32_e32 v20, v0
	v_mov_b32_e32 v21, v0
	v_mov_b32_e32 v22, v0
	v_mov_b32_e32 v23, v0
	v_mov_b32_e32 v32, v0
	v_mov_b32_e32 v33, v0
	v_mov_b32_e32 v34, v0
	v_mov_b32_e32 v35, v0
	v_mov_b32_e32 v36, v0
	v_mov_b32_e32 v37, v0
	v_mov_b32_e32 v38, v0
	v_mov_b32_e32 v39, v0
	v_mov_b32_e32 v48, v0
	v_mov_b32_e32 v49, v0
	v_mov_b32_e32 v50, v0
	v_mov_b32_e32 v51, v0
	v_mov_b32_e32 v52, v0
	v_mov_b32_e32 v53, v0
	v_mov_b32_e32 v54, v0
	v_mov_b32_e32 v55, v0
	v_mov_b32_e32 v8, v0
	v_mov_b32_e32 v9, v0
	v_mov_b32_e32 v10, v0
	v_mov_b32_e32 v11, v0
	v_mov_b32_e32 v12, v0
	v_mov_b32_e32 v13, v0
	v_mov_b32_e32 v14, v0
	v_mov_b32_e32 v15, v0
	v_mov_b32_e32 v24, v0
	v_mov_b32_e32 v25, v0
	v_mov_b32_e32 v26, v0
	v_mov_b32_e32 v27, v0
	v_mov_b32_e32 v28, v0
	v_mov_b32_e32 v29, v0
	v_mov_b32_e32 v30, v0
	v_mov_b32_e32 v31, v0
	v_mov_b32_e32 v40, v0
	v_mov_b32_e32 v41, v0
	v_mov_b32_e32 v42, v0
	v_mov_b32_e32 v43, v0
	v_mov_b32_e32 v44, v0
	v_mov_b32_e32 v45, v0
	v_mov_b32_e32 v46, v0
	v_mov_b32_e32 v47, v0
	v_mov_b32_e32 v56, v0
	v_mov_b32_e32 v57, v0
	v_mov_b32_e32 v58, v0
	v_mov_b32_e32 v59, v0
	v_mov_b32_e32 v60, v0
	v_mov_b32_e32 v61, v0
	v_mov_b32_e32 v62, v0
	v_mov_b32_e32 v63, v0
	v_mov_b32_e32 v64, v0
	v_mov_b32_e32 v65, v0
	v_mov_b32_e32 v66, v0
	v_mov_b32_e32 v67, v0
	v_mov_b32_e32 v68, v0
	v_mov_b32_e32 v69, v0
	v_mov_b32_e32 v70, v0
	v_mov_b32_e32 v71, v0
	v_mov_b32_e32 v80, v0
	v_mov_b32_e32 v81, v0
	v_mov_b32_e32 v82, v0
	v_mov_b32_e32 v83, v0
	v_mov_b32_e32 v84, v0
	v_mov_b32_e32 v85, v0
	v_mov_b32_e32 v86, v0
	v_mov_b32_e32 v87, v0
	v_mov_b32_e32 v96, v0
	v_mov_b32_e32 v97, v0
	v_mov_b32_e32 v98, v0
	v_mov_b32_e32 v99, v0
	v_mov_b32_e32 v100, v0
	v_mov_b32_e32 v101, v0
	v_mov_b32_e32 v102, v0
	v_mov_b32_e32 v103, v0
	v_mov_b32_e32 v112, v0
	v_mov_b32_e32 v113, v0
	v_mov_b32_e32 v114, v0
	v_mov_b32_e32 v115, v0
	v_mov_b32_e32 v116, v0
	v_mov_b32_e32 v117, v0
	v_mov_b32_e32 v118, v0
	v_mov_b32_e32 v119, v0
	v_mov_b32_e32 v72, v0
	v_mov_b32_e32 v73, v0
	v_mov_b32_e32 v74, v0
	v_mov_b32_e32 v75, v0
	v_mov_b32_e32 v76, v0
	v_mov_b32_e32 v77, v0
	v_mov_b32_e32 v78, v0
	v_mov_b32_e32 v79, v0
	v_mov_b32_e32 v88, v0
	v_mov_b32_e32 v89, v0
	v_mov_b32_e32 v90, v0
	v_mov_b32_e32 v91, v0
	v_mov_b32_e32 v92, v0
	v_mov_b32_e32 v93, v0
	v_mov_b32_e32 v94, v0
	v_mov_b32_e32 v95, v0
	v_mov_b32_e32 v104, v0
	v_mov_b32_e32 v105, v0
	v_mov_b32_e32 v106, v0
	v_mov_b32_e32 v107, v0
	v_mov_b32_e32 v108, v0
	v_mov_b32_e32 v109, v0
	v_mov_b32_e32 v110, v0
	v_mov_b32_e32 v111, v0
	v_mov_b32_e32 v120, v0
	v_mov_b32_e32 v121, v0
	v_mov_b32_e32 v122, v0
	v_mov_b32_e32 v123, v0
	v_mov_b32_e32 v124, v0
	v_mov_b32_e32 v125, v0
	v_mov_b32_e32 v126, v0
	v_mov_b32_e32 v127, v0
	ds_read_b128 v[140:143], v190
	ds_read_b128 v[146:149], v190 offset:1024
	ds_read_b128 v[150:153], v190 offset:2048
	ds_read_b128 v[154:157], v190 offset:3072
	ds_read_b128 v[158:161], v191
	ds_read_b128 v[162:165], v191 offset:1024
	ds_read_b128 v[166:169], v191 offset:2048
	ds_read_b128 v[170:173], v191 offset:3072
	s_add_u32 s58, s80, 0xfffc0080
	s_addc_u32 s59, s81, -1
	s_cmp_eq_u32 s90, 12
	s_cselect_b32 s85, s5, s59
	s_cselect_b32 s84, s71, s58
	s_cselect_b32 s83, s73, s89
	s_cselect_b32 s82, s87, s88
	v_lshl_add_u64 v[186:187], s[80:81], 0, v[136:137]
	s_add_i32 m0, s20, 0xc000
	ds_read_b128 v[174:177], v192
	ds_read_b128 v[178:181], v192 offset:1024
	ds_read_b128 v[182:185], v192 offset:2048
	ds_read_b128 v[194:197], v192 offset:3072
	ds_read_b128 v[206:209], v192 offset:4096
	ds_read_b128 v[210:213], v192 offset:5120
	ds_read_b128 v[214:217], v192 offset:6144
	ds_read_b128 v[218:221], v192 offset:7168
	global_load_lds_dwordx4 v[186:187], off
	v_lshl_add_u64 v[186:187], s[80:81], 0, v[138:139]
	s_add_i32 m0, s20, 0xe000
	s_nop 0
	global_load_lds_dwordx4 v[186:187], off
	s_waitcnt vmcnt(24)
	s_waitcnt lgkmcnt(0)
	s_branch .Lpeel_join_660
.LBB0_660:
	ds_read_b128 v[140:143], v190
	ds_read_b128 v[146:149], v190 offset:1024
	ds_read_b128 v[150:153], v190 offset:2048
	ds_read_b128 v[154:157], v190 offset:3072
	ds_read_b128 v[158:161], v191
	ds_read_b128 v[162:165], v191 offset:1024
	ds_read_b128 v[166:169], v191 offset:2048
	ds_read_b128 v[170:173], v191 offset:3072
	s_add_u32 s58, s80, 0xfffc0080
	s_addc_u32 s59, s81, -1
	s_cmp_eq_u32 s90, 12
	s_cselect_b32 s85, s5, s59
	s_cselect_b32 s84, s71, s58
	s_cselect_b32 s83, s73, s89
	s_cselect_b32 s82, s87, s88
	v_lshl_add_u64 v[186:187], s[80:81], 0, v[136:137]
	s_add_i32 m0, s20, 0xc000
	ds_read_b128 v[174:177], v192
	ds_read_b128 v[178:181], v192 offset:1024
	ds_read_b128 v[182:185], v192 offset:2048
	ds_read_b128 v[194:197], v192 offset:3072
	ds_read_b128 v[206:209], v192 offset:4096
	ds_read_b128 v[210:213], v192 offset:5120
	ds_read_b128 v[214:217], v192 offset:6144
	ds_read_b128 v[218:221], v192 offset:7168
	global_load_lds_dwordx4 v[186:187], off
	v_lshl_add_u64 v[186:187], s[80:81], 0, v[138:139]
	s_add_i32 m0, s20, 0xe000
	s_nop 0
	global_load_lds_dwordx4 v[186:187], off
	s_waitcnt vmcnt(8)
	s_waitcnt lgkmcnt(0)
; #define PG8_STAGE(bufoff, gbase, voff) do { _Pragma("unroll") for (int _i = 0; _i < 2; ++_i) \
;         __builtin_amdgcn_global_load_lds((const unsigned*)((const char*)(gbase) + (voff)[_i]), (PG8_LAS unsigned*)(lds + (bufoff) + ldsw + _i * 8192), 16, 0, 0); } while (0)
; #define PG8_LDA(dst, b, h) do { _Pragma("unroll") for (int m = 0; m < 4; ++m) _Pragma("unroll") for (int k = 0; k < 2; ++k) dst[m][k] = *(const PG8_LAS bf16x8*)(lds + PG8_SA(b, h) + aoff + m * 2048 + k * 1024); } while (0)
; #define PG8_MMA(ai, bj, At, Bt) do { __builtin_amdgcn_s_setprio(1); _Pragma("unroll") for (int m = 0; m < 4; ++m) _Pragma("unroll") for (int n = 0; n < 2; ++n) _Pragma("unroll") for (int k = 0; k < 2; ++k) \
;         acc[ai][bj][m][n] = __builtin_amdgcn_mfma_f32_16x16x32_bf16(Bt[n][k], At[m][k], acc[ai][bj][m][n], 0, 0, 0); __builtin_amdgcn_s_setprio(0); } while (0)
; #define PG8_WAIT_V(n) asm volatile("s_waitcnt vmcnt(" #n ")" ::: "memory")
; #define PG8_WAIT_L(n) asm volatile("s_waitcnt lgkmcnt(" #n ")" ::: "memory")
; #define PG8_BAR __builtin_amdgcn_s_barrier()
; #define PG8_SCHED __builtin_amdgcn_sched_barrier(0)
; template <class Epi, class Sched, bool ALIGN_EPI = false, bool SP2 = false>
; __device__ __forceinline__ void gemm_phase(PG8_LAS unsigned char* lds, const Gemm g, const Sched& S, const Epi& E) {
;     ...
;             PG8_WAIT_V(8); PG8_WAIT_L(0); PG8_BAR; PG8_MMA(0, 0, At, B0); PG8_MMA(0, 1, At, B1); PG8_BAR; PG8_SCHED;
;             PG8_LDA(At, 0, 1); PG8_STAGE(PG8_SB(0, 0), b2, voffB); PG8_STAGE(PG8_SB(0, 1), b2 + hstep, voffB); PG8_STAGE(PG8_SA(0, 0), a2, voffA);
;             PG8_WAIT_V(8); PG8_WAIT_L(0); PG8_BAR; PG8_MMA(1, 0, At, B0); PG8_MMA(1, 1, At, B1); PG8_BAR; PG8_SCHED;
.Lpeel_join_660:
	s_barrier
	s_setprio 1
	s_waitcnt lgkmcnt(0)
	v_mfma_f32_16x16x32_bf16 v[124:127], v[140:143], v[174:177], v[124:127]
	v_mfma_f32_16x16x32_bf16 v[120:123], v[150:153], v[174:177], v[120:123]
	v_mfma_f32_16x16x32_bf16 v[108:111], v[140:143], v[182:185], v[108:111]
	v_mfma_f32_16x16x32_bf16 v[104:107], v[150:153], v[182:185], v[104:107]
	v_mfma_f32_16x16x32_bf16 v[92:95], v[140:143], v[206:209], v[92:95]
	v_mfma_f32_16x16x32_bf16 v[88:91], v[150:153], v[206:209], v[88:91]
	v_mfma_f32_16x16x32_bf16 v[76:79], v[140:143], v[214:217], v[76:79]
	v_mfma_f32_16x16x32_bf16 v[72:75], v[150:153], v[214:217], v[72:75]
	v_mfma_f32_16x16x32_bf16 v[124:127], v[146:149], v[178:181], v[124:127]
	v_mfma_f32_16x16x32_bf16 v[120:123], v[154:157], v[178:181], v[120:123]
	v_mfma_f32_16x16x32_bf16 v[108:111], v[146:149], v[194:197], v[108:111]
	v_mfma_f32_16x16x32_bf16 v[104:107], v[154:157], v[194:197], v[104:107]
	v_mfma_f32_16x16x32_bf16 v[92:95], v[146:149], v[210:213], v[92:95]
	v_mfma_f32_16x16x32_bf16 v[88:91], v[154:157], v[210:213], v[88:91]
	v_mfma_f32_16x16x32_bf16 v[76:79], v[146:149], v[218:221], v[76:79]
	v_mfma_f32_16x16x32_bf16 v[72:75], v[154:157], v[218:221], v[72:75]
	s_setprio 0
	s_setprio 1
	v_mfma_f32_16x16x32_bf16 v[116:119], v[158:161], v[174:177], v[116:119]
	v_mfma_f32_16x16x32_bf16 v[112:115], v[166:169], v[174:177], v[112:115]
	v_mfma_f32_16x16x32_bf16 v[100:103], v[158:161], v[182:185], v[100:103]
	v_mfma_f32_16x16x32_bf16 v[96:99], v[166:169], v[182:185], v[96:99]
	v_mfma_f32_16x16x32_bf16 v[84:87], v[158:161], v[206:209], v[84:87]
	v_mfma_f32_16x16x32_bf16 v[80:83], v[166:169], v[206:209], v[80:83]
	v_mfma_f32_16x16x32_bf16 v[68:71], v[158:161], v[214:217], v[68:71]
	v_mfma_f32_16x16x32_bf16 v[64:67], v[166:169], v[214:217], v[64:67]
	v_mfma_f32_16x16x32_bf16 v[116:119], v[162:165], v[178:181], v[116:119]
	v_mfma_f32_16x16x32_bf16 v[112:115], v[170:173], v[178:181], v[112:115]
	v_mfma_f32_16x16x32_bf16 v[100:103], v[162:165], v[194:197], v[100:103]
	v_mfma_f32_16x16x32_bf16 v[96:99], v[170:173], v[194:197], v[96:99]
	v_mfma_f32_16x16x32_bf16 v[84:87], v[162:165], v[210:213], v[84:87]
	v_mfma_f32_16x16x32_bf16 v[80:83], v[170:173], v[210:213], v[80:83]
	v_mfma_f32_16x16x32_bf16 v[68:71], v[162:165], v[218:221], v[68:71]
	v_mfma_f32_16x16x32_bf16 v[64:67], v[170:173], v[218:221], v[64:67]
	s_setprio 0
	s_barrier
	s_add_i32 s58, s39, s11
	v_lshl_add_u64 v[186:187], s[82:83], 0, v[132:133]
	s_mov_b32 m0, s58
	ds_read_b128 v[174:177], v192 offset:16384
	ds_read_b128 v[178:181], v192 offset:17408
	ds_read_b128 v[182:185], v192 offset:18432
	ds_read_b128 v[194:197], v192 offset:19456
	ds_read_b128 v[206:209], v192 offset:20480
	ds_read_b128 v[210:213], v192 offset:21504
	ds_read_b128 v[214:217], v192 offset:22528
	ds_read_b128 v[218:221], v192 offset:23552
	global_load_lds_dwordx4 v[186:187], off
	s_add_i32 m0, s58, 0x2000
	s_add_u32 s58, s82, 0x40000
	v_lshl_add_u64 v[198:199], s[82:83], 0, v[128:129]
	s_addc_u32 s59, s83, 0
	s_add_i32 s60, s56, s11
	global_load_lds_dwordx4 v[198:199], off
	v_lshl_add_u64 v[222:223], s[58:59], 0, v[132:133]
	s_mov_b32 m0, s60
	v_lshl_add_u64 v[224:225], s[84:85], 0, v[130:131]
	global_load_lds_dwordx4 v[222:223], off
	v_lshl_add_u64 v[222:223], s[58:59], 0, v[128:129]
	s_add_i32 m0, s60, 0x2000
	s_nop 0
	global_load_lds_dwordx4 v[222:223], off
	v_lshl_add_u64 v[222:223], s[84:85], 0, v[134:135]
	s_mov_b32 m0, s20
	s_nop 0
	global_load_lds_dwordx4 v[222:223], off
	s_mov_b32 m0, s21
	s_nop 0
	global_load_lds_dwordx4 v[224:225], off
	s_waitcnt vmcnt(8)
	s_waitcnt lgkmcnt(0)
	s_barrier
	s_setprio 1
	s_waitcnt lgkmcnt(0)
	v_mfma_f32_16x16x32_bf16 v[60:63], v[140:143], v[174:177], v[60:63]
	v_mfma_f32_16x16x32_bf16 v[56:59], v[150:153], v[174:177], v[56:59]
	v_mfma_f32_16x16x32_bf16 v[44:47], v[140:143], v[182:185], v[44:47]
	v_mfma_f32_16x16x32_bf16 v[40:43], v[150:153], v[182:185], v[40:43]
	v_mfma_f32_16x16x32_bf16 v[28:31], v[140:143], v[206:209], v[28:31]
	v_mfma_f32_16x16x32_bf16 v[24:27], v[150:153], v[206:209], v[24:27]
	v_mfma_f32_16x16x32_bf16 v[12:15], v[140:143], v[214:217], v[12:15]
	v_mfma_f32_16x16x32_bf16 v[8:11], v[150:153], v[214:217], v[8:11]
	v_mfma_f32_16x16x32_bf16 v[60:63], v[146:149], v[178:181], v[60:63]
	v_mfma_f32_16x16x32_bf16 v[56:59], v[154:157], v[178:181], v[56:59]
	v_mfma_f32_16x16x32_bf16 v[44:47], v[146:149], v[194:197], v[44:47]
	v_mfma_f32_16x16x32_bf16 v[40:43], v[154:157], v[194:197], v[40:43]
	v_mfma_f32_16x16x32_bf16 v[28:31], v[146:149], v[210:213], v[28:31]
	v_mfma_f32_16x16x32_bf16 v[24:27], v[154:157], v[210:213], v[24:27]
	v_mfma_f32_16x16x32_bf16 v[12:15], v[146:149], v[218:221], v[12:15]
	v_mfma_f32_16x16x32_bf16 v[8:11], v[154:157], v[218:221], v[8:11]
	s_setprio 0
	s_setprio 1
	v_mfma_f32_16x16x32_bf16 v[52:55], v[158:161], v[174:177], v[52:55]
	v_mfma_f32_16x16x32_bf16 v[48:51], v[166:169], v[174:177], v[48:51]
	v_mfma_f32_16x16x32_bf16 v[36:39], v[158:161], v[182:185], v[36:39]
	v_mfma_f32_16x16x32_bf16 v[32:35], v[166:169], v[182:185], v[32:35]
	v_mfma_f32_16x16x32_bf16 v[20:23], v[158:161], v[206:209], v[20:23]
	v_mfma_f32_16x16x32_bf16 v[16:19], v[166:169], v[206:209], v[16:19]
	v_mfma_f32_16x16x32_bf16 v[4:7], v[158:161], v[214:217], v[4:7]
	v_mfma_f32_16x16x32_bf16 v[0:3], v[166:169], v[214:217], v[0:3]
	v_mfma_f32_16x16x32_bf16 v[52:55], v[162:165], v[178:181], v[52:55]
	v_mfma_f32_16x16x32_bf16 v[48:51], v[170:173], v[178:181], v[48:51]
	v_mfma_f32_16x16x32_bf16 v[36:39], v[162:165], v[194:197], v[36:39]
	v_mfma_f32_16x16x32_bf16 v[32:35], v[170:173], v[194:197], v[32:35]
	v_mfma_f32_16x16x32_bf16 v[20:23], v[162:165], v[210:213], v[20:23]
	v_mfma_f32_16x16x32_bf16 v[16:19], v[170:173], v[210:213], v[16:19]
	v_mfma_f32_16x16x32_bf16 v[4:7], v[162:165], v[218:221], v[4:7]
	v_mfma_f32_16x16x32_bf16 v[0:3], v[170:173], v[218:221], v[0:3]
	s_setprio 0
	s_barrier
; #define PG8_STAGE(bufoff, gbase, voff) do { _Pragma("unroll") for (int _i = 0; _i < 2; ++_i) \
;         __builtin_amdgcn_global_load_lds((const unsigned*)((const char*)(gbase) + (voff)[_i]), (PG8_LAS unsigned*)(lds + (bufoff) + ldsw + _i * 8192), 16, 0, 0); } while (0)
; #define PG8_LDA(dst, b, h) do { _Pragma("unroll") for (int m = 0; m < 4; ++m) _Pragma("unroll") for (int k = 0; k < 2; ++k) dst[m][k] = *(const PG8_LAS bf16x8*)(lds + PG8_SA(b, h) + aoff + m * 2048 + k * 1024); } while (0)
; #define PG8_LDB(dst, b, h) do { _Pragma("unroll") for (int n = 0; n < 2; ++n) _Pragma("unroll") for (int k = 0; k < 2; ++k) dst[n][k] = *(const PG8_LAS bf16x8*)(lds + PG8_SB(b, h) + boff + n * 2048 + k * 1024); } while (0)
; #define PG8_MMA(ai, bj, At, Bt) do { __builtin_amdgcn_s_setprio(1); _Pragma("unroll") for (int m = 0; m < 4; ++m) _Pragma("unroll") for (int n = 0; n < 2; ++n) _Pragma("unroll") for (int k = 0; k < 2; ++k) \
;         acc[ai][bj][m][n] = __builtin_amdgcn_mfma_f32_16x16x32_bf16(Bt[n][k], At[m][k], acc[ai][bj][m][n], 0, 0, 0); __builtin_amdgcn_s_setprio(0); } while (0)
; #define PG8_WAIT_V(n) asm volatile("s_waitcnt vmcnt(" #n ")" ::: "memory")
; #define PG8_WAIT_L(n) asm volatile("s_waitcnt lgkmcnt(" #n ")" ::: "memory")
; #define PG8_BAR __builtin_amdgcn_s_barrier()
; #define PG8_SCHED __builtin_amdgcn_sched_barrier(0)
; template <class Epi, class Sched, bool ALIGN_EPI = false, bool SP2 = false>
; __device__ __forceinline__ void gemm_phase(PG8_LAS unsigned char* lds, const Gemm g, const Sched& S, const Epi& E) {
;     ...
;             PG8_WAIT_V(8); PG8_WAIT_L(0); PG8_BAR; PG8_MMA(1, 0, At, B0); PG8_MMA(1, 1, At, B1); PG8_BAR; PG8_SCHED;
;             PG8_LDB(B0, 1, 0); PG8_LDB(B1, 1, 1); PG8_SCHED; PG8_LDA(At, 1, 0); PG8_STAGE(PG8_SA(0, 1), a2 + hstep, voffA);
;             PG8_WAIT_V(8); PG8_WAIT_L(0); PG8_BAR; PG8_MMA(0, 0, At, B0); PG8_MMA(0, 1, At, B1); PG8_BAR; PG8_SCHED;
;             PG8_LDA(At, 1, 1); PG8_STAGE(PG8_SB(1, 0), b3, voffB); PG8_STAGE(PG8_SB(1, 1), b3 + hstep, voffB); PG8_STAGE(PG8_SA(1, 0), a3, voffA);
	s_add_i32 s60, 0, 0x18000
	s_add_i32 s61, 0, 0x1c000
	v_add_u32_e32 v154, s60, v188
	v_add_u32_e32 v170, s61, v188
	ds_read_b128 v[140:143], v154
	ds_read_b128 v[146:149], v154 offset:1024
	ds_read_b128 v[150:153], v154 offset:2048
	ds_read_b128 v[154:157], v154 offset:3072
	ds_read_b128 v[158:161], v170
	ds_read_b128 v[162:165], v170 offset:1024
	ds_read_b128 v[166:169], v170 offset:2048
	ds_read_b128 v[170:173], v170 offset:3072
	s_add_u32 s58, s84, 0x40000
	s_addc_u32 s59, s85, 0
	s_mov_b32 m0, s28
	v_lshl_add_u64 v[226:227], s[58:59], 0, v[134:135]
	ds_read_b128 v[174:177], v192 offset:32768
	ds_read_b128 v[178:181], v192 offset:33792
	ds_read_b128 v[182:185], v192 offset:34816
	ds_read_b128 v[194:197], v192 offset:35840
	ds_read_b128 v[206:209], v192 offset:36864
	ds_read_b128 v[210:213], v192 offset:37888
	ds_read_b128 v[214:217], v192 offset:38912
	ds_read_b128 v[218:221], v192 offset:39936
	global_load_lds_dwordx4 v[226:227], off
	v_lshl_add_u64 v[226:227], s[58:59], 0, v[130:131]
	s_mov_b32 m0, s29
	s_nop 0
	global_load_lds_dwordx4 v[226:227], off
	s_waitcnt vmcnt(8)
	s_waitcnt lgkmcnt(0)
	s_barrier
	s_setprio 1
	s_waitcnt lgkmcnt(0)
	v_mfma_f32_16x16x32_bf16 v[124:127], v[140:143], v[174:177], v[124:127]
	v_mfma_f32_16x16x32_bf16 v[120:123], v[150:153], v[174:177], v[120:123]
	v_mfma_f32_16x16x32_bf16 v[108:111], v[140:143], v[182:185], v[108:111]
	v_mfma_f32_16x16x32_bf16 v[104:107], v[150:153], v[182:185], v[104:107]
	v_mfma_f32_16x16x32_bf16 v[92:95], v[140:143], v[206:209], v[92:95]
	v_mfma_f32_16x16x32_bf16 v[88:91], v[150:153], v[206:209], v[88:91]
	v_mfma_f32_16x16x32_bf16 v[76:79], v[140:143], v[214:217], v[76:79]
	v_mfma_f32_16x16x32_bf16 v[72:75], v[150:153], v[214:217], v[72:75]
	v_mfma_f32_16x16x32_bf16 v[124:127], v[146:149], v[178:181], v[124:127]
	v_mfma_f32_16x16x32_bf16 v[120:123], v[154:157], v[178:181], v[120:123]
	v_mfma_f32_16x16x32_bf16 v[108:111], v[146:149], v[194:197], v[108:111]
	v_mfma_f32_16x16x32_bf16 v[104:107], v[154:157], v[194:197], v[104:107]
	v_mfma_f32_16x16x32_bf16 v[92:95], v[146:149], v[210:213], v[92:95]
	v_mfma_f32_16x16x32_bf16 v[88:91], v[154:157], v[210:213], v[88:91]
	v_mfma_f32_16x16x32_bf16 v[76:79], v[146:149], v[218:221], v[76:79]
	v_mfma_f32_16x16x32_bf16 v[72:75], v[154:157], v[218:221], v[72:75]
	s_setprio 0
	s_setprio 1
	v_mfma_f32_16x16x32_bf16 v[116:119], v[158:161], v[174:177], v[116:119]
	v_mfma_f32_16x16x32_bf16 v[112:115], v[166:169], v[174:177], v[112:115]
	v_mfma_f32_16x16x32_bf16 v[100:103], v[158:161], v[182:185], v[100:103]
	v_mfma_f32_16x16x32_bf16 v[96:99], v[166:169], v[182:185], v[96:99]
	v_mfma_f32_16x16x32_bf16 v[84:87], v[158:161], v[206:209], v[84:87]
	v_mfma_f32_16x16x32_bf16 v[80:83], v[166:169], v[206:209], v[80:83]
	v_mfma_f32_16x16x32_bf16 v[68:71], v[158:161], v[214:217], v[68:71]
	v_mfma_f32_16x16x32_bf16 v[64:67], v[166:169], v[214:217], v[64:67]
	v_mfma_f32_16x16x32_bf16 v[116:119], v[162:165], v[178:181], v[116:119]
	v_mfma_f32_16x16x32_bf16 v[112:115], v[170:173], v[178:181], v[112:115]
	v_mfma_f32_16x16x32_bf16 v[100:103], v[162:165], v[194:197], v[100:103]
	v_mfma_f32_16x16x32_bf16 v[96:99], v[170:173], v[194:197], v[96:99]
	v_mfma_f32_16x16x32_bf16 v[84:87], v[162:165], v[210:213], v[84:87]
	v_mfma_f32_16x16x32_bf16 v[80:83], v[170:173], v[210:213], v[80:83]
	v_mfma_f32_16x16x32_bf16 v[68:71], v[162:165], v[218:221], v[68:71]
	v_mfma_f32_16x16x32_bf16 v[64:67], v[170:173], v[218:221], v[64:67]
	s_setprio 0
	s_barrier
	s_add_i32 s58, s60, s11
	v_lshl_add_u64 v[186:187], v[186:187], 0, s[66:67]
	s_mov_b32 m0, s58
	ds_read_b128 v[174:177], v192 offset:49152
	ds_read_b128 v[178:181], v192 offset:50176
	ds_read_b128 v[182:185], v192 offset:51200
	ds_read_b128 v[194:197], v192 offset:52224
	ds_read_b128 v[206:209], v192 offset:53248
	ds_read_b128 v[210:213], v192 offset:54272
	ds_read_b128 v[214:217], v192 offset:55296
	ds_read_b128 v[218:221], v192 offset:56320
	global_load_lds_dwordx4 v[186:187], off
	s_add_i32 m0, s58, 0x2000
	s_add_u32 s58, s82, 0x40080
	v_lshl_add_u64 v[186:187], v[198:199], 0, s[66:67]
	s_addc_u32 s59, s83, 0
	s_add_i32 s60, s61, s11
	global_load_lds_dwordx4 v[186:187], off
	v_lshl_add_u64 v[186:187], s[58:59], 0, v[132:133]
	s_mov_b32 m0, s60
	s_nop 0
	global_load_lds_dwordx4 v[186:187], off
	v_lshl_add_u64 v[186:187], s[58:59], 0, v[128:129]
	s_add_i32 m0, s60, 0x2000
	s_nop 0
	global_load_lds_dwordx4 v[186:187], off
	v_lshl_add_u64 v[186:187], v[222:223], 0, s[66:67]
	s_mov_b32 m0, s31
	s_nop 0
	global_load_lds_dwordx4 v[186:187], off
	v_lshl_add_u64 v[186:187], v[224:225], 0, s[66:67]
	s_mov_b32 m0, s37
	s_nop 0
	global_load_lds_dwordx4 v[186:187], off
	s_waitcnt vmcnt(8)
	s_waitcnt lgkmcnt(0)
	s_barrier
; #define PG8_BAR __builtin_amdgcn_s_barrier()
;     __device__ __forceinline__ void operator()(const f32x4 (&acc)[2][2][4][2], const Unit& u, const Unit& nxt, bool has_next, int wr, int wc, int fr, int fq) const {
;         const int row0 = u.pm * BM + wr * 64 + fr, col0 = u.pn * HALF + wc * 32 + 8 * fq;
;         u64 cur[8], warm[8];
; #pragma unroll
;         for (int g = 0; g < 8; ++g) cur[g] = rowss[row0 + (g >> 2) * HALF + (g & 3) * 16];
;         if (has_next) {
; #pragma unroll
;             for (int g = 0; g < 8; ++g) warm[g] = rowss[nxt.pm * BM + wr * 64 + fr + (g >> 2) * HALF + (g & 3) * 16];
; template <class Epi, class Sched, bool ALIGN_EPI = false, bool SP2 = false>
; __device__ __forceinline__ void gemm_phase(PG8_LAS unsigned char* lds, const Gemm g, const Sched& S, const Epi& E) {
;     ...
;             PG8_WAIT_V(8); PG8_WAIT_L(0); PG8_BAR; PG8_MMA(1, 0, At, B0); PG8_MMA(1, 1, At, B1); PG8_BAR; PG8_SCHED;
;             } else {
;             PG8_LDB(B0, 0, 0); PG8_SCHED; PG8_LDA(At, 0, 0); PG8_STAGE(PG8_SA(1, 1), a1 + hstep, voffA);
;             PG8_WAIT_L(8); PG8_BAR; PG8_WAIT_L(0); PG8_MMA(0, 0, At, B0); PG8_BAR; PG8_SCHED;
;             PG8_LDB(B1, 0, 1); PG8_STAGE(PG8_SB(0, 0), b2, voffB);
;             PG8_BAR; PG8_WAIT_L(0); PG8_MMA(0, 1, At, B1); PG8_BAR;
;             PG8_LDA(At, 0, 1); PG8_STAGE(PG8_SA(0, 0), a2, voffA);
;             PG8_BAR; PG8_WAIT_L(0); PG8_MMA(1, 0, At, B0); PG8_BAR; PG8_SCHED;
;             PG8_STAGE(PG8_SB(0, 1), b2 + hstep, voffB);
;             PG8_WAIT_V(6); PG8_BAR; PG8_MMA(1, 1, At, B1); PG8_BAR;
;             PG8_LDB(B0, 1, 0); PG8_SCHED; PG8_LDA(At, 1, 0); PG8_STAGE(PG8_SA(0, 1), a2 + hstep, voffA);
;             PG8_WAIT_L(8); PG8_BAR; PG8_WAIT_L(0); PG8_MMA(0, 0, At, B0); PG8_BAR; PG8_SCHED;
;             PG8_LDB(B1, 1, 1); PG8_STAGE(PG8_SB(1, 0), b3, voffB);
;             PG8_BAR; PG8_WAIT_L(0); PG8_MMA(0, 1, At, B1); PG8_BAR;
;             PG8_LDA(At, 1, 1); PG8_STAGE(PG8_SA(1, 0), a3, voffA);
;             PG8_BAR; PG8_WAIT_L(0); PG8_MMA(1, 0, At, B0); PG8_BAR; PG8_SCHED;
;             PG8_STAGE(PG8_SB(1, 1), b3 + hstep, voffB);
;             PG8_WAIT_V(6); PG8_BAR; PG8_MMA(1, 1, At, B1); PG8_BAR;
;             }
;         }
;         if constexpr (ALIGN_EPI) { if (wr == 0) PG8_BAR; }
;         if constexpr (!Epi::AFTER_DRAIN) { E(acc, cur, nxt, has_next, wr, wc, fr, fq); S.done(cur); }
	s_setprio 1
	s_waitcnt lgkmcnt(0)
	v_mfma_f32_16x16x32_bf16 v[60:63], v[140:143], v[174:177], v[60:63]
	v_mfma_f32_16x16x32_bf16 v[56:59], v[150:153], v[174:177], v[56:59]
	v_mfma_f32_16x16x32_bf16 v[44:47], v[140:143], v[182:185], v[44:47]
	v_mfma_f32_16x16x32_bf16 v[40:43], v[150:153], v[182:185], v[40:43]
	v_mfma_f32_16x16x32_bf16 v[28:31], v[140:143], v[206:209], v[28:31]
	v_mfma_f32_16x16x32_bf16 v[24:27], v[150:153], v[206:209], v[24:27]
	v_mfma_f32_16x16x32_bf16 v[12:15], v[140:143], v[214:217], v[12:15]
	v_mfma_f32_16x16x32_bf16 v[8:11], v[150:153], v[214:217], v[8:11]
	v_mfma_f32_16x16x32_bf16 v[60:63], v[146:149], v[178:181], v[60:63]
	v_mfma_f32_16x16x32_bf16 v[56:59], v[154:157], v[178:181], v[56:59]
	v_mfma_f32_16x16x32_bf16 v[44:47], v[146:149], v[194:197], v[44:47]
	v_mfma_f32_16x16x32_bf16 v[40:43], v[154:157], v[194:197], v[40:43]
	v_mfma_f32_16x16x32_bf16 v[28:31], v[146:149], v[210:213], v[28:31]
	v_mfma_f32_16x16x32_bf16 v[24:27], v[154:157], v[210:213], v[24:27]
	v_mfma_f32_16x16x32_bf16 v[12:15], v[146:149], v[218:221], v[12:15]
	v_mfma_f32_16x16x32_bf16 v[8:11], v[154:157], v[218:221], v[8:11]
	s_setprio 0
	s_setprio 1
	v_mfma_f32_16x16x32_bf16 v[52:55], v[158:161], v[174:177], v[52:55]
	v_mfma_f32_16x16x32_bf16 v[48:51], v[166:169], v[174:177], v[48:51]
	v_mfma_f32_16x16x32_bf16 v[36:39], v[158:161], v[182:185], v[36:39]
	v_mfma_f32_16x16x32_bf16 v[32:35], v[166:169], v[182:185], v[32:35]
	v_mfma_f32_16x16x32_bf16 v[20:23], v[158:161], v[206:209], v[20:23]
	v_mfma_f32_16x16x32_bf16 v[16:19], v[166:169], v[206:209], v[16:19]
	v_mfma_f32_16x16x32_bf16 v[4:7], v[158:161], v[214:217], v[4:7]
	v_mfma_f32_16x16x32_bf16 v[0:3], v[166:169], v[214:217], v[0:3]
	v_mfma_f32_16x16x32_bf16 v[52:55], v[162:165], v[178:181], v[52:55]
	v_mfma_f32_16x16x32_bf16 v[48:51], v[170:173], v[178:181], v[48:51]
	v_mfma_f32_16x16x32_bf16 v[36:39], v[162:165], v[194:197], v[36:39]
	v_mfma_f32_16x16x32_bf16 v[32:35], v[170:173], v[194:197], v[32:35]
	v_mfma_f32_16x16x32_bf16 v[20:23], v[162:165], v[210:213], v[20:23]
	v_mfma_f32_16x16x32_bf16 v[16:19], v[170:173], v[210:213], v[16:19]
	v_mfma_f32_16x16x32_bf16 v[4:7], v[162:165], v[218:221], v[4:7]
	v_mfma_f32_16x16x32_bf16 v[0:3], v[170:173], v[218:221], v[0:3]
	s_setprio 0
	s_barrier
	s_add_i32 s90, s90, 2
	s_add_u32 s80, s80, 0x100
	s_addc_u32 s81, s81, 0
	s_add_u32 s88, s88, 0x100
	s_addc_u32 s89, s89, 0
	s_cmp_gt_u32 s90, 13
	s_cbranch_scc0 .LBB0_660
	s_and_b64 vcc, exec, s[68:69]
	s_cbranch_vccz .LBB0_663
	s_barrier
.LBB0_663:
	v_lshl_add_u32 v182, s4, 8, v145
	v_ashrrev_i32_e32 v183, 31, v182
	v_or_b32_e32 v178, 16, v182
	v_or_b32_e32 v174, 32, v182
	v_lshl_add_u64 v[140:141], v[182:183], 3, s[64:65]
	v_ashrrev_i32_e32 v179, 31, v178
	v_ashrrev_i32_e32 v175, 31, v174
	v_or_b32_e32 v170, 48, v182
	v_lshl_add_u64 v[142:143], v[178:179], 3, s[64:65]
	v_lshl_add_u64 v[146:147], v[174:175], 3, s[64:65]
	v_ashrrev_i32_e32 v171, 31, v170
	v_mov_b32_e32 v186, v232
	v_mov_b32_e32 v187, v233
	v_mov_b32_e32 v184, v234
	v_mov_b32_e32 v185, v235
	v_mov_b32_e32 v180, v236
	v_mov_b32_e32 v181, v237
	v_mov_b32_e32 v172, v240
	v_mov_b32_e32 v173, v241
	v_add_u32_e32 v164, 0x90, v182
	v_add_u32_e32 v160, 0xa0, v182
	v_add_u32_e32 v140, 0xb0, v182
	v_lshl_add_u64 v[148:149], v[170:171], 3, s[64:65]
	v_ashrrev_i32_e32 v165, 31, v164
	v_ashrrev_i32_e32 v161, 31, v160
	v_ashrrev_i32_e32 v141, 31, v140
	v_lshl_add_u64 v[142:143], v[164:165], 3, s[64:65]
	v_lshl_add_u64 v[146:147], v[160:161], 3, s[64:65]
	v_lshl_add_u64 v[150:151], v[140:141], 3, s[64:65]
	v_mov_b32_e32 v176, v238
	v_mov_b32_e32 v177, v239
	v_mov_b32_e32 v168, v242
	v_mov_b32_e32 v169, v243
	v_mov_b32_e32 v166, v244
	v_mov_b32_e32 v167, v245
	v_mov_b32_e32 v162, v246
	v_mov_b32_e32 v163, v247
	v_cndmask_b32_e64 v141, 0, 1, s[78:79]
	v_cmp_ne_u32_e64 s[4:5], 1, v141
	s_andn2_b64 vcc, exec, s[78:79]
	s_cbranch_vccnz .LBB0_665
	v_lshl_add_u32 v142, s70, 8, v145
	v_ashrrev_i32_e32 v143, 31, v142
	v_lshl_add_u64 v[156:157], v[142:143], 3, s[64:65]
	global_load_dwordx2 v[232:233], v[156:157], off
	global_load_dwordx2 v[234:235], v[156:157], off offset:128
	global_load_dwordx2 v[236:237], v[156:157], off offset:256
	global_load_dwordx2 v[238:239], v[156:157], off offset:384
	global_load_dwordx2 v[240:241], v[156:157], off offset:1024
	global_load_dwordx2 v[242:243], v[156:157], off offset:1152
	global_load_dwordx2 v[244:245], v[156:157], off offset:1280
	s_nop 0
	global_load_dwordx2 v[246:247], v[156:157], off offset:1408
; __device__ __forceinline__ unsigned cvt_pk_bf16(float lo, float hi) { unsigned r; asm volatile("v_cvt_pk_bf16_f32 %0, %1, %2" : "=v"(r) : "v"(lo), "v"(hi)); return r; }
; __device__ __forceinline__ float ss_val(u64 v) { return (float)v * (1.0f / 1099511627776.0f); }
;     __device__ __forceinline__ void operator()(const f32x4 (&acc)[2][2][4][2], const Unit& u, const Unit& nxt, bool has_next, int wr, int wc, int fr, int fq) const {
;     ...
; #pragma unroll
;         for (int g = 0; g < 8; ++g) {
;             const int ai = g >> 2, m = g & 3;
;             const float rs = __builtin_amdgcn_rsqf(ss_val(cur[g]) * inv_k + eps), rsn = rs * -1.44269504089f, rs2 = rs * rs;
;             float h[8];
; #pragma unroll
;             for (int n = 0; n < 2; ++n)
; #pragma unroll
;                 for (int jp = 0; jp < 2; ++jp) {
;                     const f32x2v av = {acc[ai][0][m][n][2 * jp], acc[ai][0][m][n][2 * jp + 1]}, gv = {acc[ai][1][m][n][2 * jp], acc[ai][1][m][n][2 * jp + 1]};
;                     const f32x2v t = (av * gv) * rs2, y = gv * rsn;
;                     f32x2v ex; ex.x = __builtin_amdgcn_exp2f(y.x); ex.y = __builtin_amdgcn_exp2f(y.y);
;                     const f32x2v d = ex + 1.0f;
;                     f32x2v r; r.x = __builtin_amdgcn_rcpf(d.x); r.y = __builtin_amdgcn_rcpf(d.y);
;                     const f32x2v o = t * r;
;                     h[4 * n + 2 * jp] = o.x; h[4 * n + 2 * jp + 1] = o.y;
;                 }
;             u32x4 w; w.x = cvt_pk_bf16(h[0], h[1]); w.y = cvt_pk_bf16(h[2], h[3]); w.z = cvt_pk_bf16(h[4], h[5]); w.w = cvt_pk_bf16(h[6], h[7]);
;             *(u32x4*)(O + (size_t)(row0 + ai * HALF + m * 16) * ldc + col0) = w;
.LBB0_665:
	v_ffbh_u32_e32 v141, v187
	v_min_u32_e32 v161, 32, v141
	v_lshlrev_b64 v[186:187], v161, v[186:187]
	v_min_u32_e32 v141, 1, v186
	v_or_b32_e32 v141, v187, v141
	v_cvt_f32_u32_e32 v165, v141
	v_sub_u32_e32 v161, 32, v161
	v_pk_mul_f32 v[124:125], v[124:125], v[116:117]
	v_pk_mul_f32 v[120:121], v[120:121], v[112:113]
	v_ldexp_f32 v161, v165, v161
	v_mul_f32_e32 v161, 0x2b800000, v161
	v_fmamk_f32 v161, v161, 0x3a800000, v193
	v_rsq_f32_e32 v161, v161
	v_pk_mul_f32 v[126:127], v[126:127], v[118:119]
	v_pk_mul_f32 v[122:123], v[122:123], v[114:115]
	v_lshl_or_b32 v186, s86, 7, v189
	v_mul_f32_e32 v194, 0xbfb8aa3b, v161
	v_pk_mul_f32 v[116:117], v[116:117], v[194:195] op_sel_hi:[1,0]
	v_pk_mul_f32 v[112:113], v[112:113], v[194:195] op_sel_hi:[1,0]
	v_exp_f32_e32 v116, v116
	v_exp_f32_e32 v117, v117
	v_pk_mul_f32 v[118:119], v[118:119], v[194:195] op_sel_hi:[1,0]
	v_exp_f32_e32 v112, v112
	v_exp_f32_e32 v113, v113
	v_pk_mul_f32 v[114:115], v[114:115], v[194:195] op_sel_hi:[1,0]
	v_exp_f32_e32 v118, v118
	v_exp_f32_e32 v119, v119
	v_exp_f32_e32 v114, v114
	v_exp_f32_e32 v115, v115
	v_pk_add_f32 v[116:117], v[116:117], 1.0 op_sel_hi:[1,0]
	v_pk_add_f32 v[112:113], v[112:113], 1.0 op_sel_hi:[1,0]
	v_rcp_f32_e32 v116, v116
	v_rcp_f32_e32 v117, v117
	v_pk_add_f32 v[118:119], v[118:119], 1.0 op_sel_hi:[1,0]
	v_rcp_f32_e32 v112, v112
	v_rcp_f32_e32 v113, v113
	v_pk_add_f32 v[114:115], v[114:115], 1.0 op_sel_hi:[1,0]
	v_rcp_f32_e32 v118, v118
	v_rcp_f32_e32 v119, v119
	v_rcp_f32_e32 v114, v114
	v_rcp_f32_e32 v115, v115
	v_mul_f32_e32 v196, v161, v161
	v_pk_mul_f32 v[124:125], v[124:125], v[196:197] op_sel_hi:[1,0]
	v_pk_mul_f32 v[120:121], v[120:121], v[196:197] op_sel_hi:[1,0]
	v_pk_mul_f32 v[116:117], v[124:125], v[116:117]
	v_pk_mul_f32 v[124:125], v[126:127], v[196:197] op_sel_hi:[1,0]
	v_pk_mul_f32 v[112:113], v[120:121], v[112:113]
	v_pk_mul_f32 v[120:121], v[122:123], v[196:197] op_sel_hi:[1,0]
	v_pk_mul_f32 v[118:119], v[124:125], v[118:119]
	v_pk_mul_f32 v[114:115], v[120:121], v[114:115]
	v_cvt_pk_bf16_f32 v116, v116, v117
	v_cvt_pk_bf16_f32 v117, v118, v119
	v_cvt_pk_bf16_f32 v118, v112, v113
	v_ashrrev_i32_e32 v187, 31, v186
	v_cvt_pk_bf16_f32 v119, v114, v115
	v_ffbh_u32_e32 v114, v185
	v_min_u32_e32 v122, 32, v114
	v_lshlrev_b64 v[114:115], v122, v[184:185]
	v_min_u32_e32 v114, 1, v114
	v_or_b32_e32 v114, v115, v114
	v_cvt_f32_u32_e32 v114, v114
	v_sub_u32_e32 v115, 32, v122
	v_mov_b64_e32 v[112:113], s[24:25]
	v_mad_i64_i32 v[120:121], s[58:59], v182, s57, v[112:113]
	v_ldexp_f32 v114, v114, v115
	v_mul_f32_e32 v114, 0x2b800000, v114
	v_fmamk_f32 v114, v114, 0x3a800000, v193
	v_rsq_f32_e32 v122, v114
	v_lshlrev_b64 v[114:115], 1, v[186:187]
	v_lshl_add_u64 v[120:121], v[120:121], 0, v[114:115]
	global_store_dwordx4 v[120:121], v[116:119], off
	v_pk_mul_f32 v[104:105], v[104:105], v[96:97]
	v_pk_mul_f32 v[108:109], v[108:109], v[100:101]
	v_mul_f32_e32 v116, 0xbfb8aa3b, v122
	v_pk_mul_f32 v[96:97], v[96:97], v[116:117] op_sel_hi:[1,0]
	v_pk_mul_f32 v[100:101], v[100:101], v[116:117] op_sel_hi:[1,0]
	v_pk_mul_f32 v[106:107], v[106:107], v[98:99]
	v_exp_f32_e32 v96, v96
	v_exp_f32_e32 v97, v97
	v_pk_mul_f32 v[98:99], v[98:99], v[116:117] op_sel_hi:[1,0]
	v_exp_f32_e32 v100, v100
	v_exp_f32_e32 v101, v101
	v_exp_f32_e32 v98, v98
	v_exp_f32_e32 v99, v99
	v_pk_add_f32 v[96:97], v[96:97], 1.0 op_sel_hi:[1,0]
	v_pk_add_f32 v[100:101], v[100:101], 1.0 op_sel_hi:[1,0]
	v_rcp_f32_e32 v96, v96
	v_rcp_f32_e32 v97, v97
	v_pk_add_f32 v[98:99], v[98:99], 1.0 op_sel_hi:[1,0]
	v_rcp_f32_e32 v100, v100
	v_rcp_f32_e32 v101, v101
	v_rcp_f32_e32 v98, v98
	v_rcp_f32_e32 v99, v99
	v_mul_f32_e32 v118, v122, v122
	v_pk_mul_f32 v[104:105], v[104:105], v[118:119] op_sel_hi:[1,0]
	v_pk_mul_f32 v[108:109], v[108:109], v[118:119] op_sel_hi:[1,0]
	v_pk_mul_f32 v[104:105], v[104:105], v[96:97]
	v_pk_mul_f32 v[96:97], v[106:107], v[118:119] op_sel_hi:[1,0]
	v_pk_mul_f32 v[100:101], v[108:109], v[100:101]
	v_pk_mul_f32 v[106:107], v[96:97], v[98:99]
	v_ffbh_u32_e32 v98, v181
	v_pk_mul_f32 v[110:111], v[110:111], v[102:103]
	v_pk_mul_f32 v[102:103], v[102:103], v[116:117] op_sel_hi:[1,0]
	v_cvt_pk_bf16_f32 v96, v100, v101
	v_min_u32_e32 v100, 32, v98
	v_exp_f32_e32 v102, v102
	v_exp_f32_e32 v103, v103
	v_lshlrev_b64 v[98:99], v100, v[180:181]
	v_min_u32_e32 v98, 1, v98
	v_or_b32_e32 v98, v99, v98
	v_cvt_f32_u32_e32 v101, v98
	v_pk_add_f32 v[102:103], v[102:103], 1.0 op_sel_hi:[1,0]
	v_sub_u32_e32 v100, 32, v100
	v_rcp_f32_e32 v102, v102
	v_rcp_f32_e32 v103, v103
	v_ldexp_f32 v100, v101, v100
	v_pk_mul_f32 v[108:109], v[110:111], v[118:119] op_sel_hi:[1,0]
	v_mul_f32_e32 v100, 0x2b800000, v100
	v_pk_mul_f32 v[102:103], v[108:109], v[102:103]
	v_fmamk_f32 v100, v100, 0x3a800000, v193
	v_cvt_pk_bf16_f32 v97, v102, v103
	v_rsq_f32_e32 v102, v100
	v_mad_i64_i32 v[100:101], s[58:59], v178, s57, v[112:113]
	v_lshl_add_u64 v[100:101], v[100:101], 0, v[114:115]
	v_cvt_pk_bf16_f32 v98, v104, v105
	v_cvt_pk_bf16_f32 v99, v106, v107
	global_store_dwordx4 v[100:101], v[96:99], off
	v_pk_mul_f32 v[88:89], v[88:89], v[80:81]
	v_pk_mul_f32 v[92:93], v[92:93], v[84:85]
	v_mul_f32_e32 v96, 0xbfb8aa3b, v102
	v_pk_mul_f32 v[80:81], v[80:81], v[96:97] op_sel_hi:[1,0]
	v_pk_mul_f32 v[84:85], v[84:85], v[96:97] op_sel_hi:[1,0]
	v_pk_mul_f32 v[90:91], v[90:91], v[82:83]
	v_exp_f32_e32 v80, v80
	v_exp_f32_e32 v81, v81
	v_pk_mul_f32 v[82:83], v[82:83], v[96:97] op_sel_hi:[1,0]
	v_exp_f32_e32 v84, v84
	v_exp_f32_e32 v85, v85
	v_exp_f32_e32 v82, v82
	v_exp_f32_e32 v83, v83
	v_pk_add_f32 v[80:81], v[80:81], 1.0 op_sel_hi:[1,0]
	v_pk_add_f32 v[84:85], v[84:85], 1.0 op_sel_hi:[1,0]
; __device__ __forceinline__ unsigned cvt_pk_bf16(float lo, float hi) { unsigned r; asm volatile("v_cvt_pk_bf16_f32 %0, %1, %2" : "=v"(r) : "v"(lo), "v"(hi)); return r; }
; __device__ __forceinline__ float ss_val(u64 v) { return (float)v * (1.0f / 1099511627776.0f); }
;     __device__ __forceinline__ void operator()(const f32x4 (&acc)[2][2][4][2], const Unit& u, const Unit& nxt, bool has_next, int wr, int wc, int fr, int fq) const {
;     ...
; #pragma unroll
;         for (int g = 0; g < 8; ++g) {
;             const int ai = g >> 2, m = g & 3;
;             const float rs = __builtin_amdgcn_rsqf(ss_val(cur[g]) * inv_k + eps), rsn = rs * -1.44269504089f, rs2 = rs * rs;
;             float h[8];
; #pragma unroll
;             for (int n = 0; n < 2; ++n)
; #pragma unroll
;                 for (int jp = 0; jp < 2; ++jp) {
;                     const f32x2v av = {acc[ai][0][m][n][2 * jp], acc[ai][0][m][n][2 * jp + 1]}, gv = {acc[ai][1][m][n][2 * jp], acc[ai][1][m][n][2 * jp + 1]};
;                     const f32x2v t = (av * gv) * rs2, y = gv * rsn;
;                     f32x2v ex; ex.x = __builtin_amdgcn_exp2f(y.x); ex.y = __builtin_amdgcn_exp2f(y.y);
;                     const f32x2v d = ex + 1.0f;
;                     f32x2v r; r.x = __builtin_amdgcn_rcpf(d.x); r.y = __builtin_amdgcn_rcpf(d.y);
;                     const f32x2v o = t * r;
;                     h[4 * n + 2 * jp] = o.x; h[4 * n + 2 * jp + 1] = o.y;
;                 }
;             u32x4 w; w.x = cvt_pk_bf16(h[0], h[1]); w.y = cvt_pk_bf16(h[2], h[3]); w.z = cvt_pk_bf16(h[4], h[5]); w.w = cvt_pk_bf16(h[6], h[7]);
;             *(u32x4*)(O + (size_t)(row0 + ai * HALF + m * 16) * ldc + col0) = w;
	v_rcp_f32_e32 v80, v80
	v_rcp_f32_e32 v81, v81
	v_pk_add_f32 v[82:83], v[82:83], 1.0 op_sel_hi:[1,0]
	v_rcp_f32_e32 v84, v84
	v_rcp_f32_e32 v85, v85
	v_rcp_f32_e32 v82, v82
	v_rcp_f32_e32 v83, v83
	v_mul_f32_e32 v98, v102, v102
	v_pk_mul_f32 v[88:89], v[88:89], v[98:99] op_sel_hi:[1,0]
	v_pk_mul_f32 v[92:93], v[92:93], v[98:99] op_sel_hi:[1,0]
	v_pk_mul_f32 v[88:89], v[88:89], v[80:81]
	v_pk_mul_f32 v[80:81], v[90:91], v[98:99] op_sel_hi:[1,0]
	v_pk_mul_f32 v[84:85], v[92:93], v[84:85]
	v_pk_mul_f32 v[90:91], v[80:81], v[82:83]
	v_ffbh_u32_e32 v82, v177
	v_pk_mul_f32 v[94:95], v[94:95], v[86:87]
	v_pk_mul_f32 v[86:87], v[86:87], v[96:97] op_sel_hi:[1,0]
	v_cvt_pk_bf16_f32 v80, v84, v85
	v_min_u32_e32 v84, 32, v82
	v_exp_f32_e32 v86, v86
	v_exp_f32_e32 v87, v87
	v_lshlrev_b64 v[82:83], v84, v[176:177]
	v_min_u32_e32 v82, 1, v82
	v_or_b32_e32 v82, v83, v82
	v_cvt_f32_u32_e32 v85, v82
	v_pk_add_f32 v[86:87], v[86:87], 1.0 op_sel_hi:[1,0]
	v_sub_u32_e32 v84, 32, v84
	v_rcp_f32_e32 v86, v86
	v_rcp_f32_e32 v87, v87
	v_ldexp_f32 v84, v85, v84
	v_pk_mul_f32 v[92:93], v[94:95], v[98:99] op_sel_hi:[1,0]
	v_mul_f32_e32 v84, 0x2b800000, v84
	v_pk_mul_f32 v[86:87], v[92:93], v[86:87]
	v_fmamk_f32 v84, v84, 0x3a800000, v193
	v_cvt_pk_bf16_f32 v81, v86, v87
	v_rsq_f32_e32 v86, v84
	v_mad_i64_i32 v[84:85], s[58:59], v174, s57, v[112:113]
	v_lshl_add_u64 v[84:85], v[84:85], 0, v[114:115]
	v_cvt_pk_bf16_f32 v82, v88, v89
	v_cvt_pk_bf16_f32 v83, v90, v91
	global_store_dwordx4 v[84:85], v[80:83], off
	v_pk_mul_f32 v[72:73], v[72:73], v[64:65]
	v_pk_mul_f32 v[76:77], v[76:77], v[68:69]
	v_mul_f32_e32 v80, 0xbfb8aa3b, v86
	v_pk_mul_f32 v[64:65], v[64:65], v[80:81] op_sel_hi:[1,0]
	v_pk_mul_f32 v[68:69], v[68:69], v[80:81] op_sel_hi:[1,0]
	v_pk_mul_f32 v[74:75], v[74:75], v[66:67]
	v_exp_f32_e32 v64, v64
	v_exp_f32_e32 v65, v65
	v_pk_mul_f32 v[66:67], v[66:67], v[80:81] op_sel_hi:[1,0]
	v_exp_f32_e32 v68, v68
	v_exp_f32_e32 v69, v69
	v_exp_f32_e32 v66, v66
	v_exp_f32_e32 v67, v67
	v_pk_add_f32 v[64:65], v[64:65], 1.0 op_sel_hi:[1,0]
	v_pk_add_f32 v[68:69], v[68:69], 1.0 op_sel_hi:[1,0]
	v_rcp_f32_e32 v64, v64
	v_rcp_f32_e32 v65, v65
	v_pk_add_f32 v[66:67], v[66:67], 1.0 op_sel_hi:[1,0]
	v_rcp_f32_e32 v68, v68
	v_rcp_f32_e32 v69, v69
	v_rcp_f32_e32 v66, v66
	v_rcp_f32_e32 v67, v67
	v_mul_f32_e32 v82, v86, v86
	v_pk_mul_f32 v[72:73], v[72:73], v[82:83] op_sel_hi:[1,0]
	v_pk_mul_f32 v[76:77], v[76:77], v[82:83] op_sel_hi:[1,0]
	v_pk_mul_f32 v[72:73], v[72:73], v[64:65]
	v_pk_mul_f32 v[64:65], v[74:75], v[82:83] op_sel_hi:[1,0]
	v_pk_mul_f32 v[68:69], v[76:77], v[68:69]
	v_pk_mul_f32 v[74:75], v[64:65], v[66:67]
	v_ffbh_u32_e32 v66, v173
	v_pk_mul_f32 v[78:79], v[78:79], v[70:71]
	v_pk_mul_f32 v[70:71], v[70:71], v[80:81] op_sel_hi:[1,0]
	v_cvt_pk_bf16_f32 v64, v68, v69
	v_min_u32_e32 v68, 32, v66
	v_exp_f32_e32 v70, v70
	v_exp_f32_e32 v71, v71
	v_lshlrev_b64 v[66:67], v68, v[172:173]
	v_min_u32_e32 v66, 1, v66
	v_or_b32_e32 v66, v67, v66
	v_cvt_f32_u32_e32 v69, v66
	v_pk_add_f32 v[70:71], v[70:71], 1.0 op_sel_hi:[1,0]
	v_sub_u32_e32 v68, 32, v68
	v_rcp_f32_e32 v70, v70
	v_rcp_f32_e32 v71, v71
	v_ldexp_f32 v68, v69, v68
	v_pk_mul_f32 v[76:77], v[78:79], v[82:83] op_sel_hi:[1,0]
	v_mul_f32_e32 v68, 0x2b800000, v68
	v_pk_mul_f32 v[70:71], v[76:77], v[70:71]
	v_fmamk_f32 v68, v68, 0x3a800000, v193
	v_cvt_pk_bf16_f32 v65, v70, v71
	v_rsq_f32_e32 v70, v68
	v_mad_i64_i32 v[68:69], s[58:59], v170, s57, v[112:113]
	v_lshl_add_u64 v[68:69], v[68:69], 0, v[114:115]
	v_cvt_pk_bf16_f32 v66, v72, v73
	v_cvt_pk_bf16_f32 v67, v74, v75
	global_store_dwordx4 v[68:69], v[64:67], off
	v_pk_mul_f32 v[56:57], v[56:57], v[48:49]
	v_pk_mul_f32 v[60:61], v[60:61], v[52:53]
	v_mul_f32_e32 v64, 0xbfb8aa3b, v70
	v_pk_mul_f32 v[48:49], v[48:49], v[64:65] op_sel_hi:[1,0]
	v_pk_mul_f32 v[52:53], v[52:53], v[64:65] op_sel_hi:[1,0]
	v_pk_mul_f32 v[58:59], v[58:59], v[50:51]
	v_exp_f32_e32 v48, v48
	v_exp_f32_e32 v49, v49
	v_pk_mul_f32 v[50:51], v[50:51], v[64:65] op_sel_hi:[1,0]
	v_exp_f32_e32 v52, v52
	v_exp_f32_e32 v53, v53
	v_exp_f32_e32 v50, v50
	v_exp_f32_e32 v51, v51
	v_pk_add_f32 v[48:49], v[48:49], 1.0 op_sel_hi:[1,0]
	v_pk_add_f32 v[52:53], v[52:53], 1.0 op_sel_hi:[1,0]
	v_rcp_f32_e32 v48, v48
	v_rcp_f32_e32 v49, v49
	v_pk_add_f32 v[50:51], v[50:51], 1.0 op_sel_hi:[1,0]
	v_rcp_f32_e32 v52, v52
	v_rcp_f32_e32 v53, v53
	v_rcp_f32_e32 v50, v50
	v_rcp_f32_e32 v51, v51
	v_mul_f32_e32 v66, v70, v70
	v_pk_mul_f32 v[56:57], v[56:57], v[66:67] op_sel_hi:[1,0]
	v_pk_mul_f32 v[60:61], v[60:61], v[66:67] op_sel_hi:[1,0]
	v_pk_mul_f32 v[56:57], v[56:57], v[48:49]
	v_pk_mul_f32 v[48:49], v[58:59], v[66:67] op_sel_hi:[1,0]
	v_pk_mul_f32 v[52:53], v[60:61], v[52:53]
	v_pk_mul_f32 v[58:59], v[48:49], v[50:51]
	v_ffbh_u32_e32 v50, v169
	v_pk_mul_f32 v[62:63], v[62:63], v[54:55]
	v_pk_mul_f32 v[54:55], v[54:55], v[64:65] op_sel_hi:[1,0]
	v_cvt_pk_bf16_f32 v48, v52, v53
	v_min_u32_e32 v52, 32, v50
	v_exp_f32_e32 v54, v54
	v_exp_f32_e32 v55, v55
	v_lshlrev_b64 v[50:51], v52, v[168:169]
	v_min_u32_e32 v50, 1, v50
	v_or_b32_e32 v50, v51, v50
	v_cvt_f32_u32_e32 v53, v50
	v_pk_add_f32 v[54:55], v[54:55], 1.0 op_sel_hi:[1,0]
	v_sub_u32_e32 v52, 32, v52
	v_rcp_f32_e32 v54, v54
	v_rcp_f32_e32 v55, v55
	v_ldexp_f32 v52, v53, v52
	v_pk_mul_f32 v[60:61], v[62:63], v[66:67] op_sel_hi:[1,0]
	v_mul_f32_e32 v52, 0x2b800000, v52
	v_pk_mul_f32 v[54:55], v[60:61], v[54:55]
	v_fmamk_f32 v52, v52, 0x3a800000, v193
	v_cvt_pk_bf16_f32 v49, v54, v55
	v_rsq_f32_e32 v54, v52
	v_add_u32_e32 v141, 0x80, v182
	v_mad_i64_i32 v[52:53], s[58:59], v141, s57, v[112:113]
	v_lshl_add_u64 v[52:53], v[52:53], 0, v[114:115]
; __device__ __forceinline__ unsigned cvt_pk_bf16(float lo, float hi) { unsigned r; asm volatile("v_cvt_pk_bf16_f32 %0, %1, %2" : "=v"(r) : "v"(lo), "v"(hi)); return r; }
; __device__ __forceinline__ float ss_val(u64 v) { return (float)v * (1.0f / 1099511627776.0f); }
;     __device__ __forceinline__ void operator()(const f32x4 (&acc)[2][2][4][2], const Unit& u, const Unit& nxt, bool has_next, int wr, int wc, int fr, int fq) const {
;     ...
; #pragma unroll
;         for (int g = 0; g < 8; ++g) {
;             const int ai = g >> 2, m = g & 3;
;             const float rs = __builtin_amdgcn_rsqf(ss_val(cur[g]) * inv_k + eps), rsn = rs * -1.44269504089f, rs2 = rs * rs;
;             float h[8];
; #pragma unroll
;             for (int n = 0; n < 2; ++n)
; #pragma unroll
;                 for (int jp = 0; jp < 2; ++jp) {
;                     const f32x2v av = {acc[ai][0][m][n][2 * jp], acc[ai][0][m][n][2 * jp + 1]}, gv = {acc[ai][1][m][n][2 * jp], acc[ai][1][m][n][2 * jp + 1]};
;                     const f32x2v t = (av * gv) * rs2, y = gv * rsn;
;                     f32x2v ex; ex.x = __builtin_amdgcn_exp2f(y.x); ex.y = __builtin_amdgcn_exp2f(y.y);
;                     const f32x2v d = ex + 1.0f;
;                     f32x2v r; r.x = __builtin_amdgcn_rcpf(d.x); r.y = __builtin_amdgcn_rcpf(d.y);
;                     const f32x2v o = t * r;
;                     h[4 * n + 2 * jp] = o.x; h[4 * n + 2 * jp + 1] = o.y;
;                 }
;             u32x4 w; w.x = cvt_pk_bf16(h[0], h[1]); w.y = cvt_pk_bf16(h[2], h[3]); w.z = cvt_pk_bf16(h[4], h[5]); w.w = cvt_pk_bf16(h[6], h[7]);
;             *(u32x4*)(O + (size_t)(row0 + ai * HALF + m * 16) * ldc + col0) = w;
;         }
;         if (has_next) { u64 x = 0;
; #pragma unroll
;             for (int g = 0; g < 8; ++g) x |= warm[g];
;             asm volatile("" :: "v"((unsigned)x), "v"((unsigned)(x >> 32))); }
	v_cvt_pk_bf16_f32 v50, v56, v57
	v_cvt_pk_bf16_f32 v51, v58, v59
	global_store_dwordx4 v[52:53], v[48:51], off
	v_pk_mul_f32 v[40:41], v[40:41], v[32:33]
	v_pk_mul_f32 v[44:45], v[44:45], v[36:37]
	v_mul_f32_e32 v48, 0xbfb8aa3b, v54
	v_pk_mul_f32 v[32:33], v[32:33], v[48:49] op_sel_hi:[1,0]
	v_pk_mul_f32 v[36:37], v[36:37], v[48:49] op_sel_hi:[1,0]
	v_pk_mul_f32 v[42:43], v[42:43], v[34:35]
	v_exp_f32_e32 v32, v32
	v_exp_f32_e32 v33, v33
	v_pk_mul_f32 v[34:35], v[34:35], v[48:49] op_sel_hi:[1,0]
	v_exp_f32_e32 v36, v36
	v_exp_f32_e32 v37, v37
	v_exp_f32_e32 v34, v34
	v_exp_f32_e32 v35, v35
	v_pk_add_f32 v[32:33], v[32:33], 1.0 op_sel_hi:[1,0]
	v_pk_add_f32 v[36:37], v[36:37], 1.0 op_sel_hi:[1,0]
	v_rcp_f32_e32 v32, v32
	v_rcp_f32_e32 v33, v33
	v_pk_add_f32 v[34:35], v[34:35], 1.0 op_sel_hi:[1,0]
	v_rcp_f32_e32 v36, v36
	v_rcp_f32_e32 v37, v37
	v_rcp_f32_e32 v34, v34
	v_rcp_f32_e32 v35, v35
	v_mul_f32_e32 v50, v54, v54
	v_pk_mul_f32 v[40:41], v[40:41], v[50:51] op_sel_hi:[1,0]
	v_pk_mul_f32 v[44:45], v[44:45], v[50:51] op_sel_hi:[1,0]
	v_pk_mul_f32 v[40:41], v[40:41], v[32:33]
	v_pk_mul_f32 v[32:33], v[42:43], v[50:51] op_sel_hi:[1,0]
	v_pk_mul_f32 v[36:37], v[44:45], v[36:37]
	v_pk_mul_f32 v[42:43], v[32:33], v[34:35]
	v_ffbh_u32_e32 v34, v167
	v_pk_mul_f32 v[46:47], v[46:47], v[38:39]
	v_pk_mul_f32 v[38:39], v[38:39], v[48:49] op_sel_hi:[1,0]
	v_cvt_pk_bf16_f32 v32, v36, v37
	v_min_u32_e32 v36, 32, v34
	v_exp_f32_e32 v38, v38
	v_exp_f32_e32 v39, v39
	v_lshlrev_b64 v[34:35], v36, v[166:167]
	v_min_u32_e32 v34, 1, v34
	v_or_b32_e32 v34, v35, v34
	v_cvt_f32_u32_e32 v37, v34
	v_pk_add_f32 v[38:39], v[38:39], 1.0 op_sel_hi:[1,0]
	v_sub_u32_e32 v36, 32, v36
	v_rcp_f32_e32 v38, v38
	v_rcp_f32_e32 v39, v39
	v_ldexp_f32 v36, v37, v36
	v_pk_mul_f32 v[44:45], v[46:47], v[50:51] op_sel_hi:[1,0]
	v_mul_f32_e32 v36, 0x2b800000, v36
	v_pk_mul_f32 v[38:39], v[44:45], v[38:39]
	v_fmamk_f32 v36, v36, 0x3a800000, v193
	v_cvt_pk_bf16_f32 v33, v38, v39
	v_rsq_f32_e32 v38, v36
	v_mad_i64_i32 v[36:37], s[58:59], v164, s57, v[112:113]
	v_lshl_add_u64 v[36:37], v[36:37], 0, v[114:115]
	v_cvt_pk_bf16_f32 v34, v40, v41
	v_cvt_pk_bf16_f32 v35, v42, v43
	global_store_dwordx4 v[36:37], v[32:35], off
	v_pk_mul_f32 v[24:25], v[24:25], v[16:17]
	v_pk_mul_f32 v[28:29], v[28:29], v[20:21]
	v_mul_f32_e32 v32, 0xbfb8aa3b, v38
	v_pk_mul_f32 v[16:17], v[16:17], v[32:33] op_sel_hi:[1,0]
	v_pk_mul_f32 v[20:21], v[20:21], v[32:33] op_sel_hi:[1,0]
	v_pk_mul_f32 v[26:27], v[26:27], v[18:19]
	v_exp_f32_e32 v16, v16
	v_exp_f32_e32 v17, v17
	v_pk_mul_f32 v[18:19], v[18:19], v[32:33] op_sel_hi:[1,0]
	v_exp_f32_e32 v20, v20
	v_exp_f32_e32 v21, v21
	v_exp_f32_e32 v18, v18
	v_exp_f32_e32 v19, v19
	v_pk_add_f32 v[16:17], v[16:17], 1.0 op_sel_hi:[1,0]
	v_pk_add_f32 v[20:21], v[20:21], 1.0 op_sel_hi:[1,0]
	v_rcp_f32_e32 v16, v16
	v_rcp_f32_e32 v17, v17
	v_pk_add_f32 v[18:19], v[18:19], 1.0 op_sel_hi:[1,0]
	v_rcp_f32_e32 v20, v20
	v_rcp_f32_e32 v21, v21
	v_rcp_f32_e32 v18, v18
	v_rcp_f32_e32 v19, v19
	v_mul_f32_e32 v34, v38, v38
	v_pk_mul_f32 v[24:25], v[24:25], v[34:35] op_sel_hi:[1,0]
	v_pk_mul_f32 v[28:29], v[28:29], v[34:35] op_sel_hi:[1,0]
	v_pk_mul_f32 v[24:25], v[24:25], v[16:17]
	v_pk_mul_f32 v[16:17], v[26:27], v[34:35] op_sel_hi:[1,0]
	v_pk_mul_f32 v[20:21], v[28:29], v[20:21]
	v_pk_mul_f32 v[26:27], v[16:17], v[18:19]
	v_ffbh_u32_e32 v18, v163
	v_pk_mul_f32 v[30:31], v[30:31], v[22:23]
	v_pk_mul_f32 v[22:23], v[22:23], v[32:33] op_sel_hi:[1,0]
	v_cvt_pk_bf16_f32 v16, v20, v21
	v_min_u32_e32 v20, 32, v18
	v_exp_f32_e32 v22, v22
	v_exp_f32_e32 v23, v23
	v_lshlrev_b64 v[18:19], v20, v[162:163]
	v_min_u32_e32 v18, 1, v18
	v_or_b32_e32 v18, v19, v18
	v_cvt_f32_u32_e32 v21, v18
	v_pk_add_f32 v[22:23], v[22:23], 1.0 op_sel_hi:[1,0]
	v_sub_u32_e32 v20, 32, v20
	v_rcp_f32_e32 v22, v22
	v_rcp_f32_e32 v23, v23
	v_ldexp_f32 v20, v21, v20
	v_pk_mul_f32 v[28:29], v[30:31], v[34:35] op_sel_hi:[1,0]
	v_mul_f32_e32 v20, 0x2b800000, v20
	v_pk_mul_f32 v[22:23], v[28:29], v[22:23]
	v_fmamk_f32 v20, v20, 0x3a800000, v193
	v_cvt_pk_bf16_f32 v17, v22, v23
	v_rsq_f32_e32 v22, v20
	v_mad_i64_i32 v[20:21], s[58:59], v160, s57, v[112:113]
	v_lshl_add_u64 v[20:21], v[20:21], 0, v[114:115]
	v_cvt_pk_bf16_f32 v18, v24, v25
	v_cvt_pk_bf16_f32 v19, v26, v27
	global_store_dwordx4 v[20:21], v[16:19], off
	v_pk_mul_f32 v[12:13], v[12:13], v[4:5]
	v_pk_mul_f32 v[8:9], v[8:9], v[0:1]
	v_mul_f32_e32 v16, 0xbfb8aa3b, v22
	v_pk_mul_f32 v[4:5], v[4:5], v[16:17] op_sel_hi:[1,0]
	v_pk_mul_f32 v[0:1], v[0:1], v[16:17] op_sel_hi:[1,0]
	v_exp_f32_e32 v4, v4
	v_exp_f32_e32 v5, v5
	v_pk_mul_f32 v[10:11], v[10:11], v[2:3]
	v_exp_f32_e32 v0, v0
	v_exp_f32_e32 v1, v1
	v_pk_mul_f32 v[2:3], v[2:3], v[16:17] op_sel_hi:[1,0]
	v_pk_mul_f32 v[14:15], v[14:15], v[6:7]
	v_exp_f32_e32 v2, v2
	v_exp_f32_e32 v3, v3
	v_pk_mul_f32 v[6:7], v[6:7], v[16:17] op_sel_hi:[1,0]
	v_pk_add_f32 v[4:5], v[4:5], 1.0 op_sel_hi:[1,0]
	v_exp_f32_e32 v6, v6
	v_exp_f32_e32 v7, v7
	v_pk_add_f32 v[0:1], v[0:1], 1.0 op_sel_hi:[1,0]
	v_rcp_f32_e32 v4, v4
	v_rcp_f32_e32 v5, v5
	v_rcp_f32_e32 v0, v0
	v_rcp_f32_e32 v1, v1
	v_pk_add_f32 v[2:3], v[2:3], 1.0 op_sel_hi:[1,0]
	v_mul_f32_e32 v18, v22, v22
	v_rcp_f32_e32 v2, v2
	v_rcp_f32_e32 v3, v3
	v_pk_add_f32 v[6:7], v[6:7], 1.0 op_sel_hi:[1,0]
	v_pk_mul_f32 v[12:13], v[12:13], v[18:19] op_sel_hi:[1,0]
	v_rcp_f32_e32 v6, v6
	v_rcp_f32_e32 v7, v7
	v_pk_mul_f32 v[8:9], v[8:9], v[18:19] op_sel_hi:[1,0]
	v_pk_mul_f32 v[4:5], v[12:13], v[4:5]
	v_pk_mul_f32 v[8:9], v[8:9], v[0:1]
	v_pk_mul_f32 v[0:1], v[10:11], v[18:19] op_sel_hi:[1,0]
	v_pk_mul_f32 v[12:13], v[14:15], v[18:19] op_sel_hi:[1,0]
	v_pk_mul_f32 v[10:11], v[0:1], v[2:3]
	v_cvt_pk_bf16_f32 v0, v4, v5
	v_mad_i64_i32 v[4:5], s[58:59], v140, s57, v[112:113]
	v_lshl_add_u64 v[4:5], v[4:5], 0, v[114:115]
	s_and_b64 vcc, exec, s[4:5]
	s_mov_b64 s[4:5], -1
	v_pk_mul_f32 v[6:7], v[12:13], v[6:7]
	s_nop 0
	v_cvt_pk_bf16_f32 v1, v6, v7
	v_cvt_pk_bf16_f32 v2, v8, v9
	v_cvt_pk_bf16_f32 v3, v10, v11
	global_store_dwordx4 v[4:5], v[0:3], off
	s_cbranch_vccnz .LBB0_656
	s_nop 0
	v_or_b32_e32 v0, v159, v157
	v_or_b32_e32 v1, v158, v156
	v_or3_b32 v0, v0, v153, v155
	v_or3_b32 v1, v1, v152, v154
	v_or3_b32 v0, v0, v149, v151
	v_or3_b32 v1, v1, v148, v150
	s_andn2_b64 vcc, exec, s[6:7]
	v_or3_b32 v0, v0, v143, v147
	v_or3_b32 v1, v1, v142, v146
	s_cbranch_vccnz .LBB0_655
	s_barrier
	s_branch .LBB0_655

; #define PG8_STAGE(bufoff, gbase, voff) do { _Pragma("unroll") for (int _i = 0; _i < 2; ++_i) \
;         __builtin_amdgcn_global_load_lds((const unsigned*)((const char*)(gbase) + (voff)[_i]), (PG8_LAS unsigned*)(lds + (bufoff) + ldsw + _i * 8192), 16, 0, 0); } while (0)
; #define PG8_WAIT_V(n) asm volatile("s_waitcnt vmcnt(" #n ")" ::: "memory")
; #define PG8_BAR __builtin_amdgcn_s_barrier()
; template <class Epi, class Sched, bool ALIGN_EPI = false, bool SP2 = false>
; __device__ __forceinline__ void gemm_phase(PG8_LAS unsigned char* lds, const Gemm g, const Sched& S, const Epi& E) {
;     ...
;     const char* cA = (const char*)g.A + (size_t)cur.pm * tstep; const char* cB = (const char*)g.Bt + (size_t)cur.pn * tstep;
;     S.a_ready(cur);
;     if constexpr (SP2) {
;         PG8_STAGE(PG8_SB(0, 0), cB, voffB); PG8_STAGE(PG8_SB(0, 1), cB + hstep, voffB); PG8_STAGE(PG8_SA(0, 0), cA, voffA); PG8_STAGE(PG8_SA(0, 1), cA + hstep, voffA);
;         if (wr == 1) PG8_BAR;
;         PG8_WAIT_V(2); PG8_BAR;
;         PG8_STAGE(PG8_SB(1, 0), cB + kstep, voffB); PG8_STAGE(PG8_SA(1, 0), cA + kstep, voffA); PG8_STAGE(PG8_SB(1, 1), cB + hstep + kstep, voffB);
;         PG8_WAIT_V(6); PG8_BAR;
;     } else {
;         PG8_STAGE(PG8_SB(0, 0), cB, voffB); PG8_STAGE(PG8_SA(0, 0), cA, voffA); PG8_STAGE(PG8_SB(0, 1), cB + hstep, voffB); PG8_STAGE(PG8_SA(0, 1), cA + hstep, voffA);
;         if (wr == 1) PG8_BAR;
;         PG8_WAIT_V(4); PG8_BAR;
;         PG8_STAGE(PG8_SB(1, 0), cB + kstep, voffB); PG8_STAGE(PG8_SA(1, 0), cA + kstep, voffA); PG8_STAGE(PG8_SB(1, 1), cB + hstep + kstep, voffB);
;         PG8_WAIT_V(6); PG8_BAR;
;     }
.LBB0_802:
	s_add_u32 s64, s26, 0xc0000
	s_addc_u32 s65, s27, 0
	s_lshl_b32 s31, s31, 5
	s_mov_b64 s[66:67], 0x80
	s_and_b32 s57, s31, 0x60
	s_add_i32 m0, s20, 0x18000
	v_lshl_add_u64 v[6:7], v[6:7], 0, s[66:67]
	s_lshl_b32 s5, s56, 13
	s_lshl_b32 s60, s57, 7
	s_waitcnt vmcnt(2)
	s_barrier
	global_load_lds_dwordx4 v[6:7], off
	v_lshl_add_u64 v[4:5], v[4:5], 0, s[66:67]
	s_add_i32 m0, s20, 0x1a000
	s_add_i32 s31, s20, 0x8000
	s_add_i32 s37, s20, 0xa000
	global_load_lds_dwordx4 v[4:5], off
	v_lshl_add_u64 v[0:1], v[0:1], 0, s[66:67]
	s_mov_b32 m0, s31
	s_add_u32 s58, s82, 0x40080
	global_load_lds_dwordx4 v[0:1], off
	v_lshl_add_u64 v[0:1], v[2:3], 0, s[66:67]
	s_mov_b32 m0, s37
	s_addc_u32 s59, s83, 0
	global_load_lds_dwordx4 v[0:1], off
	s_add_i32 m0, s20, 0x1c000
	v_lshl_add_u64 v[0:1], s[58:59], 0, v[132:133]
	global_load_lds_dwordx4 v[0:1], off
	v_lshl_add_u64 v[0:1], s[58:59], 0, v[128:129]
	s_add_i32 m0, s20, 0x1e000
	v_lshlrev_b32_e32 v2, 2, v201
	global_load_lds_dwordx4 v[0:1], off
	v_and_b32_e32 v0, 15, v201
	v_lshlrev_b32_e32 v1, 1, v11
	v_lshl_or_b32 v145, s56, 6, v0
	v_lshl_or_b32 v0, v0, 6, v1
	v_and_b32_e32 v2, 32, v2
	v_bitop3_b32 v0, v0, s5, v2 bitop3:0xde
	v_lshlrev_b32_e32 v3, 6, v201
	s_movk_i32 s5, 0x3c0
	v_and_or_b32 v1, v3, s5, v1
	v_bitop3_b32 v188, s60, v1, v2 bitop3:0xf6
	v_lshlrev_b32_e32 v1, 8, v201
	v_and_b32_e32 v1, 0x38000, v1
	v_lshlrev_b32_e32 v2, 11, v12
	v_or3_b32 v1, v9, v1, v2
	v_add_u32_e32 v136, v1, v10
	v_lshlrev_b32_e32 v1, 4, v8
	s_waitcnt vmcnt(6)
	s_cmpk_lt_u32 s39, 0x100
	v_and_b32_e32 v1, 0x78000, v1
	s_sext_i32_i8 s86, s68
	s_cselect_b64 s[68:69], -1, 0
	v_or3_b32 v1, v9, v1, v2
	s_add_i32 s39, 0, 0x10000
	s_add_i32 s56, 0, 0x14000
	v_or_b32_e32 v189, s57, v11
	v_mov_b32_e32 v137, v133
	v_add_u32_e32 v138, v1, v10
	v_mov_b32_e32 v139, v133
	v_add_u32_e32 v190, s39, v188
	v_add_u32_e32 v191, s56, v188
	v_add_u32_e32 v192, 0, v0
	v_mov_b32_e32 v193, 0x358637bd
	s_movk_i32 s57, 0x1600
	v_lshl_add_u32 v232, s4, 8, v145
	v_ashrrev_i32_e32 v233, 31, v232
	v_lshl_add_u64 v[246:247], v[232:233], 3, s[64:65]
	global_load_dwordx2 v[232:233], v[246:247], off
	global_load_dwordx2 v[234:235], v[246:247], off offset:128
	global_load_dwordx2 v[236:237], v[246:247], off offset:256
	global_load_dwordx2 v[238:239], v[246:247], off offset:384
	global_load_dwordx2 v[240:241], v[246:247], off offset:1024
	global_load_dwordx2 v[242:243], v[246:247], off offset:1152
	global_load_dwordx2 v[244:245], v[246:247], off offset:1280
	global_load_dwordx2 v[246:247], v[246:247], off offset:1408
	s_barrier
	s_branch .LBB0_805

; #define PG8_STAGE(bufoff, gbase, voff) do { _Pragma("unroll") for (int _i = 0; _i < 2; ++_i) \
;         __builtin_amdgcn_global_load_lds((const unsigned*)((const char*)(gbase) + (voff)[_i]), (PG8_LAS unsigned*)(lds + (bufoff) + ldsw + _i * 8192), 16, 0, 0); } while (0)
; #define PG8_WAIT_V(n) asm volatile("s_waitcnt vmcnt(" #n ")" ::: "memory")
; #define PG8_BAR __builtin_amdgcn_s_barrier()
; template <class Epi, class Sched, bool ALIGN_EPI = false, bool SP2 = false>
; __device__ __forceinline__ void gemm_phase(PG8_LAS unsigned char* lds, const Gemm g, const Sched& S, const Epi& E) {
;     ...
;     const char* cA = (const char*)g.A + (size_t)cur.pm * tstep; const char* cB = (const char*)g.Bt + (size_t)cur.pn * tstep;
;     S.a_ready(cur);
;     if constexpr (SP2) {
;         PG8_STAGE(PG8_SB(0, 0), cB, voffB); PG8_STAGE(PG8_SB(0, 1), cB + hstep, voffB); PG8_STAGE(PG8_SA(0, 0), cA, voffA); PG8_STAGE(PG8_SA(0, 1), cA + hstep, voffA);
;         if (wr == 1) PG8_BAR;
;         PG8_WAIT_V(2); PG8_BAR;
;         PG8_STAGE(PG8_SB(1, 0), cB + kstep, voffB); PG8_STAGE(PG8_SA(1, 0), cA + kstep, voffA); PG8_STAGE(PG8_SB(1, 1), cB + hstep + kstep, voffB);
;         PG8_WAIT_V(6); PG8_BAR;
;     } else {
;         PG8_STAGE(PG8_SB(0, 0), cB, voffB); PG8_STAGE(PG8_SA(0, 0), cA, voffA); PG8_STAGE(PG8_SB(0, 1), cB + hstep, voffB); PG8_STAGE(PG8_SA(0, 1), cA + hstep, voffA);
;         if (wr == 1) PG8_BAR;
;         PG8_WAIT_V(4); PG8_BAR;
;         PG8_STAGE(PG8_SB(1, 0), cB + kstep, voffB); PG8_STAGE(PG8_SA(1, 0), cA + kstep, voffA); PG8_STAGE(PG8_SB(1, 1), cB + hstep + kstep, voffB);
;         PG8_WAIT_V(6); PG8_BAR;
;     }
.LBB0_1287:
	s_add_u32 s6, s26, 0x140000
	s_addc_u32 s7, s27, 0
	s_lshl_b32 s12, s12, 5
	s_and_b32 s17, s12, 0x60
	s_mov_b64 s[12:13], 0x80
	s_add_i32 m0, s28, 0x18000
	v_lshl_add_u64 v[6:7], v[6:7], 0, s[12:13]
	s_lshl_b32 s3, s16, 13
	s_lshl_b32 s42, s17, 7
	s_waitcnt vmcnt(2)
	s_barrier
	global_load_lds_dwordx4 v[6:7], off
	v_lshl_add_u64 v[4:5], v[4:5], 0, s[12:13]
	s_add_i32 m0, s28, 0x1a000
	s_add_i32 s39, s28, 0x8000
	s_add_i32 s58, s28, 0xa000
	global_load_lds_dwordx4 v[4:5], off
	v_lshl_add_u64 v[0:1], v[0:1], 0, s[12:13]
	s_mov_b32 m0, s39
	s_add_u32 s18, s50, 0x40080
	global_load_lds_dwordx4 v[0:1], off
	v_lshl_add_u64 v[0:1], v[2:3], 0, s[12:13]
	s_mov_b32 m0, s58
	s_addc_u32 s19, s51, 0
	global_load_lds_dwordx4 v[0:1], off
	s_add_i32 m0, s28, 0x1c000
	v_lshl_add_u64 v[0:1], s[18:19], 0, v[132:133]
	global_load_lds_dwordx4 v[0:1], off
	v_lshl_add_u64 v[0:1], s[18:19], 0, v[128:129]
	s_add_i32 m0, s28, 0x1e000
	v_lshlrev_b32_e32 v2, 2, v201
	global_load_lds_dwordx4 v[0:1], off
	v_and_b32_e32 v0, 15, v201
	v_lshlrev_b32_e32 v1, 1, v11
	v_lshl_or_b32 v186, s16, 6, v0
	v_lshl_or_b32 v0, v0, 6, v1
	v_and_b32_e32 v2, 32, v2
	v_bitop3_b32 v0, v0, s3, v2 bitop3:0xde
	v_lshlrev_b32_e32 v3, 6, v201
	s_movk_i32 s3, 0x3c0
	v_and_or_b32 v1, v3, s3, v1
	v_bitop3_b32 v187, s42, v1, v2 bitop3:0xf6
	v_lshlrev_b32_e32 v1, 8, v201
	v_and_b32_e32 v1, 0x38000, v1
	v_lshlrev_b32_e32 v2, 11, v12
	v_or3_b32 v1, v9, v1, v2
	v_add_u32_e32 v136, v1, v10
	v_lshlrev_b32_e32 v1, 4, v8
	s_waitcnt vmcnt(6)
	s_cmpk_lt_u32 s15, 0x100
	v_and_b32_e32 v1, 0x78000, v1
	s_sext_i32_i8 s62, s14
	s_cselect_b64 s[14:15], -1, 0
	v_or3_b32 v1, v9, v1, v2
	s_add_i32 s59, 0, 0x10000
	s_add_i32 s60, 0, 0x14000
	v_or_b32_e32 v188, s17, v11
	v_mov_b32_e32 v137, v133
	v_add_u32_e32 v138, v1, v10
	v_mov_b32_e32 v139, v133
	v_add_u32_e32 v189, s59, v187
	v_add_u32_e32 v190, s60, v187
	v_add_u32_e32 v191, 0, v0
	v_mov_b32_e32 v192, 0x358637bd
	s_movk_i32 s61, 0x1600
	v_lshl_add_u32 v232, s2, 8, v186
	v_ashrrev_i32_e32 v233, 31, v232
	v_lshl_add_u64 v[246:247], v[232:233], 3, s[6:7]
	global_load_dwordx2 v[232:233], v[246:247], off
	global_load_dwordx2 v[234:235], v[246:247], off offset:128
	global_load_dwordx2 v[236:237], v[246:247], off offset:256
	global_load_dwordx2 v[238:239], v[246:247], off offset:384
	global_load_dwordx2 v[240:241], v[246:247], off offset:1024
	global_load_dwordx2 v[242:243], v[246:247], off offset:1152
	global_load_dwordx2 v[244:245], v[246:247], off offset:1280
	global_load_dwordx2 v[246:247], v[246:247], off offset:1408
	s_barrier
	s_branch .LBB0_1290

; #define PG8_STAGE(bufoff, gbase, voff) do { _Pragma("unroll") for (int _i = 0; _i < 2; ++_i) \
;         __builtin_amdgcn_global_load_lds((const unsigned*)((const char*)(gbase) + (voff)[_i]), (PG8_LAS unsigned*)(lds + (bufoff) + ldsw + _i * 8192), 16, 0, 0); } while (0)
; #define PG8_LDA(dst, b, h) do { _Pragma("unroll") for (int m = 0; m < 4; ++m) _Pragma("unroll") for (int k = 0; k < 2; ++k) dst[m][k] = *(const PG8_LAS bf16x8*)(lds + PG8_SA(b, h) + aoff + m * 2048 + k * 1024); } while (0)
; #define PG8_LDB(dst, b, h) do { _Pragma("unroll") for (int n = 0; n < 2; ++n) _Pragma("unroll") for (int k = 0; k < 2; ++k) dst[n][k] = *(const PG8_LAS bf16x8*)(lds + PG8_SB(b, h) + boff + n * 2048 + k * 1024); } while (0)
; #define PG8_WAIT_V(n) asm volatile("s_waitcnt vmcnt(" #n ")" ::: "memory")
; #define PG8_WAIT_L(n) asm volatile("s_waitcnt lgkmcnt(" #n ")" ::: "memory")
; #define PG8_BAR __builtin_amdgcn_s_barrier()
; #define PG8_SCHED __builtin_amdgcn_sched_barrier(0)
; template <class Epi, class Sched, bool ALIGN_EPI = false, bool SP2 = false>
; __device__ __forceinline__ void gemm_phase(PG8_LAS unsigned char* lds, const Gemm g, const Sched& S, const Epi& E) {
;     ...
;         const bool has_next = S.next(ui + 1, nxt);
;         const char* nA = has_next ? (const char*)g.A + (size_t)nxt.pm * tstep : cA; const char* nB = has_next ? (const char*)g.Bt + (size_t)nxt.pn * tstep : cB;
;         for (int t = 0; t < nt; t += 2) {
;             const bool last = (t == nt - 2);
;             const char* a1 = cA + (size_t)(t + 1) * kstep;
;             const char* a2 = last ? nA : cA + (size_t)(t + 2) * kstep; const char* b2 = last ? nB : cB + (size_t)(t + 2) * kstep;
;             const char* a3 = a2 + kstep; const char* b3 = b2 + kstep;
;             if (last && has_next) S.a_ready(nxt);
;             if constexpr (SP2) {
;             PG8_LDB(B0, 0, 0); PG8_LDB(B1, 0, 1); PG8_SCHED; PG8_LDA(At, 0, 0); PG8_STAGE(PG8_SA(1, 1), a1 + hstep, voffA);
;             PG8_WAIT_V(8); PG8_WAIT_L(0); PG8_BAR; PG8_MMA(0, 0, At, B0); PG8_MMA(0, 1, At, B1); PG8_BAR; PG8_SCHED;
;     ...
; #pragma unroll
;         for (int a = 0; a < 2; ++a)
; #pragma unroll
;             for (int b = 0; b < 2; ++b)
; #pragma unroll
;                 for (int m = 0; m < 4; ++m)
; #pragma unroll
;                     for (int n = 0; n < 2; ++n) acc[a][b][m][n] = (f32x4){0.f, 0.f, 0.f, 0.f};
.LBB0_1292:
	s_ashr_i32 s17, s16, 31
	s_lshl_b64 s[42:43], s[16:17], 19
	s_add_u32 s42, s22, s42
	s_addc_u32 s43, s23, s43
	s_and_b64 s[44:45], s[46:47], exec
	s_cselect_b32 s3, s43, s49
	s_cselect_b32 s17, s42, s48
	s_ashr_i32 s19, s18, 31
	s_lshl_b64 s[44:45], s[18:19], 19
	s_add_u32 s44, s11, s44
	s_addc_u32 s45, s20, s45
	s_and_b64 s[56:57], s[46:47], exec
	s_cselect_b32 s19, s45, s51
	s_cselect_b32 s63, s44, s50
	s_add_u32 s48, s48, 0x40080
	s_addc_u32 s49, s49, 0
	s_add_u32 s64, s50, 0x100
	v_mov_b32_e32 v0, 0
	s_addc_u32 s65, s51, 0
	s_mov_b32 s66, -2
	v_mov_b32_e32 v1, v0
	v_mov_b32_e32 v2, v0
	v_mov_b32_e32 v3, v0
	v_mov_b32_e32 v4, v0
	v_mov_b32_e32 v5, v0
	v_mov_b32_e32 v6, v0
	v_mov_b32_e32 v7, v0
	v_mov_b32_e32 v16, v0
	v_mov_b32_e32 v17, v0
	v_mov_b32_e32 v18, v0
	v_mov_b32_e32 v19, v0
	v_mov_b32_e32 v20, v0
	v_mov_b32_e32 v21, v0
	v_mov_b32_e32 v22, v0
	v_mov_b32_e32 v23, v0
	v_mov_b32_e32 v32, v0
	v_mov_b32_e32 v33, v0
	v_mov_b32_e32 v34, v0
	v_mov_b32_e32 v35, v0
	v_mov_b32_e32 v36, v0
	v_mov_b32_e32 v37, v0
	v_mov_b32_e32 v38, v0
	v_mov_b32_e32 v39, v0
	v_mov_b32_e32 v48, v0
	v_mov_b32_e32 v49, v0
	v_mov_b32_e32 v50, v0
	v_mov_b32_e32 v51, v0
	v_mov_b32_e32 v52, v0
	v_mov_b32_e32 v53, v0
	v_mov_b32_e32 v54, v0
	v_mov_b32_e32 v55, v0
	v_mov_b32_e32 v8, v0
	v_mov_b32_e32 v9, v0
	v_mov_b32_e32 v10, v0
	v_mov_b32_e32 v11, v0
	v_mov_b32_e32 v12, v0
	v_mov_b32_e32 v13, v0
	v_mov_b32_e32 v14, v0
	v_mov_b32_e32 v15, v0
	v_mov_b32_e32 v24, v0
	v_mov_b32_e32 v25, v0
	v_mov_b32_e32 v26, v0
	v_mov_b32_e32 v27, v0
	v_mov_b32_e32 v28, v0
	v_mov_b32_e32 v29, v0
	v_mov_b32_e32 v30, v0
	v_mov_b32_e32 v31, v0
	v_mov_b32_e32 v40, v0
	v_mov_b32_e32 v41, v0
	v_mov_b32_e32 v42, v0
	v_mov_b32_e32 v43, v0
	v_mov_b32_e32 v44, v0
	v_mov_b32_e32 v45, v0
	v_mov_b32_e32 v46, v0
	v_mov_b32_e32 v47, v0
	v_mov_b32_e32 v56, v0
	v_mov_b32_e32 v57, v0
	v_mov_b32_e32 v58, v0
	v_mov_b32_e32 v59, v0
	v_mov_b32_e32 v60, v0
	v_mov_b32_e32 v61, v0
	v_mov_b32_e32 v62, v0
	v_mov_b32_e32 v63, v0
	v_mov_b32_e32 v64, v0
	v_mov_b32_e32 v65, v0
	v_mov_b32_e32 v66, v0
	v_mov_b32_e32 v67, v0
	v_mov_b32_e32 v68, v0
	v_mov_b32_e32 v69, v0
	v_mov_b32_e32 v70, v0
	v_mov_b32_e32 v71, v0
	v_mov_b32_e32 v80, v0
	v_mov_b32_e32 v81, v0
	v_mov_b32_e32 v82, v0
	v_mov_b32_e32 v83, v0
	v_mov_b32_e32 v84, v0
	v_mov_b32_e32 v85, v0
	v_mov_b32_e32 v86, v0
	v_mov_b32_e32 v87, v0
	v_mov_b32_e32 v96, v0
	v_mov_b32_e32 v97, v0
	v_mov_b32_e32 v98, v0
	v_mov_b32_e32 v99, v0
	v_mov_b32_e32 v100, v0
	v_mov_b32_e32 v101, v0
	v_mov_b32_e32 v102, v0
	v_mov_b32_e32 v103, v0
	v_mov_b32_e32 v112, v0
	v_mov_b32_e32 v113, v0
	v_mov_b32_e32 v114, v0
	v_mov_b32_e32 v115, v0
	v_mov_b32_e32 v116, v0
	v_mov_b32_e32 v117, v0
	v_mov_b32_e32 v118, v0
	v_mov_b32_e32 v119, v0
	v_mov_b32_e32 v72, v0
	v_mov_b32_e32 v73, v0
	v_mov_b32_e32 v74, v0
	v_mov_b32_e32 v75, v0
	v_mov_b32_e32 v76, v0
	v_mov_b32_e32 v77, v0
	v_mov_b32_e32 v78, v0
	v_mov_b32_e32 v79, v0
	v_mov_b32_e32 v88, v0
	v_mov_b32_e32 v89, v0
	v_mov_b32_e32 v90, v0
	v_mov_b32_e32 v91, v0
	v_mov_b32_e32 v92, v0
	v_mov_b32_e32 v93, v0
	v_mov_b32_e32 v94, v0
	v_mov_b32_e32 v95, v0
	v_mov_b32_e32 v104, v0
	v_mov_b32_e32 v105, v0
	v_mov_b32_e32 v106, v0
	v_mov_b32_e32 v107, v0
	v_mov_b32_e32 v108, v0
	v_mov_b32_e32 v109, v0
	v_mov_b32_e32 v110, v0
	v_mov_b32_e32 v111, v0
	v_mov_b32_e32 v120, v0
	v_mov_b32_e32 v121, v0
	v_mov_b32_e32 v122, v0
	v_mov_b32_e32 v123, v0
	v_mov_b32_e32 v124, v0
	v_mov_b32_e32 v125, v0
	v_mov_b32_e32 v126, v0
	v_mov_b32_e32 v127, v0
	ds_read_b128 v[140:143], v189
	ds_read_b128 v[144:147], v189 offset:1024
	ds_read_b128 v[148:151], v189 offset:2048
	ds_read_b128 v[152:155], v189 offset:3072
	ds_read_b128 v[156:159], v190
	ds_read_b128 v[160:163], v190 offset:1024
	ds_read_b128 v[164:167], v190 offset:2048
	ds_read_b128 v[168:171], v190 offset:3072
	s_add_u32 s50, s48, 0xfffc0080
	s_addc_u32 s51, s49, -1
	s_cmp_eq_u32 s66, 12
	s_cselect_b32 s57, s3, s51
	s_cselect_b32 s56, s17, s50
	s_cselect_b32 s51, s19, s65
	s_cselect_b32 s50, s63, s64
	v_lshl_add_u64 v[184:185], s[48:49], 0, v[136:137]
	s_add_i32 m0, s28, 0xc000
	ds_read_b128 v[172:175], v191
	ds_read_b128 v[176:179], v191 offset:1024
	ds_read_b128 v[180:183], v191 offset:2048
	ds_read_b128 v[194:197], v191 offset:3072
	ds_read_b128 v[202:205], v191 offset:4096
	ds_read_b128 v[206:209], v191 offset:5120
	ds_read_b128 v[210:213], v191 offset:6144
	ds_read_b128 v[214:217], v191 offset:7168
	global_load_lds_dwordx4 v[184:185], off
	v_lshl_add_u64 v[184:185], s[48:49], 0, v[138:139]
	s_add_i32 m0, s28, 0xe000
	s_nop 0
	global_load_lds_dwordx4 v[184:185], off
	s_waitcnt vmcnt(24)
	s_waitcnt lgkmcnt(0)
	s_branch .Lpeel_join_1293
.LBB0_1293:
	ds_read_b128 v[140:143], v189
	ds_read_b128 v[144:147], v189 offset:1024
	ds_read_b128 v[148:151], v189 offset:2048
	ds_read_b128 v[152:155], v189 offset:3072
	ds_read_b128 v[156:159], v190
	ds_read_b128 v[160:163], v190 offset:1024
	ds_read_b128 v[164:167], v190 offset:2048
	ds_read_b128 v[168:171], v190 offset:3072
	s_add_u32 s50, s48, 0xfffc0080
	s_addc_u32 s51, s49, -1
	s_cmp_eq_u32 s66, 12
	s_cselect_b32 s57, s3, s51
	s_cselect_b32 s56, s17, s50
	s_cselect_b32 s51, s19, s65
	s_cselect_b32 s50, s63, s64
	v_lshl_add_u64 v[184:185], s[48:49], 0, v[136:137]
	s_add_i32 m0, s28, 0xc000
	ds_read_b128 v[172:175], v191
	ds_read_b128 v[176:179], v191 offset:1024
	ds_read_b128 v[180:183], v191 offset:2048
	ds_read_b128 v[194:197], v191 offset:3072
	ds_read_b128 v[202:205], v191 offset:4096
	ds_read_b128 v[206:209], v191 offset:5120
	ds_read_b128 v[210:213], v191 offset:6144
	ds_read_b128 v[214:217], v191 offset:7168
	global_load_lds_dwordx4 v[184:185], off
	v_lshl_add_u64 v[184:185], s[48:49], 0, v[138:139]
	s_add_i32 m0, s28, 0xe000
	s_nop 0
	global_load_lds_dwordx4 v[184:185], off
	s_waitcnt vmcnt(8)
	s_waitcnt lgkmcnt(0)
; #define PG8_STAGE(bufoff, gbase, voff) do { _Pragma("unroll") for (int _i = 0; _i < 2; ++_i) \
;         __builtin_amdgcn_global_load_lds((const unsigned*)((const char*)(gbase) + (voff)[_i]), (PG8_LAS unsigned*)(lds + (bufoff) + ldsw + _i * 8192), 16, 0, 0); } while (0)
; #define PG8_LDA(dst, b, h) do { _Pragma("unroll") for (int m = 0; m < 4; ++m) _Pragma("unroll") for (int k = 0; k < 2; ++k) dst[m][k] = *(const PG8_LAS bf16x8*)(lds + PG8_SA(b, h) + aoff + m * 2048 + k * 1024); } while (0)
; #define PG8_MMA(ai, bj, At, Bt) do { __builtin_amdgcn_s_setprio(1); _Pragma("unroll") for (int m = 0; m < 4; ++m) _Pragma("unroll") for (int n = 0; n < 2; ++n) _Pragma("unroll") for (int k = 0; k < 2; ++k) \
;         acc[ai][bj][m][n] = __builtin_amdgcn_mfma_f32_16x16x32_bf16(Bt[n][k], At[m][k], acc[ai][bj][m][n], 0, 0, 0); __builtin_amdgcn_s_setprio(0); } while (0)
; #define PG8_WAIT_V(n) asm volatile("s_waitcnt vmcnt(" #n ")" ::: "memory")
; #define PG8_WAIT_L(n) asm volatile("s_waitcnt lgkmcnt(" #n ")" ::: "memory")
; #define PG8_BAR __builtin_amdgcn_s_barrier()
; #define PG8_SCHED __builtin_amdgcn_sched_barrier(0)
; template <class Epi, class Sched, bool ALIGN_EPI = false, bool SP2 = false>
; __device__ __forceinline__ void gemm_phase(PG8_LAS unsigned char* lds, const Gemm g, const Sched& S, const Epi& E) {
;     ...
;             PG8_WAIT_V(8); PG8_WAIT_L(0); PG8_BAR; PG8_MMA(0, 0, At, B0); PG8_MMA(0, 1, At, B1); PG8_BAR; PG8_SCHED;
;             PG8_LDA(At, 0, 1); PG8_STAGE(PG8_SB(0, 0), b2, voffB); PG8_STAGE(PG8_SB(0, 1), b2 + hstep, voffB); PG8_STAGE(PG8_SA(0, 0), a2, voffA);
;             PG8_WAIT_V(8); PG8_WAIT_L(0); PG8_BAR; PG8_MMA(1, 0, At, B0); PG8_MMA(1, 1, At, B1); PG8_BAR; PG8_SCHED;
.Lpeel_join_1293:
	s_barrier
	s_setprio 1
	s_waitcnt lgkmcnt(0)
	v_mfma_f32_16x16x32_bf16 v[124:127], v[140:143], v[172:175], v[124:127]
	v_mfma_f32_16x16x32_bf16 v[120:123], v[148:151], v[172:175], v[120:123]
	v_mfma_f32_16x16x32_bf16 v[108:111], v[140:143], v[180:183], v[108:111]
	v_mfma_f32_16x16x32_bf16 v[104:107], v[148:151], v[180:183], v[104:107]
	v_mfma_f32_16x16x32_bf16 v[92:95], v[140:143], v[202:205], v[92:95]
	v_mfma_f32_16x16x32_bf16 v[88:91], v[148:151], v[202:205], v[88:91]
	v_mfma_f32_16x16x32_bf16 v[76:79], v[140:143], v[210:213], v[76:79]
	v_mfma_f32_16x16x32_bf16 v[72:75], v[148:151], v[210:213], v[72:75]
	v_mfma_f32_16x16x32_bf16 v[124:127], v[144:147], v[176:179], v[124:127]
	v_mfma_f32_16x16x32_bf16 v[120:123], v[152:155], v[176:179], v[120:123]
	v_mfma_f32_16x16x32_bf16 v[108:111], v[144:147], v[194:197], v[108:111]
	v_mfma_f32_16x16x32_bf16 v[104:107], v[152:155], v[194:197], v[104:107]
	v_mfma_f32_16x16x32_bf16 v[92:95], v[144:147], v[206:209], v[92:95]
	v_mfma_f32_16x16x32_bf16 v[88:91], v[152:155], v[206:209], v[88:91]
	v_mfma_f32_16x16x32_bf16 v[76:79], v[144:147], v[214:217], v[76:79]
	v_mfma_f32_16x16x32_bf16 v[72:75], v[152:155], v[214:217], v[72:75]
	s_setprio 0
	s_setprio 1
	v_mfma_f32_16x16x32_bf16 v[116:119], v[156:159], v[172:175], v[116:119]
	v_mfma_f32_16x16x32_bf16 v[112:115], v[164:167], v[172:175], v[112:115]
	v_mfma_f32_16x16x32_bf16 v[100:103], v[156:159], v[180:183], v[100:103]
	v_mfma_f32_16x16x32_bf16 v[96:99], v[164:167], v[180:183], v[96:99]
	v_mfma_f32_16x16x32_bf16 v[84:87], v[156:159], v[202:205], v[84:87]
	v_mfma_f32_16x16x32_bf16 v[80:83], v[164:167], v[202:205], v[80:83]
	v_mfma_f32_16x16x32_bf16 v[68:71], v[156:159], v[210:213], v[68:71]
	v_mfma_f32_16x16x32_bf16 v[64:67], v[164:167], v[210:213], v[64:67]
	v_mfma_f32_16x16x32_bf16 v[116:119], v[160:163], v[176:179], v[116:119]
	v_mfma_f32_16x16x32_bf16 v[112:115], v[168:171], v[176:179], v[112:115]
	v_mfma_f32_16x16x32_bf16 v[100:103], v[160:163], v[194:197], v[100:103]
	v_mfma_f32_16x16x32_bf16 v[96:99], v[168:171], v[194:197], v[96:99]
	v_mfma_f32_16x16x32_bf16 v[84:87], v[160:163], v[206:209], v[84:87]
	v_mfma_f32_16x16x32_bf16 v[80:83], v[168:171], v[206:209], v[80:83]
	v_mfma_f32_16x16x32_bf16 v[68:71], v[160:163], v[214:217], v[68:71]
	v_mfma_f32_16x16x32_bf16 v[64:67], v[168:171], v[214:217], v[64:67]
	s_setprio 0
	s_barrier
	s_add_i32 s67, s59, s21
	v_lshl_add_u64 v[184:185], s[50:51], 0, v[132:133]
	s_mov_b32 m0, s67
	ds_read_b128 v[172:175], v191 offset:16384
	ds_read_b128 v[176:179], v191 offset:17408
	ds_read_b128 v[180:183], v191 offset:18432
	ds_read_b128 v[194:197], v191 offset:19456
	ds_read_b128 v[202:205], v191 offset:20480
	ds_read_b128 v[206:209], v191 offset:21504
	ds_read_b128 v[210:213], v191 offset:22528
	ds_read_b128 v[214:217], v191 offset:23552
	global_load_lds_dwordx4 v[184:185], off
	s_add_i32 m0, s67, 0x2000
	s_add_u32 s68, s50, 0x40000
	v_lshl_add_u64 v[198:199], s[50:51], 0, v[128:129]
	s_addc_u32 s69, s51, 0
	s_add_i32 s67, s60, s21
	global_load_lds_dwordx4 v[198:199], off
	v_lshl_add_u64 v[218:219], s[68:69], 0, v[132:133]
	s_mov_b32 m0, s67
	v_lshl_add_u64 v[220:221], s[56:57], 0, v[130:131]
	global_load_lds_dwordx4 v[218:219], off
	v_lshl_add_u64 v[218:219], s[68:69], 0, v[128:129]
	s_add_i32 m0, s67, 0x2000
	s_nop 0
	global_load_lds_dwordx4 v[218:219], off
	v_lshl_add_u64 v[218:219], s[56:57], 0, v[134:135]
	s_mov_b32 m0, s28
	s_nop 0
	global_load_lds_dwordx4 v[218:219], off
	s_mov_b32 m0, s29
	s_nop 0
	global_load_lds_dwordx4 v[220:221], off
	s_waitcnt vmcnt(8)
	s_waitcnt lgkmcnt(0)
	s_barrier
	s_setprio 1
	s_waitcnt lgkmcnt(0)
	v_mfma_f32_16x16x32_bf16 v[60:63], v[140:143], v[172:175], v[60:63]
	v_mfma_f32_16x16x32_bf16 v[56:59], v[148:151], v[172:175], v[56:59]
	v_mfma_f32_16x16x32_bf16 v[44:47], v[140:143], v[180:183], v[44:47]
	v_mfma_f32_16x16x32_bf16 v[40:43], v[148:151], v[180:183], v[40:43]
	v_mfma_f32_16x16x32_bf16 v[28:31], v[140:143], v[202:205], v[28:31]
	v_mfma_f32_16x16x32_bf16 v[24:27], v[148:151], v[202:205], v[24:27]
	v_mfma_f32_16x16x32_bf16 v[12:15], v[140:143], v[210:213], v[12:15]
	v_mfma_f32_16x16x32_bf16 v[8:11], v[148:151], v[210:213], v[8:11]
	v_mfma_f32_16x16x32_bf16 v[60:63], v[144:147], v[176:179], v[60:63]
	v_mfma_f32_16x16x32_bf16 v[56:59], v[152:155], v[176:179], v[56:59]
	v_mfma_f32_16x16x32_bf16 v[44:47], v[144:147], v[194:197], v[44:47]
	v_mfma_f32_16x16x32_bf16 v[40:43], v[152:155], v[194:197], v[40:43]
	v_mfma_f32_16x16x32_bf16 v[28:31], v[144:147], v[206:209], v[28:31]
	v_mfma_f32_16x16x32_bf16 v[24:27], v[152:155], v[206:209], v[24:27]
	v_mfma_f32_16x16x32_bf16 v[12:15], v[144:147], v[214:217], v[12:15]
	v_mfma_f32_16x16x32_bf16 v[8:11], v[152:155], v[214:217], v[8:11]
	s_setprio 0
	s_setprio 1
	v_mfma_f32_16x16x32_bf16 v[52:55], v[156:159], v[172:175], v[52:55]
	v_mfma_f32_16x16x32_bf16 v[48:51], v[164:167], v[172:175], v[48:51]
	v_mfma_f32_16x16x32_bf16 v[36:39], v[156:159], v[180:183], v[36:39]
	v_mfma_f32_16x16x32_bf16 v[32:35], v[164:167], v[180:183], v[32:35]
	v_mfma_f32_16x16x32_bf16 v[20:23], v[156:159], v[202:205], v[20:23]
	v_mfma_f32_16x16x32_bf16 v[16:19], v[164:167], v[202:205], v[16:19]
	v_mfma_f32_16x16x32_bf16 v[4:7], v[156:159], v[210:213], v[4:7]
	v_mfma_f32_16x16x32_bf16 v[0:3], v[164:167], v[210:213], v[0:3]
	v_mfma_f32_16x16x32_bf16 v[52:55], v[160:163], v[176:179], v[52:55]
	v_mfma_f32_16x16x32_bf16 v[48:51], v[168:171], v[176:179], v[48:51]
	v_mfma_f32_16x16x32_bf16 v[36:39], v[160:163], v[194:197], v[36:39]
	v_mfma_f32_16x16x32_bf16 v[32:35], v[168:171], v[194:197], v[32:35]
	v_mfma_f32_16x16x32_bf16 v[20:23], v[160:163], v[206:209], v[20:23]
	v_mfma_f32_16x16x32_bf16 v[16:19], v[168:171], v[206:209], v[16:19]
	v_mfma_f32_16x16x32_bf16 v[4:7], v[160:163], v[214:217], v[4:7]
	v_mfma_f32_16x16x32_bf16 v[0:3], v[168:171], v[214:217], v[0:3]
	s_setprio 0
	s_barrier
; #define PG8_STAGE(bufoff, gbase, voff) do { _Pragma("unroll") for (int _i = 0; _i < 2; ++_i) \
;         __builtin_amdgcn_global_load_lds((const unsigned*)((const char*)(gbase) + (voff)[_i]), (PG8_LAS unsigned*)(lds + (bufoff) + ldsw + _i * 8192), 16, 0, 0); } while (0)
; #define PG8_LDA(dst, b, h) do { _Pragma("unroll") for (int m = 0; m < 4; ++m) _Pragma("unroll") for (int k = 0; k < 2; ++k) dst[m][k] = *(const PG8_LAS bf16x8*)(lds + PG8_SA(b, h) + aoff + m * 2048 + k * 1024); } while (0)
; #define PG8_LDB(dst, b, h) do { _Pragma("unroll") for (int n = 0; n < 2; ++n) _Pragma("unroll") for (int k = 0; k < 2; ++k) dst[n][k] = *(const PG8_LAS bf16x8*)(lds + PG8_SB(b, h) + boff + n * 2048 + k * 1024); } while (0)
; #define PG8_MMA(ai, bj, At, Bt) do { __builtin_amdgcn_s_setprio(1); _Pragma("unroll") for (int m = 0; m < 4; ++m) _Pragma("unroll") for (int n = 0; n < 2; ++n) _Pragma("unroll") for (int k = 0; k < 2; ++k) \
;         acc[ai][bj][m][n] = __builtin_amdgcn_mfma_f32_16x16x32_bf16(Bt[n][k], At[m][k], acc[ai][bj][m][n], 0, 0, 0); __builtin_amdgcn_s_setprio(0); } while (0)
; #define PG8_WAIT_V(n) asm volatile("s_waitcnt vmcnt(" #n ")" ::: "memory")
; #define PG8_WAIT_L(n) asm volatile("s_waitcnt lgkmcnt(" #n ")" ::: "memory")
; #define PG8_BAR __builtin_amdgcn_s_barrier()
; #define PG8_SCHED __builtin_amdgcn_sched_barrier(0)
; template <class Epi, class Sched, bool ALIGN_EPI = false, bool SP2 = false>
; __device__ __forceinline__ void gemm_phase(PG8_LAS unsigned char* lds, const Gemm g, const Sched& S, const Epi& E) {
;     ...
;             PG8_WAIT_V(8); PG8_WAIT_L(0); PG8_BAR; PG8_MMA(1, 0, At, B0); PG8_MMA(1, 1, At, B1); PG8_BAR; PG8_SCHED;
;             PG8_LDB(B0, 1, 0); PG8_LDB(B1, 1, 1); PG8_SCHED; PG8_LDA(At, 1, 0); PG8_STAGE(PG8_SA(0, 1), a2 + hstep, voffA);
;             PG8_WAIT_V(8); PG8_WAIT_L(0); PG8_BAR; PG8_MMA(0, 0, At, B0); PG8_MMA(0, 1, At, B1); PG8_BAR; PG8_SCHED;
;             PG8_LDA(At, 1, 1); PG8_STAGE(PG8_SB(1, 0), b3, voffB); PG8_STAGE(PG8_SB(1, 1), b3 + hstep, voffB); PG8_STAGE(PG8_SA(1, 0), a3, voffA);
	s_add_i32 s67, 0, 0x18000
	s_add_i32 s68, 0, 0x1c000
	v_add_u32_e32 v152, s67, v187
	v_add_u32_e32 v168, s68, v187
	ds_read_b128 v[140:143], v152
	ds_read_b128 v[144:147], v152 offset:1024
	ds_read_b128 v[148:151], v152 offset:2048
	ds_read_b128 v[152:155], v152 offset:3072
	ds_read_b128 v[156:159], v168
	ds_read_b128 v[160:163], v168 offset:1024
	ds_read_b128 v[164:167], v168 offset:2048
	ds_read_b128 v[168:171], v168 offset:3072
	s_add_u32 s56, s56, 0x40000
	s_addc_u32 s57, s57, 0
	s_mov_b32 m0, s30
	v_lshl_add_u64 v[222:223], s[56:57], 0, v[134:135]
	ds_read_b128 v[172:175], v191 offset:32768
	ds_read_b128 v[176:179], v191 offset:33792
	ds_read_b128 v[180:183], v191 offset:34816
	ds_read_b128 v[194:197], v191 offset:35840
	ds_read_b128 v[202:205], v191 offset:36864
	ds_read_b128 v[206:209], v191 offset:37888
	ds_read_b128 v[210:213], v191 offset:38912
	ds_read_b128 v[214:217], v191 offset:39936
	global_load_lds_dwordx4 v[222:223], off
	v_lshl_add_u64 v[222:223], s[56:57], 0, v[130:131]
	s_mov_b32 m0, s31
	s_nop 0
	global_load_lds_dwordx4 v[222:223], off
	s_waitcnt vmcnt(8)
	s_waitcnt lgkmcnt(0)
	s_barrier
	s_setprio 1
	s_waitcnt lgkmcnt(0)
	v_mfma_f32_16x16x32_bf16 v[124:127], v[140:143], v[172:175], v[124:127]
	v_mfma_f32_16x16x32_bf16 v[120:123], v[148:151], v[172:175], v[120:123]
	v_mfma_f32_16x16x32_bf16 v[108:111], v[140:143], v[180:183], v[108:111]
	v_mfma_f32_16x16x32_bf16 v[104:107], v[148:151], v[180:183], v[104:107]
	v_mfma_f32_16x16x32_bf16 v[92:95], v[140:143], v[202:205], v[92:95]
	v_mfma_f32_16x16x32_bf16 v[88:91], v[148:151], v[202:205], v[88:91]
	v_mfma_f32_16x16x32_bf16 v[76:79], v[140:143], v[210:213], v[76:79]
	v_mfma_f32_16x16x32_bf16 v[72:75], v[148:151], v[210:213], v[72:75]
	v_mfma_f32_16x16x32_bf16 v[124:127], v[144:147], v[176:179], v[124:127]
	v_mfma_f32_16x16x32_bf16 v[120:123], v[152:155], v[176:179], v[120:123]
	v_mfma_f32_16x16x32_bf16 v[108:111], v[144:147], v[194:197], v[108:111]
	v_mfma_f32_16x16x32_bf16 v[104:107], v[152:155], v[194:197], v[104:107]
	v_mfma_f32_16x16x32_bf16 v[92:95], v[144:147], v[206:209], v[92:95]
	v_mfma_f32_16x16x32_bf16 v[88:91], v[152:155], v[206:209], v[88:91]
	v_mfma_f32_16x16x32_bf16 v[76:79], v[144:147], v[214:217], v[76:79]
	v_mfma_f32_16x16x32_bf16 v[72:75], v[152:155], v[214:217], v[72:75]
	s_setprio 0
	s_setprio 1
	v_mfma_f32_16x16x32_bf16 v[116:119], v[156:159], v[172:175], v[116:119]
	v_mfma_f32_16x16x32_bf16 v[112:115], v[164:167], v[172:175], v[112:115]
	v_mfma_f32_16x16x32_bf16 v[100:103], v[156:159], v[180:183], v[100:103]
	v_mfma_f32_16x16x32_bf16 v[96:99], v[164:167], v[180:183], v[96:99]
	v_mfma_f32_16x16x32_bf16 v[84:87], v[156:159], v[202:205], v[84:87]
	v_mfma_f32_16x16x32_bf16 v[80:83], v[164:167], v[202:205], v[80:83]
	v_mfma_f32_16x16x32_bf16 v[68:71], v[156:159], v[210:213], v[68:71]
	v_mfma_f32_16x16x32_bf16 v[64:67], v[164:167], v[210:213], v[64:67]
	v_mfma_f32_16x16x32_bf16 v[116:119], v[160:163], v[176:179], v[116:119]
	v_mfma_f32_16x16x32_bf16 v[112:115], v[168:171], v[176:179], v[112:115]
	v_mfma_f32_16x16x32_bf16 v[100:103], v[160:163], v[194:197], v[100:103]
	v_mfma_f32_16x16x32_bf16 v[96:99], v[168:171], v[194:197], v[96:99]
	v_mfma_f32_16x16x32_bf16 v[84:87], v[160:163], v[206:209], v[84:87]
	v_mfma_f32_16x16x32_bf16 v[80:83], v[168:171], v[206:209], v[80:83]
	v_mfma_f32_16x16x32_bf16 v[68:71], v[160:163], v[214:217], v[68:71]
	v_mfma_f32_16x16x32_bf16 v[64:67], v[168:171], v[214:217], v[64:67]
	s_setprio 0
	s_barrier
	s_add_i32 s56, s67, s21
	v_lshl_add_u64 v[184:185], v[184:185], 0, s[12:13]
	s_mov_b32 m0, s56
	ds_read_b128 v[172:175], v191 offset:49152
	ds_read_b128 v[176:179], v191 offset:50176
	ds_read_b128 v[180:183], v191 offset:51200
	ds_read_b128 v[194:197], v191 offset:52224
	ds_read_b128 v[202:205], v191 offset:53248
	ds_read_b128 v[206:209], v191 offset:54272
	ds_read_b128 v[210:213], v191 offset:55296
	ds_read_b128 v[214:217], v191 offset:56320
	global_load_lds_dwordx4 v[184:185], off
	s_add_i32 m0, s56, 0x2000
	s_add_u32 s50, s50, 0x40080
	v_lshl_add_u64 v[184:185], v[198:199], 0, s[12:13]
	s_addc_u32 s51, s51, 0
	s_add_i32 s56, s68, s21
	global_load_lds_dwordx4 v[184:185], off
	v_lshl_add_u64 v[184:185], s[50:51], 0, v[132:133]
	s_mov_b32 m0, s56
	s_nop 0
	global_load_lds_dwordx4 v[184:185], off
	v_lshl_add_u64 v[184:185], s[50:51], 0, v[128:129]
	s_add_i32 m0, s56, 0x2000
	s_nop 0
	global_load_lds_dwordx4 v[184:185], off
	v_lshl_add_u64 v[184:185], v[218:219], 0, s[12:13]
	s_mov_b32 m0, s39
	s_nop 0
	global_load_lds_dwordx4 v[184:185], off
	v_lshl_add_u64 v[184:185], v[220:221], 0, s[12:13]
	s_mov_b32 m0, s58
	s_nop 0
	global_load_lds_dwordx4 v[184:185], off
	s_waitcnt vmcnt(8)
	s_waitcnt lgkmcnt(0)
	s_barrier
; #define PG8_BAR __builtin_amdgcn_s_barrier()
;     __device__ __forceinline__ void operator()(const f32x4 (&acc)[2][2][4][2], const Unit& u, const Unit& nxt, bool has_next, int wr, int wc, int fr, int fq) const {
;         const int row0 = u.pm * BM + wr * 64 + fr, col0 = u.pn * HALF + wc * 32 + 8 * fq;
;         u64 cur[8], warm[8];
; #pragma unroll
;         for (int g = 0; g < 8; ++g) cur[g] = rowss[row0 + (g >> 2) * HALF + (g & 3) * 16];
;         if (has_next) {
; #pragma unroll
;             for (int g = 0; g < 8; ++g) warm[g] = rowss[nxt.pm * BM + wr * 64 + fr + (g >> 2) * HALF + (g & 3) * 16];
; template <class Epi, class Sched, bool ALIGN_EPI = false, bool SP2 = false>
; __device__ __forceinline__ void gemm_phase(PG8_LAS unsigned char* lds, const Gemm g, const Sched& S, const Epi& E) {
;     ...
;             PG8_WAIT_V(8); PG8_WAIT_L(0); PG8_BAR; PG8_MMA(1, 0, At, B0); PG8_MMA(1, 1, At, B1); PG8_BAR; PG8_SCHED;
;             } else {
;             PG8_LDB(B0, 0, 0); PG8_SCHED; PG8_LDA(At, 0, 0); PG8_STAGE(PG8_SA(1, 1), a1 + hstep, voffA);
;             PG8_WAIT_L(8); PG8_BAR; PG8_WAIT_L(0); PG8_MMA(0, 0, At, B0); PG8_BAR; PG8_SCHED;
;             PG8_LDB(B1, 0, 1); PG8_STAGE(PG8_SB(0, 0), b2, voffB);
;             PG8_BAR; PG8_WAIT_L(0); PG8_MMA(0, 1, At, B1); PG8_BAR;
;             PG8_LDA(At, 0, 1); PG8_STAGE(PG8_SA(0, 0), a2, voffA);
;             PG8_BAR; PG8_WAIT_L(0); PG8_MMA(1, 0, At, B0); PG8_BAR; PG8_SCHED;
;             PG8_STAGE(PG8_SB(0, 1), b2 + hstep, voffB);
;             PG8_WAIT_V(6); PG8_BAR; PG8_MMA(1, 1, At, B1); PG8_BAR;
;             PG8_LDB(B0, 1, 0); PG8_SCHED; PG8_LDA(At, 1, 0); PG8_STAGE(PG8_SA(0, 1), a2 + hstep, voffA);
;             PG8_WAIT_L(8); PG8_BAR; PG8_WAIT_L(0); PG8_MMA(0, 0, At, B0); PG8_BAR; PG8_SCHED;
;             PG8_LDB(B1, 1, 1); PG8_STAGE(PG8_SB(1, 0), b3, voffB);
;             PG8_BAR; PG8_WAIT_L(0); PG8_MMA(0, 1, At, B1); PG8_BAR;
;             PG8_LDA(At, 1, 1); PG8_STAGE(PG8_SA(1, 0), a3, voffA);
;             PG8_BAR; PG8_WAIT_L(0); PG8_MMA(1, 0, At, B0); PG8_BAR; PG8_SCHED;
;             PG8_STAGE(PG8_SB(1, 1), b3 + hstep, voffB);
;             PG8_WAIT_V(6); PG8_BAR; PG8_MMA(1, 1, At, B1); PG8_BAR;
;             }
;         }
;         if constexpr (ALIGN_EPI) { if (wr == 0) PG8_BAR; }
;         if constexpr (!Epi::AFTER_DRAIN) { E(acc, cur, nxt, has_next, wr, wc, fr, fq); S.done(cur); }
	s_setprio 1
	s_waitcnt lgkmcnt(0)
	v_mfma_f32_16x16x32_bf16 v[60:63], v[140:143], v[172:175], v[60:63]
	v_mfma_f32_16x16x32_bf16 v[56:59], v[148:151], v[172:175], v[56:59]
	v_mfma_f32_16x16x32_bf16 v[44:47], v[140:143], v[180:183], v[44:47]
	v_mfma_f32_16x16x32_bf16 v[40:43], v[148:151], v[180:183], v[40:43]
	v_mfma_f32_16x16x32_bf16 v[28:31], v[140:143], v[202:205], v[28:31]
	v_mfma_f32_16x16x32_bf16 v[24:27], v[148:151], v[202:205], v[24:27]
	v_mfma_f32_16x16x32_bf16 v[12:15], v[140:143], v[210:213], v[12:15]
	v_mfma_f32_16x16x32_bf16 v[8:11], v[148:151], v[210:213], v[8:11]
	v_mfma_f32_16x16x32_bf16 v[60:63], v[144:147], v[176:179], v[60:63]
	v_mfma_f32_16x16x32_bf16 v[56:59], v[152:155], v[176:179], v[56:59]
	v_mfma_f32_16x16x32_bf16 v[44:47], v[144:147], v[194:197], v[44:47]
	v_mfma_f32_16x16x32_bf16 v[40:43], v[152:155], v[194:197], v[40:43]
	v_mfma_f32_16x16x32_bf16 v[28:31], v[144:147], v[206:209], v[28:31]
	v_mfma_f32_16x16x32_bf16 v[24:27], v[152:155], v[206:209], v[24:27]
	v_mfma_f32_16x16x32_bf16 v[12:15], v[144:147], v[214:217], v[12:15]
	v_mfma_f32_16x16x32_bf16 v[8:11], v[152:155], v[214:217], v[8:11]
	s_setprio 0
	s_setprio 1
	v_mfma_f32_16x16x32_bf16 v[52:55], v[156:159], v[172:175], v[52:55]
	v_mfma_f32_16x16x32_bf16 v[48:51], v[164:167], v[172:175], v[48:51]
	v_mfma_f32_16x16x32_bf16 v[36:39], v[156:159], v[180:183], v[36:39]
	v_mfma_f32_16x16x32_bf16 v[32:35], v[164:167], v[180:183], v[32:35]
	v_mfma_f32_16x16x32_bf16 v[20:23], v[156:159], v[202:205], v[20:23]
	v_mfma_f32_16x16x32_bf16 v[16:19], v[164:167], v[202:205], v[16:19]
	v_mfma_f32_16x16x32_bf16 v[4:7], v[156:159], v[210:213], v[4:7]
	v_mfma_f32_16x16x32_bf16 v[0:3], v[164:167], v[210:213], v[0:3]
	v_mfma_f32_16x16x32_bf16 v[52:55], v[160:163], v[176:179], v[52:55]
	v_mfma_f32_16x16x32_bf16 v[48:51], v[168:171], v[176:179], v[48:51]
	v_mfma_f32_16x16x32_bf16 v[36:39], v[160:163], v[194:197], v[36:39]
	v_mfma_f32_16x16x32_bf16 v[32:35], v[168:171], v[194:197], v[32:35]
	v_mfma_f32_16x16x32_bf16 v[20:23], v[160:163], v[206:209], v[20:23]
	v_mfma_f32_16x16x32_bf16 v[16:19], v[168:171], v[206:209], v[16:19]
	v_mfma_f32_16x16x32_bf16 v[4:7], v[160:163], v[214:217], v[4:7]
	v_mfma_f32_16x16x32_bf16 v[0:3], v[168:171], v[214:217], v[0:3]
	s_setprio 0
	s_barrier
	s_add_i32 s66, s66, 2
	s_add_u32 s48, s48, 0x100
	s_addc_u32 s49, s49, 0
	s_add_u32 s64, s64, 0x100
	s_addc_u32 s65, s65, 0
	s_cmp_gt_u32 s66, 13
	s_cbranch_scc0 .LBB0_1293
	s_and_b64 vcc, exec, s[14:15]
	s_cbranch_vccz .LBB0_1296
	s_barrier
.LBB0_1296:
	v_lshl_add_u32 v180, s2, 8, v186
	v_ashrrev_i32_e32 v181, 31, v180
	v_or_b32_e32 v176, 16, v180
	v_or_b32_e32 v172, 32, v180
	v_lshl_add_u64 v[140:141], v[180:181], 3, s[6:7]
	v_ashrrev_i32_e32 v177, 31, v176
	v_ashrrev_i32_e32 v173, 31, v172
	v_or_b32_e32 v168, 48, v180
	v_lshl_add_u64 v[142:143], v[176:177], 3, s[6:7]
	v_lshl_add_u64 v[144:145], v[172:173], 3, s[6:7]
	v_ashrrev_i32_e32 v169, 31, v168
	v_mov_b32_e32 v184, v232
	v_mov_b32_e32 v185, v233
	v_mov_b32_e32 v182, v234
	v_mov_b32_e32 v183, v235
	v_mov_b32_e32 v178, v236
	v_mov_b32_e32 v179, v237
	v_mov_b32_e32 v170, v240
	v_mov_b32_e32 v171, v241
	v_add_u32_e32 v162, 0x90, v180
	v_add_u32_e32 v158, 0xa0, v180
	v_add_u32_e32 v140, 0xb0, v180
	v_lshl_add_u64 v[146:147], v[168:169], 3, s[6:7]
	v_ashrrev_i32_e32 v163, 31, v162
	v_ashrrev_i32_e32 v159, 31, v158
	v_ashrrev_i32_e32 v141, 31, v140
	v_lshl_add_u64 v[142:143], v[162:163], 3, s[6:7]
	v_lshl_add_u64 v[144:145], v[158:159], 3, s[6:7]
	v_lshl_add_u64 v[148:149], v[140:141], 3, s[6:7]
	v_mov_b32_e32 v174, v238
	v_mov_b32_e32 v175, v239
	v_mov_b32_e32 v166, v242
	v_mov_b32_e32 v167, v243
	v_mov_b32_e32 v164, v244
	v_mov_b32_e32 v165, v245
	v_mov_b32_e32 v160, v246
	v_mov_b32_e32 v161, v247
	v_cndmask_b32_e64 v141, 0, 1, s[46:47]
	v_cmp_ne_u32_e64 s[2:3], 1, v141
	s_andn2_b64 vcc, exec, s[46:47]
	s_cbranch_vccnz .LBB0_1298
	v_lshl_add_u32 v142, s16, 8, v186
	v_ashrrev_i32_e32 v143, 31, v142
	v_lshl_add_u64 v[154:155], v[142:143], 3, s[6:7]
	global_load_dwordx2 v[232:233], v[154:155], off
	global_load_dwordx2 v[234:235], v[154:155], off offset:128
	global_load_dwordx2 v[236:237], v[154:155], off offset:256
	global_load_dwordx2 v[238:239], v[154:155], off offset:384
	global_load_dwordx2 v[240:241], v[154:155], off offset:1024
	global_load_dwordx2 v[242:243], v[154:155], off offset:1152
	global_load_dwordx2 v[244:245], v[154:155], off offset:1280
	s_nop 0
	global_load_dwordx2 v[246:247], v[154:155], off offset:1408
; __device__ __forceinline__ unsigned cvt_pk_bf16(float lo, float hi) { unsigned r; asm volatile("v_cvt_pk_bf16_f32 %0, %1, %2" : "=v"(r) : "v"(lo), "v"(hi)); return r; }
; __device__ __forceinline__ float ss_val(u64 v) { return (float)v * (1.0f / 1099511627776.0f); }
;     __device__ __forceinline__ void operator()(const f32x4 (&acc)[2][2][4][2], const Unit& u, const Unit& nxt, bool has_next, int wr, int wc, int fr, int fq) const {
;     ...
; #pragma unroll
;         for (int g = 0; g < 8; ++g) {
;             const int ai = g >> 2, m = g & 3;
;             const float rs = __builtin_amdgcn_rsqf(ss_val(cur[g]) * inv_k + eps), rsn = rs * -1.44269504089f, rs2 = rs * rs;
;             float h[8];
; #pragma unroll
;             for (int n = 0; n < 2; ++n)
; #pragma unroll
;                 for (int jp = 0; jp < 2; ++jp) {
;                     const f32x2v av = {acc[ai][0][m][n][2 * jp], acc[ai][0][m][n][2 * jp + 1]}, gv = {acc[ai][1][m][n][2 * jp], acc[ai][1][m][n][2 * jp + 1]};
;                     const f32x2v t = (av * gv) * rs2, y = gv * rsn;
;                     f32x2v ex; ex.x = __builtin_amdgcn_exp2f(y.x); ex.y = __builtin_amdgcn_exp2f(y.y);
;                     const f32x2v d = ex + 1.0f;
;                     f32x2v r; r.x = __builtin_amdgcn_rcpf(d.x); r.y = __builtin_amdgcn_rcpf(d.y);
;                     const f32x2v o = t * r;
;                     h[4 * n + 2 * jp] = o.x; h[4 * n + 2 * jp + 1] = o.y;
;                 }
;             u32x4 w; w.x = cvt_pk_bf16(h[0], h[1]); w.y = cvt_pk_bf16(h[2], h[3]); w.z = cvt_pk_bf16(h[4], h[5]); w.w = cvt_pk_bf16(h[6], h[7]);
;             *(u32x4*)(O + (size_t)(row0 + ai * HALF + m * 16) * ldc + col0) = w;
.LBB0_1298:
	v_ffbh_u32_e32 v141, v185
	v_min_u32_e32 v159, 32, v141
	v_lshlrev_b64 v[184:185], v159, v[184:185]
	v_min_u32_e32 v141, 1, v184
	v_or_b32_e32 v141, v185, v141
	v_cvt_f32_u32_e32 v163, v141
	v_sub_u32_e32 v159, 32, v159
	v_pk_mul_f32 v[124:125], v[124:125], v[116:117]
	v_pk_mul_f32 v[120:121], v[120:121], v[112:113]
	v_ldexp_f32 v159, v163, v159
	v_mul_f32_e32 v159, 0x2b800000, v159
	v_fmamk_f32 v159, v159, 0x3a800000, v192
	v_rsq_f32_e32 v159, v159
	v_pk_mul_f32 v[126:127], v[126:127], v[118:119]
	v_pk_mul_f32 v[122:123], v[122:123], v[114:115]
	v_lshl_or_b32 v184, s62, 7, v188
	v_mul_f32_e32 v194, 0xbfb8aa3b, v159
	v_pk_mul_f32 v[116:117], v[116:117], v[194:195] op_sel_hi:[1,0]
	v_pk_mul_f32 v[112:113], v[112:113], v[194:195] op_sel_hi:[1,0]
	v_exp_f32_e32 v116, v116
	v_exp_f32_e32 v117, v117
	v_pk_mul_f32 v[118:119], v[118:119], v[194:195] op_sel_hi:[1,0]
	v_exp_f32_e32 v112, v112
	v_exp_f32_e32 v113, v113
	v_pk_mul_f32 v[114:115], v[114:115], v[194:195] op_sel_hi:[1,0]
	v_exp_f32_e32 v118, v118
	v_exp_f32_e32 v119, v119
	v_exp_f32_e32 v114, v114
	v_exp_f32_e32 v115, v115
	v_pk_add_f32 v[116:117], v[116:117], 1.0 op_sel_hi:[1,0]
	v_pk_add_f32 v[112:113], v[112:113], 1.0 op_sel_hi:[1,0]
	v_rcp_f32_e32 v116, v116
	v_rcp_f32_e32 v117, v117
	v_pk_add_f32 v[118:119], v[118:119], 1.0 op_sel_hi:[1,0]
	v_rcp_f32_e32 v112, v112
	v_rcp_f32_e32 v113, v113
	v_pk_add_f32 v[114:115], v[114:115], 1.0 op_sel_hi:[1,0]
	v_rcp_f32_e32 v118, v118
	v_rcp_f32_e32 v119, v119
	v_rcp_f32_e32 v114, v114
	v_rcp_f32_e32 v115, v115
	v_mul_f32_e32 v196, v159, v159
	v_pk_mul_f32 v[124:125], v[124:125], v[196:197] op_sel_hi:[1,0]
	v_pk_mul_f32 v[120:121], v[120:121], v[196:197] op_sel_hi:[1,0]
	v_pk_mul_f32 v[116:117], v[124:125], v[116:117]
	v_pk_mul_f32 v[124:125], v[126:127], v[196:197] op_sel_hi:[1,0]
	v_pk_mul_f32 v[112:113], v[120:121], v[112:113]
	v_pk_mul_f32 v[120:121], v[122:123], v[196:197] op_sel_hi:[1,0]
	v_pk_mul_f32 v[118:119], v[124:125], v[118:119]
	v_pk_mul_f32 v[114:115], v[120:121], v[114:115]
	v_cvt_pk_bf16_f32 v116, v116, v117
	v_cvt_pk_bf16_f32 v117, v118, v119
	v_cvt_pk_bf16_f32 v118, v112, v113
	v_ashrrev_i32_e32 v185, 31, v184
	v_cvt_pk_bf16_f32 v119, v114, v115
	v_ffbh_u32_e32 v114, v183
	v_min_u32_e32 v122, 32, v114
	v_lshlrev_b64 v[114:115], v122, v[182:183]
	v_min_u32_e32 v114, 1, v114
	v_or_b32_e32 v114, v115, v114
	v_cvt_f32_u32_e32 v114, v114
	v_sub_u32_e32 v115, 32, v122
	v_mov_b64_e32 v[112:113], s[24:25]
	v_mad_i64_i32 v[120:121], s[46:47], v180, s61, v[112:113]
	v_ldexp_f32 v114, v114, v115
	v_mul_f32_e32 v114, 0x2b800000, v114
	v_fmamk_f32 v114, v114, 0x3a800000, v192
	v_rsq_f32_e32 v122, v114
	v_lshlrev_b64 v[114:115], 1, v[184:185]
	v_lshl_add_u64 v[120:121], v[120:121], 0, v[114:115]
	global_store_dwordx4 v[120:121], v[116:119], off
	v_pk_mul_f32 v[104:105], v[104:105], v[96:97]
	v_pk_mul_f32 v[108:109], v[108:109], v[100:101]
	v_mul_f32_e32 v116, 0xbfb8aa3b, v122
	v_pk_mul_f32 v[96:97], v[96:97], v[116:117] op_sel_hi:[1,0]
	v_pk_mul_f32 v[100:101], v[100:101], v[116:117] op_sel_hi:[1,0]
	v_pk_mul_f32 v[106:107], v[106:107], v[98:99]
	v_exp_f32_e32 v96, v96
	v_exp_f32_e32 v97, v97
	v_pk_mul_f32 v[98:99], v[98:99], v[116:117] op_sel_hi:[1,0]
	v_exp_f32_e32 v100, v100
	v_exp_f32_e32 v101, v101
	v_exp_f32_e32 v98, v98
	v_exp_f32_e32 v99, v99
	v_pk_add_f32 v[96:97], v[96:97], 1.0 op_sel_hi:[1,0]
	v_pk_add_f32 v[100:101], v[100:101], 1.0 op_sel_hi:[1,0]
	v_rcp_f32_e32 v96, v96
	v_rcp_f32_e32 v97, v97
	v_pk_add_f32 v[98:99], v[98:99], 1.0 op_sel_hi:[1,0]
	v_rcp_f32_e32 v100, v100
	v_rcp_f32_e32 v101, v101
	v_rcp_f32_e32 v98, v98
	v_rcp_f32_e32 v99, v99
	v_mul_f32_e32 v118, v122, v122
	v_pk_mul_f32 v[104:105], v[104:105], v[118:119] op_sel_hi:[1,0]
	v_pk_mul_f32 v[108:109], v[108:109], v[118:119] op_sel_hi:[1,0]
	v_pk_mul_f32 v[104:105], v[104:105], v[96:97]
	v_pk_mul_f32 v[96:97], v[106:107], v[118:119] op_sel_hi:[1,0]
	v_pk_mul_f32 v[100:101], v[108:109], v[100:101]
	v_pk_mul_f32 v[106:107], v[96:97], v[98:99]
	v_ffbh_u32_e32 v98, v179
	v_pk_mul_f32 v[110:111], v[110:111], v[102:103]
	v_pk_mul_f32 v[102:103], v[102:103], v[116:117] op_sel_hi:[1,0]
	v_cvt_pk_bf16_f32 v96, v100, v101
	v_min_u32_e32 v100, 32, v98
	v_exp_f32_e32 v102, v102
	v_exp_f32_e32 v103, v103
	v_lshlrev_b64 v[98:99], v100, v[178:179]
	v_min_u32_e32 v98, 1, v98
	v_or_b32_e32 v98, v99, v98
	v_cvt_f32_u32_e32 v101, v98
	v_pk_add_f32 v[102:103], v[102:103], 1.0 op_sel_hi:[1,0]
	v_sub_u32_e32 v100, 32, v100
	v_rcp_f32_e32 v102, v102
	v_rcp_f32_e32 v103, v103
	v_ldexp_f32 v100, v101, v100
	v_pk_mul_f32 v[108:109], v[110:111], v[118:119] op_sel_hi:[1,0]
	v_mul_f32_e32 v100, 0x2b800000, v100
	v_pk_mul_f32 v[102:103], v[108:109], v[102:103]
	v_fmamk_f32 v100, v100, 0x3a800000, v192
	v_cvt_pk_bf16_f32 v97, v102, v103
	v_rsq_f32_e32 v102, v100
	v_mad_i64_i32 v[100:101], s[46:47], v176, s61, v[112:113]
	v_lshl_add_u64 v[100:101], v[100:101], 0, v[114:115]
	v_cvt_pk_bf16_f32 v98, v104, v105
	v_cvt_pk_bf16_f32 v99, v106, v107
	global_store_dwordx4 v[100:101], v[96:99], off
	v_pk_mul_f32 v[88:89], v[88:89], v[80:81]
	v_pk_mul_f32 v[92:93], v[92:93], v[84:85]
	v_mul_f32_e32 v96, 0xbfb8aa3b, v102
	v_pk_mul_f32 v[80:81], v[80:81], v[96:97] op_sel_hi:[1,0]
	v_pk_mul_f32 v[84:85], v[84:85], v[96:97] op_sel_hi:[1,0]
	v_pk_mul_f32 v[90:91], v[90:91], v[82:83]
	v_exp_f32_e32 v80, v80
	v_exp_f32_e32 v81, v81
	v_pk_mul_f32 v[82:83], v[82:83], v[96:97] op_sel_hi:[1,0]
	v_exp_f32_e32 v84, v84
	v_exp_f32_e32 v85, v85
	v_exp_f32_e32 v82, v82
	v_exp_f32_e32 v83, v83
	v_pk_add_f32 v[80:81], v[80:81], 1.0 op_sel_hi:[1,0]
	v_pk_add_f32 v[84:85], v[84:85], 1.0 op_sel_hi:[1,0]
; __device__ __forceinline__ unsigned cvt_pk_bf16(float lo, float hi) { unsigned r; asm volatile("v_cvt_pk_bf16_f32 %0, %1, %2" : "=v"(r) : "v"(lo), "v"(hi)); return r; }
; __device__ __forceinline__ float ss_val(u64 v) { return (float)v * (1.0f / 1099511627776.0f); }
;     __device__ __forceinline__ void operator()(const f32x4 (&acc)[2][2][4][2], const Unit& u, const Unit& nxt, bool has_next, int wr, int wc, int fr, int fq) const {
;     ...
; #pragma unroll
;         for (int g = 0; g < 8; ++g) {
;             const int ai = g >> 2, m = g & 3;
;             const float rs = __builtin_amdgcn_rsqf(ss_val(cur[g]) * inv_k + eps), rsn = rs * -1.44269504089f, rs2 = rs * rs;
;             float h[8];
; #pragma unroll
;             for (int n = 0; n < 2; ++n)
; #pragma unroll
;                 for (int jp = 0; jp < 2; ++jp) {
;                     const f32x2v av = {acc[ai][0][m][n][2 * jp], acc[ai][0][m][n][2 * jp + 1]}, gv = {acc[ai][1][m][n][2 * jp], acc[ai][1][m][n][2 * jp + 1]};
;                     const f32x2v t = (av * gv) * rs2, y = gv * rsn;
;                     f32x2v ex; ex.x = __builtin_amdgcn_exp2f(y.x); ex.y = __builtin_amdgcn_exp2f(y.y);
;                     const f32x2v d = ex + 1.0f;
;                     f32x2v r; r.x = __builtin_amdgcn_rcpf(d.x); r.y = __builtin_amdgcn_rcpf(d.y);
;                     const f32x2v o = t * r;
;                     h[4 * n + 2 * jp] = o.x; h[4 * n + 2 * jp + 1] = o.y;
;                 }
;             u32x4 w; w.x = cvt_pk_bf16(h[0], h[1]); w.y = cvt_pk_bf16(h[2], h[3]); w.z = cvt_pk_bf16(h[4], h[5]); w.w = cvt_pk_bf16(h[6], h[7]);
;             *(u32x4*)(O + (size_t)(row0 + ai * HALF + m * 16) * ldc + col0) = w;
	v_rcp_f32_e32 v80, v80
	v_rcp_f32_e32 v81, v81
	v_pk_add_f32 v[82:83], v[82:83], 1.0 op_sel_hi:[1,0]
	v_rcp_f32_e32 v84, v84
	v_rcp_f32_e32 v85, v85
	v_rcp_f32_e32 v82, v82
	v_rcp_f32_e32 v83, v83
	v_mul_f32_e32 v98, v102, v102
	v_pk_mul_f32 v[88:89], v[88:89], v[98:99] op_sel_hi:[1,0]
	v_pk_mul_f32 v[92:93], v[92:93], v[98:99] op_sel_hi:[1,0]
	v_pk_mul_f32 v[88:89], v[88:89], v[80:81]
	v_pk_mul_f32 v[80:81], v[90:91], v[98:99] op_sel_hi:[1,0]
	v_pk_mul_f32 v[84:85], v[92:93], v[84:85]
	v_pk_mul_f32 v[90:91], v[80:81], v[82:83]
	v_ffbh_u32_e32 v82, v175
	v_pk_mul_f32 v[94:95], v[94:95], v[86:87]
	v_pk_mul_f32 v[86:87], v[86:87], v[96:97] op_sel_hi:[1,0]
	v_cvt_pk_bf16_f32 v80, v84, v85
	v_min_u32_e32 v84, 32, v82
	v_exp_f32_e32 v86, v86
	v_exp_f32_e32 v87, v87
	v_lshlrev_b64 v[82:83], v84, v[174:175]
	v_min_u32_e32 v82, 1, v82
	v_or_b32_e32 v82, v83, v82
	v_cvt_f32_u32_e32 v85, v82
	v_pk_add_f32 v[86:87], v[86:87], 1.0 op_sel_hi:[1,0]
	v_sub_u32_e32 v84, 32, v84
	v_rcp_f32_e32 v86, v86
	v_rcp_f32_e32 v87, v87
	v_ldexp_f32 v84, v85, v84
	v_pk_mul_f32 v[92:93], v[94:95], v[98:99] op_sel_hi:[1,0]
	v_mul_f32_e32 v84, 0x2b800000, v84
	v_pk_mul_f32 v[86:87], v[92:93], v[86:87]
	v_fmamk_f32 v84, v84, 0x3a800000, v192
	v_cvt_pk_bf16_f32 v81, v86, v87
	v_rsq_f32_e32 v86, v84
	v_mad_i64_i32 v[84:85], s[46:47], v172, s61, v[112:113]
	v_lshl_add_u64 v[84:85], v[84:85], 0, v[114:115]
	v_cvt_pk_bf16_f32 v82, v88, v89
	v_cvt_pk_bf16_f32 v83, v90, v91
	global_store_dwordx4 v[84:85], v[80:83], off
	v_pk_mul_f32 v[72:73], v[72:73], v[64:65]
	v_pk_mul_f32 v[76:77], v[76:77], v[68:69]
	v_mul_f32_e32 v80, 0xbfb8aa3b, v86
	v_pk_mul_f32 v[64:65], v[64:65], v[80:81] op_sel_hi:[1,0]
	v_pk_mul_f32 v[68:69], v[68:69], v[80:81] op_sel_hi:[1,0]
	v_pk_mul_f32 v[74:75], v[74:75], v[66:67]
	v_exp_f32_e32 v64, v64
	v_exp_f32_e32 v65, v65
	v_pk_mul_f32 v[66:67], v[66:67], v[80:81] op_sel_hi:[1,0]
	v_exp_f32_e32 v68, v68
	v_exp_f32_e32 v69, v69
	v_exp_f32_e32 v66, v66
	v_exp_f32_e32 v67, v67
	v_pk_add_f32 v[64:65], v[64:65], 1.0 op_sel_hi:[1,0]
	v_pk_add_f32 v[68:69], v[68:69], 1.0 op_sel_hi:[1,0]
	v_rcp_f32_e32 v64, v64
	v_rcp_f32_e32 v65, v65
	v_pk_add_f32 v[66:67], v[66:67], 1.0 op_sel_hi:[1,0]
	v_rcp_f32_e32 v68, v68
	v_rcp_f32_e32 v69, v69
	v_rcp_f32_e32 v66, v66
	v_rcp_f32_e32 v67, v67
	v_mul_f32_e32 v82, v86, v86
	v_pk_mul_f32 v[72:73], v[72:73], v[82:83] op_sel_hi:[1,0]
	v_pk_mul_f32 v[76:77], v[76:77], v[82:83] op_sel_hi:[1,0]
	v_pk_mul_f32 v[72:73], v[72:73], v[64:65]
	v_pk_mul_f32 v[64:65], v[74:75], v[82:83] op_sel_hi:[1,0]
	v_pk_mul_f32 v[68:69], v[76:77], v[68:69]
	v_pk_mul_f32 v[74:75], v[64:65], v[66:67]
	v_ffbh_u32_e32 v66, v171
	v_pk_mul_f32 v[78:79], v[78:79], v[70:71]
	v_pk_mul_f32 v[70:71], v[70:71], v[80:81] op_sel_hi:[1,0]
	v_cvt_pk_bf16_f32 v64, v68, v69
	v_min_u32_e32 v68, 32, v66
	v_exp_f32_e32 v70, v70
	v_exp_f32_e32 v71, v71
	v_lshlrev_b64 v[66:67], v68, v[170:171]
	v_min_u32_e32 v66, 1, v66
	v_or_b32_e32 v66, v67, v66
	v_cvt_f32_u32_e32 v69, v66
	v_pk_add_f32 v[70:71], v[70:71], 1.0 op_sel_hi:[1,0]
	v_sub_u32_e32 v68, 32, v68
	v_rcp_f32_e32 v70, v70
	v_rcp_f32_e32 v71, v71
	v_ldexp_f32 v68, v69, v68
	v_pk_mul_f32 v[76:77], v[78:79], v[82:83] op_sel_hi:[1,0]
	v_mul_f32_e32 v68, 0x2b800000, v68
	v_pk_mul_f32 v[70:71], v[76:77], v[70:71]
	v_fmamk_f32 v68, v68, 0x3a800000, v192
	v_cvt_pk_bf16_f32 v65, v70, v71
	v_rsq_f32_e32 v70, v68
	v_mad_i64_i32 v[68:69], s[46:47], v168, s61, v[112:113]
	v_lshl_add_u64 v[68:69], v[68:69], 0, v[114:115]
	v_cvt_pk_bf16_f32 v66, v72, v73
	v_cvt_pk_bf16_f32 v67, v74, v75
	global_store_dwordx4 v[68:69], v[64:67], off
	v_pk_mul_f32 v[56:57], v[56:57], v[48:49]
	v_pk_mul_f32 v[60:61], v[60:61], v[52:53]
	v_mul_f32_e32 v64, 0xbfb8aa3b, v70
	v_pk_mul_f32 v[48:49], v[48:49], v[64:65] op_sel_hi:[1,0]
	v_pk_mul_f32 v[52:53], v[52:53], v[64:65] op_sel_hi:[1,0]
	v_pk_mul_f32 v[58:59], v[58:59], v[50:51]
	v_exp_f32_e32 v48, v48
	v_exp_f32_e32 v49, v49
	v_pk_mul_f32 v[50:51], v[50:51], v[64:65] op_sel_hi:[1,0]
	v_exp_f32_e32 v52, v52
	v_exp_f32_e32 v53, v53
	v_exp_f32_e32 v50, v50
	v_exp_f32_e32 v51, v51
	v_pk_add_f32 v[48:49], v[48:49], 1.0 op_sel_hi:[1,0]
	v_pk_add_f32 v[52:53], v[52:53], 1.0 op_sel_hi:[1,0]
	v_rcp_f32_e32 v48, v48
	v_rcp_f32_e32 v49, v49
	v_pk_add_f32 v[50:51], v[50:51], 1.0 op_sel_hi:[1,0]
	v_rcp_f32_e32 v52, v52
	v_rcp_f32_e32 v53, v53
	v_rcp_f32_e32 v50, v50
	v_rcp_f32_e32 v51, v51
	v_mul_f32_e32 v66, v70, v70
	v_pk_mul_f32 v[56:57], v[56:57], v[66:67] op_sel_hi:[1,0]
	v_pk_mul_f32 v[60:61], v[60:61], v[66:67] op_sel_hi:[1,0]
	v_pk_mul_f32 v[56:57], v[56:57], v[48:49]
	v_pk_mul_f32 v[48:49], v[58:59], v[66:67] op_sel_hi:[1,0]
	v_pk_mul_f32 v[52:53], v[60:61], v[52:53]
	v_pk_mul_f32 v[58:59], v[48:49], v[50:51]
	v_ffbh_u32_e32 v50, v167
	v_pk_mul_f32 v[62:63], v[62:63], v[54:55]
	v_pk_mul_f32 v[54:55], v[54:55], v[64:65] op_sel_hi:[1,0]
	v_cvt_pk_bf16_f32 v48, v52, v53
	v_min_u32_e32 v52, 32, v50
	v_exp_f32_e32 v54, v54
	v_exp_f32_e32 v55, v55
	v_lshlrev_b64 v[50:51], v52, v[166:167]
	v_min_u32_e32 v50, 1, v50
	v_or_b32_e32 v50, v51, v50
	v_cvt_f32_u32_e32 v53, v50
	v_pk_add_f32 v[54:55], v[54:55], 1.0 op_sel_hi:[1,0]
	v_sub_u32_e32 v52, 32, v52
	v_rcp_f32_e32 v54, v54
	v_rcp_f32_e32 v55, v55
	v_ldexp_f32 v52, v53, v52
	v_pk_mul_f32 v[60:61], v[62:63], v[66:67] op_sel_hi:[1,0]
	v_mul_f32_e32 v52, 0x2b800000, v52
	v_pk_mul_f32 v[54:55], v[60:61], v[54:55]
	v_fmamk_f32 v52, v52, 0x3a800000, v192
	v_cvt_pk_bf16_f32 v49, v54, v55
	v_rsq_f32_e32 v54, v52
	v_add_u32_e32 v141, 0x80, v180
	v_mad_i64_i32 v[52:53], s[46:47], v141, s61, v[112:113]
	v_lshl_add_u64 v[52:53], v[52:53], 0, v[114:115]
; __device__ __forceinline__ unsigned cvt_pk_bf16(float lo, float hi) { unsigned r; asm volatile("v_cvt_pk_bf16_f32 %0, %1, %2" : "=v"(r) : "v"(lo), "v"(hi)); return r; }
; __device__ __forceinline__ float ss_val(u64 v) { return (float)v * (1.0f / 1099511627776.0f); }
;     __device__ __forceinline__ void operator()(const f32x4 (&acc)[2][2][4][2], const Unit& u, const Unit& nxt, bool has_next, int wr, int wc, int fr, int fq) const {
;     ...
; #pragma unroll
;         for (int g = 0; g < 8; ++g) {
;             const int ai = g >> 2, m = g & 3;
;             const float rs = __builtin_amdgcn_rsqf(ss_val(cur[g]) * inv_k + eps), rsn = rs * -1.44269504089f, rs2 = rs * rs;
;             float h[8];
; #pragma unroll
;             for (int n = 0; n < 2; ++n)
; #pragma unroll
;                 for (int jp = 0; jp < 2; ++jp) {
;                     const f32x2v av = {acc[ai][0][m][n][2 * jp], acc[ai][0][m][n][2 * jp + 1]}, gv = {acc[ai][1][m][n][2 * jp], acc[ai][1][m][n][2 * jp + 1]};
;                     const f32x2v t = (av * gv) * rs2, y = gv * rsn;
;                     f32x2v ex; ex.x = __builtin_amdgcn_exp2f(y.x); ex.y = __builtin_amdgcn_exp2f(y.y);
;                     const f32x2v d = ex + 1.0f;
;                     f32x2v r; r.x = __builtin_amdgcn_rcpf(d.x); r.y = __builtin_amdgcn_rcpf(d.y);
;                     const f32x2v o = t * r;
;                     h[4 * n + 2 * jp] = o.x; h[4 * n + 2 * jp + 1] = o.y;
;                 }
;             u32x4 w; w.x = cvt_pk_bf16(h[0], h[1]); w.y = cvt_pk_bf16(h[2], h[3]); w.z = cvt_pk_bf16(h[4], h[5]); w.w = cvt_pk_bf16(h[6], h[7]);
;             *(u32x4*)(O + (size_t)(row0 + ai * HALF + m * 16) * ldc + col0) = w;
;         }
;         if (has_next) { u64 x = 0;
; #pragma unroll
;             for (int g = 0; g < 8; ++g) x |= warm[g];
;             asm volatile("" :: "v"((unsigned)x), "v"((unsigned)(x >> 32))); }
	v_cvt_pk_bf16_f32 v50, v56, v57
	v_cvt_pk_bf16_f32 v51, v58, v59
	global_store_dwordx4 v[52:53], v[48:51], off
	v_pk_mul_f32 v[40:41], v[40:41], v[32:33]
	v_pk_mul_f32 v[44:45], v[44:45], v[36:37]
	v_mul_f32_e32 v48, 0xbfb8aa3b, v54
	v_pk_mul_f32 v[32:33], v[32:33], v[48:49] op_sel_hi:[1,0]
	v_pk_mul_f32 v[36:37], v[36:37], v[48:49] op_sel_hi:[1,0]
	v_pk_mul_f32 v[42:43], v[42:43], v[34:35]
	v_exp_f32_e32 v32, v32
	v_exp_f32_e32 v33, v33
	v_pk_mul_f32 v[34:35], v[34:35], v[48:49] op_sel_hi:[1,0]
	v_exp_f32_e32 v36, v36
	v_exp_f32_e32 v37, v37
	v_exp_f32_e32 v34, v34
	v_exp_f32_e32 v35, v35
	v_pk_add_f32 v[32:33], v[32:33], 1.0 op_sel_hi:[1,0]
	v_pk_add_f32 v[36:37], v[36:37], 1.0 op_sel_hi:[1,0]
	v_rcp_f32_e32 v32, v32
	v_rcp_f32_e32 v33, v33
	v_pk_add_f32 v[34:35], v[34:35], 1.0 op_sel_hi:[1,0]
	v_rcp_f32_e32 v36, v36
	v_rcp_f32_e32 v37, v37
	v_rcp_f32_e32 v34, v34
	v_rcp_f32_e32 v35, v35
	v_mul_f32_e32 v50, v54, v54
	v_pk_mul_f32 v[40:41], v[40:41], v[50:51] op_sel_hi:[1,0]
	v_pk_mul_f32 v[44:45], v[44:45], v[50:51] op_sel_hi:[1,0]
	v_pk_mul_f32 v[40:41], v[40:41], v[32:33]
	v_pk_mul_f32 v[32:33], v[42:43], v[50:51] op_sel_hi:[1,0]
	v_pk_mul_f32 v[36:37], v[44:45], v[36:37]
	v_pk_mul_f32 v[42:43], v[32:33], v[34:35]
	v_ffbh_u32_e32 v34, v165
	v_pk_mul_f32 v[46:47], v[46:47], v[38:39]
	v_pk_mul_f32 v[38:39], v[38:39], v[48:49] op_sel_hi:[1,0]
	v_cvt_pk_bf16_f32 v32, v36, v37
	v_min_u32_e32 v36, 32, v34
	v_exp_f32_e32 v38, v38
	v_exp_f32_e32 v39, v39
	v_lshlrev_b64 v[34:35], v36, v[164:165]
	v_min_u32_e32 v34, 1, v34
	v_or_b32_e32 v34, v35, v34
	v_cvt_f32_u32_e32 v37, v34
	v_pk_add_f32 v[38:39], v[38:39], 1.0 op_sel_hi:[1,0]
	v_sub_u32_e32 v36, 32, v36
	v_rcp_f32_e32 v38, v38
	v_rcp_f32_e32 v39, v39
	v_ldexp_f32 v36, v37, v36
	v_pk_mul_f32 v[44:45], v[46:47], v[50:51] op_sel_hi:[1,0]
	v_mul_f32_e32 v36, 0x2b800000, v36
	v_pk_mul_f32 v[38:39], v[44:45], v[38:39]
	v_fmamk_f32 v36, v36, 0x3a800000, v192
	v_cvt_pk_bf16_f32 v33, v38, v39
	v_rsq_f32_e32 v38, v36
	v_mad_i64_i32 v[36:37], s[46:47], v162, s61, v[112:113]
	v_lshl_add_u64 v[36:37], v[36:37], 0, v[114:115]
	v_cvt_pk_bf16_f32 v34, v40, v41
	v_cvt_pk_bf16_f32 v35, v42, v43
	global_store_dwordx4 v[36:37], v[32:35], off
	v_pk_mul_f32 v[24:25], v[24:25], v[16:17]
	v_pk_mul_f32 v[28:29], v[28:29], v[20:21]
	v_mul_f32_e32 v32, 0xbfb8aa3b, v38
	v_pk_mul_f32 v[16:17], v[16:17], v[32:33] op_sel_hi:[1,0]
	v_pk_mul_f32 v[20:21], v[20:21], v[32:33] op_sel_hi:[1,0]
	v_pk_mul_f32 v[26:27], v[26:27], v[18:19]
	v_exp_f32_e32 v16, v16
	v_exp_f32_e32 v17, v17
	v_pk_mul_f32 v[18:19], v[18:19], v[32:33] op_sel_hi:[1,0]
	v_exp_f32_e32 v20, v20
	v_exp_f32_e32 v21, v21
	v_exp_f32_e32 v18, v18
	v_exp_f32_e32 v19, v19
	v_pk_add_f32 v[16:17], v[16:17], 1.0 op_sel_hi:[1,0]
	v_pk_add_f32 v[20:21], v[20:21], 1.0 op_sel_hi:[1,0]
	v_rcp_f32_e32 v16, v16
	v_rcp_f32_e32 v17, v17
	v_pk_add_f32 v[18:19], v[18:19], 1.0 op_sel_hi:[1,0]
	v_rcp_f32_e32 v20, v20
	v_rcp_f32_e32 v21, v21
	v_rcp_f32_e32 v18, v18
	v_rcp_f32_e32 v19, v19
	v_mul_f32_e32 v34, v38, v38
	v_pk_mul_f32 v[24:25], v[24:25], v[34:35] op_sel_hi:[1,0]
	v_pk_mul_f32 v[28:29], v[28:29], v[34:35] op_sel_hi:[1,0]
	v_pk_mul_f32 v[24:25], v[24:25], v[16:17]
	v_pk_mul_f32 v[16:17], v[26:27], v[34:35] op_sel_hi:[1,0]
	v_pk_mul_f32 v[20:21], v[28:29], v[20:21]
	v_pk_mul_f32 v[26:27], v[16:17], v[18:19]
	v_ffbh_u32_e32 v18, v161
	v_pk_mul_f32 v[30:31], v[30:31], v[22:23]
	v_pk_mul_f32 v[22:23], v[22:23], v[32:33] op_sel_hi:[1,0]
	v_cvt_pk_bf16_f32 v16, v20, v21
	v_min_u32_e32 v20, 32, v18
	v_exp_f32_e32 v22, v22
	v_exp_f32_e32 v23, v23
	v_lshlrev_b64 v[18:19], v20, v[160:161]
	v_min_u32_e32 v18, 1, v18
	v_or_b32_e32 v18, v19, v18
	v_cvt_f32_u32_e32 v21, v18
	v_pk_add_f32 v[22:23], v[22:23], 1.0 op_sel_hi:[1,0]
	v_sub_u32_e32 v20, 32, v20
	v_rcp_f32_e32 v22, v22
	v_rcp_f32_e32 v23, v23
	v_ldexp_f32 v20, v21, v20
	v_pk_mul_f32 v[28:29], v[30:31], v[34:35] op_sel_hi:[1,0]
	v_mul_f32_e32 v20, 0x2b800000, v20
	v_pk_mul_f32 v[22:23], v[28:29], v[22:23]
	v_fmamk_f32 v20, v20, 0x3a800000, v192
	v_cvt_pk_bf16_f32 v17, v22, v23
	v_rsq_f32_e32 v22, v20
	v_mad_i64_i32 v[20:21], s[46:47], v158, s61, v[112:113]
	v_lshl_add_u64 v[20:21], v[20:21], 0, v[114:115]
	v_cvt_pk_bf16_f32 v18, v24, v25
	v_cvt_pk_bf16_f32 v19, v26, v27
	global_store_dwordx4 v[20:21], v[16:19], off
	v_pk_mul_f32 v[12:13], v[12:13], v[4:5]
	v_pk_mul_f32 v[8:9], v[8:9], v[0:1]
	v_mul_f32_e32 v16, 0xbfb8aa3b, v22
	v_pk_mul_f32 v[4:5], v[4:5], v[16:17] op_sel_hi:[1,0]
	v_pk_mul_f32 v[0:1], v[0:1], v[16:17] op_sel_hi:[1,0]
	v_exp_f32_e32 v4, v4
	v_exp_f32_e32 v5, v5
	v_pk_mul_f32 v[10:11], v[10:11], v[2:3]
	v_exp_f32_e32 v0, v0
	v_exp_f32_e32 v1, v1
	v_pk_mul_f32 v[2:3], v[2:3], v[16:17] op_sel_hi:[1,0]
	v_pk_mul_f32 v[14:15], v[14:15], v[6:7]
	v_exp_f32_e32 v2, v2
	v_exp_f32_e32 v3, v3
	v_pk_mul_f32 v[6:7], v[6:7], v[16:17] op_sel_hi:[1,0]
	v_pk_add_f32 v[4:5], v[4:5], 1.0 op_sel_hi:[1,0]
	v_exp_f32_e32 v6, v6
	v_exp_f32_e32 v7, v7
	v_pk_add_f32 v[0:1], v[0:1], 1.0 op_sel_hi:[1,0]
	v_rcp_f32_e32 v4, v4
	v_rcp_f32_e32 v5, v5
	v_rcp_f32_e32 v0, v0
	v_rcp_f32_e32 v1, v1
	v_pk_add_f32 v[2:3], v[2:3], 1.0 op_sel_hi:[1,0]
	v_mul_f32_e32 v18, v22, v22
	v_rcp_f32_e32 v2, v2
	v_rcp_f32_e32 v3, v3
	v_pk_add_f32 v[6:7], v[6:7], 1.0 op_sel_hi:[1,0]
	v_pk_mul_f32 v[12:13], v[12:13], v[18:19] op_sel_hi:[1,0]
	v_rcp_f32_e32 v6, v6
	v_rcp_f32_e32 v7, v7
	v_pk_mul_f32 v[8:9], v[8:9], v[18:19] op_sel_hi:[1,0]
	v_pk_mul_f32 v[4:5], v[12:13], v[4:5]
	v_pk_mul_f32 v[8:9], v[8:9], v[0:1]
	v_pk_mul_f32 v[0:1], v[10:11], v[18:19] op_sel_hi:[1,0]
	v_pk_mul_f32 v[12:13], v[14:15], v[18:19] op_sel_hi:[1,0]
	v_pk_mul_f32 v[10:11], v[0:1], v[2:3]
	v_cvt_pk_bf16_f32 v0, v4, v5
	v_mad_i64_i32 v[4:5], s[46:47], v140, s61, v[112:113]
	v_lshl_add_u64 v[4:5], v[4:5], 0, v[114:115]
	s_and_b64 vcc, exec, s[2:3]
	s_mov_b64 s[2:3], -1
	v_pk_mul_f32 v[6:7], v[12:13], v[6:7]
	s_nop 0
	v_cvt_pk_bf16_f32 v1, v6, v7
	v_cvt_pk_bf16_f32 v2, v8, v9
	v_cvt_pk_bf16_f32 v3, v10, v11
	global_store_dwordx4 v[4:5], v[0:3], off
	s_cbranch_vccnz .LBB0_1289
	s_nop 0
	v_or_b32_e32 v0, v157, v155
	v_or_b32_e32 v1, v156, v154
	v_or3_b32 v0, v0, v151, v153
	v_or3_b32 v1, v1, v150, v152
	v_or3_b32 v0, v0, v147, v149
	v_or3_b32 v1, v1, v146, v148
	s_andn2_b64 vcc, exec, s[4:5]
	v_or3_b32 v0, v0, v143, v145
	v_or3_b32 v1, v1, v142, v144
	s_cbranch_vccnz .LBB0_1288
	s_barrier
	s_branch .LBB0_1288

; #define LAS __attribute__((address_space(3)))
; __global__ void __launch_bounds__(NTHREADS, 2) fwd(Args a) {
;     extern __shared__ __attribute__((aligned(16))) unsigned char lds_raw[];
;     LAS unsigned char* lds = (LAS unsigned char*)lds_raw;
;     const int tid = threadIdx.x, lane = tid & 63, wave = __builtin_amdgcn_readfirstlane(tid >> 6);
	.amdhsa_kernel _Z3fwd4Args
		.amdhsa_group_segment_fixed_size 0
		.amdhsa_private_segment_fixed_size 0
		.amdhsa_kernarg_size 416
		.amdhsa_user_sgpr_count 2
		.amdhsa_user_sgpr_dispatch_ptr 0
		.amdhsa_user_sgpr_queue_ptr 0
		.amdhsa_user_sgpr_kernarg_segment_ptr 1
		.amdhsa_user_sgpr_dispatch_id 0
		.amdhsa_user_sgpr_kernarg_preload_length 0
		.amdhsa_user_sgpr_kernarg_preload_offset 0
		.amdhsa_user_sgpr_private_segment_size 0
		.amdhsa_uses_dynamic_stack 0
		.amdhsa_enable_private_segment 0
		.amdhsa_system_sgpr_workgroup_id_x 1
		.amdhsa_system_sgpr_workgroup_id_y 0
		.amdhsa_system_sgpr_workgroup_id_z 0
		.amdhsa_system_sgpr_workgroup_info 0
		.amdhsa_system_vgpr_workitem_id 2
		.amdhsa_next_free_vgpr 248
		.amdhsa_next_free_sgpr 100
		.amdhsa_accum_offset 248
		.amdhsa_reserve_vcc 1
		.amdhsa_float_round_mode_32 0
		.amdhsa_float_round_mode_16_64 0
		.amdhsa_float_denorm_mode_32 3
		.amdhsa_float_denorm_mode_16_64 3
		.amdhsa_dx10_clamp 1
		.amdhsa_ieee_mode 1
		.amdhsa_fp16_overflow 0
		.amdhsa_tg_split 0
		.amdhsa_exception_fp_ieee_invalid_op 0
		.amdhsa_exception_fp_denorm_src 0
		.amdhsa_exception_fp_ieee_div_zero 0
		.amdhsa_exception_fp_ieee_overflow 0
		.amdhsa_exception_fp_ieee_underflow 0
		.amdhsa_exception_fp_ieee_inexact 0
		.amdhsa_exception_int_div_zero 0
	.end_amdhsa_kernel

; #define LAS __attribute__((address_space(3)))
; __global__ void __launch_bounds__(NTHREADS, 2) fwd(Args a) {
;     extern __shared__ __attribute__((aligned(16))) unsigned char lds_raw[];
;     LAS unsigned char* lds = (LAS unsigned char*)lds_raw;
;     const int tid = threadIdx.x, lane = tid & 63, wave = __builtin_amdgcn_readfirstlane(tid >> 6);
amdhsa.kernels:
  - .agpr_count:     0
    .args:
      - .offset:         0
        .size:           160
        .value_kind:     by_value
      - .offset:         160
        .size:           4
        .value_kind:     hidden_block_count_x
      - .offset:         164
        .size:           4
        .value_kind:     hidden_block_count_y
      - .offset:         168
        .size:           4
        .value_kind:     hidden_block_count_z
      - .offset:         172
        .size:           2
        .value_kind:     hidden_group_size_x
      - .offset:         174
        .size:           2
        .value_kind:     hidden_group_size_y
      - .offset:         176
        .size:           2
        .value_kind:     hidden_group_size_z
      - .offset:         178
        .size:           2
        .value_kind:     hidden_remainder_x
      - .offset:         180
        .size:           2
        .value_kind:     hidden_remainder_y
      - .offset:         182
        .size:           2
        .value_kind:     hidden_remainder_z
      - .offset:         200
        .size:           8
        .value_kind:     hidden_global_offset_x
      - .offset:         208
        .size:           8
        .value_kind:     hidden_global_offset_y
      - .offset:         216
        .size:           8
        .value_kind:     hidden_global_offset_z
      - .offset:         224
        .size:           2
        .value_kind:     hidden_grid_dims
      - .offset:         248
        .size:           8
        .value_kind:     hidden_multigrid_sync_arg
      - .offset:         280
        .size:           4
        .value_kind:     hidden_dynamic_lds_size
    .group_segment_fixed_size: 0
    .kernarg_segment_align: 8
    .kernarg_segment_size: 416
    .language:       OpenCL C
    .language_version:
      - 2
      - 0
    .max_flat_workgroup_size: 512
    .name:           _Z3fwd4Args
    .private_segment_fixed_size: 0
    .sgpr_count:     106
    .sgpr_spill_count: 16
    .symbol:         _Z3fwd4Args.kd
    .uniform_work_group_size: 1
    .uses_dynamic_stack: false
    .vgpr_count:     248
    .vgpr_spill_count: 0
    .wavefront_size: 64
